# sigmoid gate arrays stored chunk-major [col/32][row][32B] by the projection epilogue so merge gate loads read 512 contiguous bytes per instruction
# speedup vs baseline: 1.0796x; 1.0050x over previous
; DI float sigmoidf_(float x) { return __builtin_amdgcn_rcpf(1.f + __expf(-x)); }
;   template <int GRP>
;   DI void run(const f32x4 (&acc)[2][2][4][2], const pg8::Unit& u, int wr, int wc, int fr, int fq) const {
;     ...
;         if (nt < 4) { off = OFF_QAB; ld = 1024; c0 = nt * 128; act = 0; }
;         else if (nt < 16) { off = OFF_GA; ld = 512; c0 = (nt - 12) * 128; act = 1; }
;         else if (nt < 20) { off = OFF_QAB; ld = 1024; c0 = 512 + (nt - 16) * 128; act = 0; }
;         else if (nt < 25) { off = OFF_GB; ld = 512; c0 = (nt - 21) * 128; act = 1; }
;         else if (nt < 29) { off = OFF_QI; ld = 512; c0 = (nt - 25) * 128; act = 0; }
;         else if (nt < 38) { off = OFF_RA; ld = 1024; c0 = (nt - 30) * 128; act = 2; }
;         else { off = OFF_RB; ld = 1024; c0 = (nt - 38) * 128; act = 2; }
;         bf16_t* dst = reinterpret_cast<bf16_t*>(ws + off) + c0 + 32 * wc + 8 * fq;
; #pragma unroll
;         for (int ai = 0; ai < 2; ++ai)
; #pragma unroll
;           for (int m = 0; m < 4; ++m) {
;             int row = u.pm * 256 + 128 * ai + 64 * wr + 16 * m + fr;
;             asm volatile("" : "+v"(row));
;             if (act == 2) {
;               u32x2v g8;
; #pragma unroll
;               for (int n = 0; n < 2; ++n) {
;                 const f32x4 v = acc[ai][bj][m][n] + bp[n];
;                 unsigned q = 0u;
; #pragma unroll
;                 for (int j = 0; j < 4; ++j) q |= ((unsigned)(sigmoidf_(v[j]) * 255.f + 0.5f)) << (8 * j);
;                 if (n == 0) g8.x = q; else g8.y = q;
;               }
;               *reinterpret_cast<u32x2v*>(reinterpret_cast<unsigned char*>(ws + off) + (size_t)row * 1024 + c0 + 32 * wc + 8 * fq) = g8;
;               continue;
;             }
;             u32x4v pk;
; #pragma unroll
;             for (int n = 0; n < 2; ++n) {
;               f32x4 v = acc[ai][bj][m][n] + bp[n];
;               if (act != 0) {
; #pragma unroll
;                 for (int j = 0; j < 4; ++j) { const float sg = sigmoidf_(v[j]); v[j] = (act == 1) ? v[j] * sg : sg; }
.LBB0_519:
	s_xor_b64 s[26:27], s[26:27], -1
	v_readlane_b32 s50, v249, 0
	v_readlane_b32 s51, v249, 1
	s_add_u32 s11, s50, s28
	s_addc_u32 s23, s51, s29
	s_ashr_i32 s7, s6, 31
	s_lshl_b64 s[28:29], s[6:7], 1
	s_add_u32 s28, s11, s28
	s_addc_u32 s29, s23, s29
	s_lshl_b32 s33, s42, 1
	s_add_u32 s28, s28, s33
	s_addc_u32 s29, s29, 0
	s_add_u32 s6, s11, s6
	s_addc_u32 s7, s23, s7
	s_sub_u32 s6, s6, s11
	s_add_i32 s6, s6, s42
	s_lshr_b32 s6, s6, 5
	s_mul_i32 s6, s6, 0x204000
	s_add_u32 s6, s11, s6
	s_addc_u32 s7, s23, 0
	s_lshl_b32 s11, s48, 8
	v_add_u32_e32 v164, s11, v21
	ds_read_b128 v[134:137], v195
	v_lshlrev_b32_e32 v16, 1, v144
	s_mov_b64 s[30:31], -1
	v_lshl_add_u64 v[150:151], s[28:29], 0, v[16:17]
	s_and_b64 vcc, exec, s[4:5]
	s_cbranch_vccnz .LBB0_525
	s_waitcnt lgkmcnt(0)
	v_pk_add_f32 v[162:163], v[132:133], v[136:137]
	v_pk_add_f32 v[166:167], v[130:131], v[134:135]
	s_and_b64 vcc, exec, s[26:27]
	s_cbranch_vccz .LBB0_522
	v_mul_f32_e32 v16, 0xbfb8aa3b, v166
	v_exp_f32_e32 v16, v16
	v_mul_f32_e32 v155, 0xbfb8aa3b, v162
	v_mul_f32_e32 v154, 0xbfb8aa3b, v167
	v_exp_f32_e32 v154, v154
	v_add_f32_e32 v16, 1.0, v16
	v_rcp_f32_e32 v168, v16
	v_exp_f32_e32 v16, v155
	v_mul_f32_e32 v155, 0xbfb8aa3b, v163
	v_exp_f32_e32 v155, v155
	v_add_f32_e32 v154, 1.0, v154
	v_add_f32_e32 v16, 1.0, v16
	v_rcp_f32_e32 v170, v16
	v_add_f32_e32 v16, 1.0, v155
	v_rcp_f32_e32 v171, v16
	v_rcp_f32_e32 v169, v154
	v_pk_mul_f32 v[162:163], v[162:163], v[170:171]
	v_pk_mul_f32 v[166:167], v[166:167], v[168:169]

; DI float sigmoidf_(float x) { return __builtin_amdgcn_rcpf(1.f + __expf(-x)); }
;   template <int GRP>
;   DI void run(const f32x4 (&acc)[2][2][4][2], const pg8::Unit& u, int wr, int wc, int fr, int fq) const {
;     ...
;             if (act == 2) {
;               u32x2v g8;
; #pragma unroll
;               for (int n = 0; n < 2; ++n) {
;                 const f32x4 v = acc[ai][bj][m][n] + bp[n];
;                 unsigned q = 0u;
; #pragma unroll
;                 for (int j = 0; j < 4; ++j) q |= ((unsigned)(sigmoidf_(v[j]) * 255.f + 0.5f)) << (8 * j);
;                 if (n == 0) g8.x = q; else g8.y = q;
;               }
;               *reinterpret_cast<u32x2v*>(reinterpret_cast<unsigned char*>(ws + off) + (size_t)row * 1024 + c0 + 32 * wc + 8 * fq) = g8;
.LBB0_525:
	v_lshl_add_u64 v[162:163], s[6:7], 0, v[144:145]
	s_and_b64 vcc, exec, s[30:31]
	s_cbranch_vccz .LBB0_527
	s_waitcnt lgkmcnt(0)
	v_add_f32_e32 v16, v130, v134
	v_mul_f32_e32 v16, 0xbfb8aa3b, v16
	v_add_f32_e32 v134, v131, v135
	v_exp_f32_e32 v16, v16
	v_mul_f32_e32 v134, 0xbfb8aa3b, v134
	v_exp_f32_e32 v134, v134
	s_mov_b32 s6, 0x437f0000
	v_add_f32_e32 v16, 1.0, v16
	v_rcp_f32_e32 v166, v16
	v_add_f32_e32 v16, 1.0, v134
	v_add_f32_e32 v134, v132, v136
	v_mul_f32_e32 v134, 0xbfb8aa3b, v134
	v_exp_f32_e32 v154, v134
	v_add_f32_e32 v134, v133, v137
	v_mul_f32_e32 v134, 0xbfb8aa3b, v134
	v_exp_f32_e32 v155, v134
	ds_read_b128 v[134:137], v195 offset:16
	v_rcp_f32_e32 v168, v16
	v_add_f32_e32 v16, 1.0, v154
	v_rcp_f32_e32 v170, v16
	v_add_f32_e32 v16, 1.0, v155
	s_waitcnt lgkmcnt(0)
	v_add_f32_e32 v134, v126, v134
	v_mul_f32_e32 v134, 0xbfb8aa3b, v134
	v_exp_f32_e32 v154, v134
	v_add_f32_e32 v134, v127, v135
	v_mul_f32_e32 v134, 0xbfb8aa3b, v134
	v_exp_f32_e32 v135, v134
	v_rcp_f32_e32 v134, v16
	v_add_f32_e32 v16, 1.0, v154
	v_rcp_f32_e32 v167, v16
	v_add_f32_e32 v16, 1.0, v135
	v_add_f32_e32 v135, v128, v136
	v_mul_f32_e32 v135, 0xbfb8aa3b, v135
	v_add_f32_e32 v136, v129, v137
	v_exp_f32_e32 v135, v135
	v_mul_f32_e32 v136, 0xbfb8aa3b, v136
	v_exp_f32_e32 v136, v136
	v_rcp_f32_e32 v169, v16
	v_add_f32_e32 v16, 1.0, v135
	v_rcp_f32_e32 v171, v16
	v_add_f32_e32 v16, 1.0, v136
	v_pk_fma_f32 v[136:137], v[166:167], s[6:7], 0.5 op_sel_hi:[1,0,0]
	v_pk_fma_f32 v[166:167], v[168:169], s[6:7], 0.5 op_sel_hi:[1,0,0]
	v_rcp_f32_e32 v135, v16
	v_cvt_u32_f32_e32 v16, v167
	v_cvt_u32_f32_e32 v154, v166
	v_cvt_u32_f32_e32 v137, v137
	v_cvt_u32_f32_e32 v136, v136
	v_lshlrev_b32_e32 v16, 8, v16
	v_lshlrev_b32_e32 v154, 8, v154
	v_or_b32_e32 v16, v16, v137
	v_or_b32_e32 v154, v154, v136
	v_pk_fma_f32 v[136:137], v[170:171], s[6:7], 0.5 op_sel_hi:[1,0,0]
	v_pk_fma_f32 v[134:135], v[134:135], s[6:7], 0.5 op_sel_hi:[1,0,0]
	v_cvt_u32_f32_sdwa v136, v136 dst_sel:WORD_1 dst_unused:UNUSED_PAD src0_sel:DWORD
	v_cvt_u32_f32_sdwa v137, v137 dst_sel:WORD_1 dst_unused:UNUSED_PAD src0_sel:DWORD
	v_cvt_u32_f32_sdwa v134, v134 dst_sel:BYTE_3 dst_unused:UNUSED_PAD src0_sel:DWORD
	v_cvt_u32_f32_sdwa v135, v135 dst_sel:BYTE_3 dst_unused:UNUSED_PAD src0_sel:DWORD
	v_or_b32_e32 v136, v154, v136
	v_ashrrev_i32_e32 v165, 31, v164
	v_or_b32_e32 v16, v16, v137
	v_or_b32_e32 v134, v136, v134
	v_lshlrev_b64 v[136:137], 5, v[164:165]
	v_or_b32_e32 v135, v16, v135
	v_lshl_add_u64 v[136:137], v[162:163], 0, v[136:137]
	global_store_dwordx2 v[136:137], v[134:135], off

; DI float sigmoidf_(float x) { return __builtin_amdgcn_rcpf(1.f + __expf(-x)); }
;   template <int GRP>
;   DI void run(const f32x4 (&acc)[2][2][4][2], const pg8::Unit& u, int wr, int wc, int fr, int fq) const {
;     ...
;             if (act == 2) {
;               u32x2v g8;
; #pragma unroll
;               for (int n = 0; n < 2; ++n) {
;                 const f32x4 v = acc[ai][bj][m][n] + bp[n];
;                 unsigned q = 0u;
; #pragma unroll
;                 for (int j = 0; j < 4; ++j) q |= ((unsigned)(sigmoidf_(v[j]) * 255.f + 0.5f)) << (8 * j);
;                 if (n == 0) g8.x = q; else g8.y = q;
;               }
;               *reinterpret_cast<u32x2v*>(reinterpret_cast<unsigned char*>(ws + off) + (size_t)row * 1024 + c0 + 32 * wc + 8 * fq) = g8;
.LBB0_533:
	s_and_b64 vcc, exec, s[28:29]
	s_cbranch_vccz .LBB0_535
	s_waitcnt lgkmcnt(0)
	v_add_f32_e32 v16, v122, v134
	v_mul_f32_e32 v16, 0xbfb8aa3b, v16
	v_add_f32_e32 v134, v123, v135
	v_exp_f32_e32 v16, v16
	v_mul_f32_e32 v134, 0xbfb8aa3b, v134
	v_exp_f32_e32 v134, v134
	s_mov_b32 s26, 0x437f0000
	v_add_f32_e32 v16, 1.0, v16
	v_rcp_f32_e32 v166, v16
	v_add_f32_e32 v16, 1.0, v134
	v_add_f32_e32 v134, v124, v136
	v_mul_f32_e32 v134, 0xbfb8aa3b, v134
	v_exp_f32_e32 v154, v134
	v_add_f32_e32 v134, v125, v137
	v_mul_f32_e32 v134, 0xbfb8aa3b, v134
	v_exp_f32_e32 v155, v134
	ds_read_b128 v[134:137], v195 offset:16
	v_rcp_f32_e32 v168, v16
	v_add_f32_e32 v16, 1.0, v154
	v_rcp_f32_e32 v170, v16
	v_add_f32_e32 v16, 1.0, v155
	s_waitcnt lgkmcnt(0)
	v_add_f32_e32 v134, v118, v134
	v_mul_f32_e32 v134, 0xbfb8aa3b, v134
	v_exp_f32_e32 v154, v134
	v_add_f32_e32 v134, v119, v135
	v_mul_f32_e32 v134, 0xbfb8aa3b, v134
	v_exp_f32_e32 v135, v134
	v_rcp_f32_e32 v134, v16
	v_add_f32_e32 v16, 1.0, v154
	v_rcp_f32_e32 v167, v16
	v_add_f32_e32 v16, 1.0, v135
	v_add_f32_e32 v135, v120, v136
	v_mul_f32_e32 v135, 0xbfb8aa3b, v135
	v_add_f32_e32 v136, v121, v137
	v_exp_f32_e32 v135, v135
	v_mul_f32_e32 v136, 0xbfb8aa3b, v136
	v_exp_f32_e32 v136, v136
	v_rcp_f32_e32 v169, v16
	v_add_f32_e32 v16, 1.0, v135
	v_rcp_f32_e32 v171, v16
	v_add_f32_e32 v16, 1.0, v136
	v_pk_fma_f32 v[136:137], v[166:167], s[26:27], 0.5 op_sel_hi:[1,0,0]
	v_pk_fma_f32 v[166:167], v[168:169], s[26:27], 0.5 op_sel_hi:[1,0,0]
	v_rcp_f32_e32 v135, v16
	v_cvt_u32_f32_e32 v16, v167
	v_cvt_u32_f32_e32 v154, v166
	v_cvt_u32_f32_e32 v137, v137
	v_cvt_u32_f32_e32 v136, v136
	v_lshlrev_b32_e32 v16, 8, v16
	v_lshlrev_b32_e32 v154, 8, v154
	v_or_b32_e32 v16, v16, v137
	v_or_b32_e32 v154, v154, v136
	v_pk_fma_f32 v[136:137], v[170:171], s[26:27], 0.5 op_sel_hi:[1,0,0]
	v_pk_fma_f32 v[134:135], v[134:135], s[26:27], 0.5 op_sel_hi:[1,0,0]
	v_cvt_u32_f32_sdwa v136, v136 dst_sel:WORD_1 dst_unused:UNUSED_PAD src0_sel:DWORD
	v_cvt_u32_f32_sdwa v137, v137 dst_sel:WORD_1 dst_unused:UNUSED_PAD src0_sel:DWORD
	v_cvt_u32_f32_sdwa v134, v134 dst_sel:BYTE_3 dst_unused:UNUSED_PAD src0_sel:DWORD
	v_cvt_u32_f32_sdwa v135, v135 dst_sel:BYTE_3 dst_unused:UNUSED_PAD src0_sel:DWORD
	v_or_b32_e32 v136, v154, v136
	v_ashrrev_i32_e32 v165, 31, v164
	v_or_b32_e32 v16, v16, v137
	v_or_b32_e32 v134, v136, v134
	v_lshlrev_b64 v[136:137], 5, v[164:165]
	v_or_b32_e32 v135, v16, v135
	v_lshl_add_u64 v[136:137], v[162:163], 0, v[136:137]
	global_store_dwordx2 v[136:137], v[134:135], off

; DI float sigmoidf_(float x) { return __builtin_amdgcn_rcpf(1.f + __expf(-x)); }
;   template <int GRP>
;   DI void run(const f32x4 (&acc)[2][2][4][2], const pg8::Unit& u, int wr, int wc, int fr, int fq) const {
;     ...
;             if (act == 2) {
;               u32x2v g8;
; #pragma unroll
;               for (int n = 0; n < 2; ++n) {
;                 const f32x4 v = acc[ai][bj][m][n] + bp[n];
;                 unsigned q = 0u;
; #pragma unroll
;                 for (int j = 0; j < 4; ++j) q |= ((unsigned)(sigmoidf_(v[j]) * 255.f + 0.5f)) << (8 * j);
;                 if (n == 0) g8.x = q; else g8.y = q;
;               }
;               *reinterpret_cast<u32x2v*>(reinterpret_cast<unsigned char*>(ws + off) + (size_t)row * 1024 + c0 + 32 * wc + 8 * fq) = g8;
.LBB0_541:
	s_and_b64 vcc, exec, s[26:27]
	s_cbranch_vccz .LBB0_543
	s_waitcnt lgkmcnt(0)
	v_add_f32_e32 v16, v114, v134
	v_mul_f32_e32 v16, 0xbfb8aa3b, v16
	v_add_f32_e32 v134, v115, v135
	v_exp_f32_e32 v16, v16
	v_mul_f32_e32 v134, 0xbfb8aa3b, v134
	v_exp_f32_e32 v134, v134
	s_mov_b32 s26, 0x437f0000
	v_add_f32_e32 v16, 1.0, v16
	v_rcp_f32_e32 v166, v16
	v_add_f32_e32 v16, 1.0, v134
	v_add_f32_e32 v134, v116, v136
	v_mul_f32_e32 v134, 0xbfb8aa3b, v134
	v_exp_f32_e32 v154, v134
	v_add_f32_e32 v134, v117, v137
	v_mul_f32_e32 v134, 0xbfb8aa3b, v134
	v_exp_f32_e32 v155, v134
	ds_read_b128 v[134:137], v195 offset:16
	v_rcp_f32_e32 v168, v16
	v_add_f32_e32 v16, 1.0, v154
	v_rcp_f32_e32 v170, v16
	v_add_f32_e32 v16, 1.0, v155
	s_waitcnt lgkmcnt(0)
	v_add_f32_e32 v134, v110, v134
	v_mul_f32_e32 v134, 0xbfb8aa3b, v134
	v_exp_f32_e32 v154, v134
	v_add_f32_e32 v134, v111, v135
	v_mul_f32_e32 v134, 0xbfb8aa3b, v134
	v_exp_f32_e32 v135, v134
	v_rcp_f32_e32 v134, v16
	v_add_f32_e32 v16, 1.0, v154
	v_rcp_f32_e32 v167, v16
	v_add_f32_e32 v16, 1.0, v135
	v_add_f32_e32 v135, v112, v136
	v_mul_f32_e32 v135, 0xbfb8aa3b, v135
	v_add_f32_e32 v136, v113, v137
	v_exp_f32_e32 v135, v135
	v_mul_f32_e32 v136, 0xbfb8aa3b, v136
	v_exp_f32_e32 v136, v136
	v_rcp_f32_e32 v169, v16
	v_add_f32_e32 v16, 1.0, v135
	v_rcp_f32_e32 v171, v16
	v_add_f32_e32 v16, 1.0, v136
	v_pk_fma_f32 v[136:137], v[166:167], s[26:27], 0.5 op_sel_hi:[1,0,0]
	v_pk_fma_f32 v[166:167], v[168:169], s[26:27], 0.5 op_sel_hi:[1,0,0]
	v_rcp_f32_e32 v135, v16
	v_cvt_u32_f32_e32 v16, v167
	v_cvt_u32_f32_e32 v154, v166
	v_cvt_u32_f32_e32 v137, v137
	v_cvt_u32_f32_e32 v136, v136
	v_lshlrev_b32_e32 v16, 8, v16
	v_lshlrev_b32_e32 v154, 8, v154
	v_or_b32_e32 v16, v16, v137
	v_or_b32_e32 v154, v154, v136
	v_pk_fma_f32 v[136:137], v[170:171], s[26:27], 0.5 op_sel_hi:[1,0,0]
	v_pk_fma_f32 v[134:135], v[134:135], s[26:27], 0.5 op_sel_hi:[1,0,0]
	v_cvt_u32_f32_sdwa v136, v136 dst_sel:WORD_1 dst_unused:UNUSED_PAD src0_sel:DWORD
	v_cvt_u32_f32_sdwa v137, v137 dst_sel:WORD_1 dst_unused:UNUSED_PAD src0_sel:DWORD
	v_cvt_u32_f32_sdwa v134, v134 dst_sel:BYTE_3 dst_unused:UNUSED_PAD src0_sel:DWORD
	v_cvt_u32_f32_sdwa v135, v135 dst_sel:BYTE_3 dst_unused:UNUSED_PAD src0_sel:DWORD
	v_or_b32_e32 v136, v154, v136
	v_ashrrev_i32_e32 v165, 31, v164
	v_or_b32_e32 v16, v16, v137
	v_or_b32_e32 v134, v136, v134
	v_lshlrev_b64 v[136:137], 5, v[164:165]
	v_or_b32_e32 v135, v16, v135
	v_lshl_add_u64 v[136:137], v[162:163], 0, v[136:137]
	global_store_dwordx2 v[136:137], v[134:135], off

; DI float sigmoidf_(float x) { return __builtin_amdgcn_rcpf(1.f + __expf(-x)); }
;   template <int GRP>
;   DI void run(const f32x4 (&acc)[2][2][4][2], const pg8::Unit& u, int wr, int wc, int fr, int fq) const {
;     ...
;             if (act == 2) {
;               u32x2v g8;
; #pragma unroll
;               for (int n = 0; n < 2; ++n) {
;                 const f32x4 v = acc[ai][bj][m][n] + bp[n];
;                 unsigned q = 0u;
; #pragma unroll
;                 for (int j = 0; j < 4; ++j) q |= ((unsigned)(sigmoidf_(v[j]) * 255.f + 0.5f)) << (8 * j);
;                 if (n == 0) g8.x = q; else g8.y = q;
;               }
;               *reinterpret_cast<u32x2v*>(reinterpret_cast<unsigned char*>(ws + off) + (size_t)row * 1024 + c0 + 32 * wc + 8 * fq) = g8;
.LBB0_549:
	s_and_b64 vcc, exec, s[26:27]
	s_cbranch_vccz .LBB0_551
	s_waitcnt lgkmcnt(0)
	v_add_f32_e32 v16, v106, v134
	v_mul_f32_e32 v16, 0xbfb8aa3b, v16
	v_add_f32_e32 v134, v107, v135
	v_exp_f32_e32 v16, v16
	v_mul_f32_e32 v134, 0xbfb8aa3b, v134
	v_exp_f32_e32 v134, v134
	s_mov_b32 s26, 0x437f0000
	v_add_f32_e32 v16, 1.0, v16
	v_rcp_f32_e32 v166, v16
	v_add_f32_e32 v16, 1.0, v134
	v_add_f32_e32 v134, v108, v136
	v_mul_f32_e32 v134, 0xbfb8aa3b, v134
	v_exp_f32_e32 v154, v134
	v_add_f32_e32 v134, v109, v137
	v_mul_f32_e32 v134, 0xbfb8aa3b, v134
	v_exp_f32_e32 v155, v134
	ds_read_b128 v[134:137], v195 offset:16
	v_rcp_f32_e32 v168, v16
	v_add_f32_e32 v16, 1.0, v154
	v_rcp_f32_e32 v170, v16
	v_add_f32_e32 v16, 1.0, v155
	s_waitcnt lgkmcnt(0)
	v_add_f32_e32 v134, v102, v134
	v_mul_f32_e32 v134, 0xbfb8aa3b, v134
	v_exp_f32_e32 v154, v134
	v_add_f32_e32 v134, v103, v135
	v_mul_f32_e32 v134, 0xbfb8aa3b, v134
	v_exp_f32_e32 v135, v134
	v_rcp_f32_e32 v134, v16
	v_add_f32_e32 v16, 1.0, v154
	v_rcp_f32_e32 v167, v16
	v_add_f32_e32 v16, 1.0, v135
	v_add_f32_e32 v135, v104, v136
	v_mul_f32_e32 v135, 0xbfb8aa3b, v135
	v_add_f32_e32 v136, v105, v137
	v_exp_f32_e32 v135, v135
	v_mul_f32_e32 v136, 0xbfb8aa3b, v136
	v_exp_f32_e32 v136, v136
	v_rcp_f32_e32 v169, v16
	v_add_f32_e32 v16, 1.0, v135
	v_rcp_f32_e32 v171, v16
	v_add_f32_e32 v16, 1.0, v136
	v_pk_fma_f32 v[136:137], v[166:167], s[26:27], 0.5 op_sel_hi:[1,0,0]
	v_pk_fma_f32 v[166:167], v[168:169], s[26:27], 0.5 op_sel_hi:[1,0,0]
	v_rcp_f32_e32 v135, v16
	v_cvt_u32_f32_e32 v16, v167
	v_cvt_u32_f32_e32 v154, v166
	v_cvt_u32_f32_e32 v137, v137
	v_cvt_u32_f32_e32 v136, v136
	v_lshlrev_b32_e32 v16, 8, v16
	v_lshlrev_b32_e32 v154, 8, v154
	v_or_b32_e32 v16, v16, v137
	v_or_b32_e32 v154, v154, v136
	v_pk_fma_f32 v[136:137], v[170:171], s[26:27], 0.5 op_sel_hi:[1,0,0]
	v_pk_fma_f32 v[134:135], v[134:135], s[26:27], 0.5 op_sel_hi:[1,0,0]
	v_cvt_u32_f32_sdwa v136, v136 dst_sel:WORD_1 dst_unused:UNUSED_PAD src0_sel:DWORD
	v_cvt_u32_f32_sdwa v137, v137 dst_sel:WORD_1 dst_unused:UNUSED_PAD src0_sel:DWORD
	v_cvt_u32_f32_sdwa v134, v134 dst_sel:BYTE_3 dst_unused:UNUSED_PAD src0_sel:DWORD
	v_cvt_u32_f32_sdwa v135, v135 dst_sel:BYTE_3 dst_unused:UNUSED_PAD src0_sel:DWORD
	v_or_b32_e32 v136, v154, v136
	v_ashrrev_i32_e32 v165, 31, v164
	v_or_b32_e32 v16, v16, v137
	v_or_b32_e32 v134, v136, v134
	v_lshlrev_b64 v[136:137], 5, v[164:165]
	v_or_b32_e32 v135, v16, v135
	v_lshl_add_u64 v[136:137], v[162:163], 0, v[136:137]
	global_store_dwordx2 v[136:137], v[134:135], off

; DI float sigmoidf_(float x) { return __builtin_amdgcn_rcpf(1.f + __expf(-x)); }
;   template <int GRP>
;   DI void run(const f32x4 (&acc)[2][2][4][2], const pg8::Unit& u, int wr, int wc, int fr, int fq) const {
;     ...
;             if (act == 2) {
;               u32x2v g8;
; #pragma unroll
;               for (int n = 0; n < 2; ++n) {
;                 const f32x4 v = acc[ai][bj][m][n] + bp[n];
;                 unsigned q = 0u;
; #pragma unroll
;                 for (int j = 0; j < 4; ++j) q |= ((unsigned)(sigmoidf_(v[j]) * 255.f + 0.5f)) << (8 * j);
;                 if (n == 0) g8.x = q; else g8.y = q;
;               }
;               *reinterpret_cast<u32x2v*>(reinterpret_cast<unsigned char*>(ws + off) + (size_t)row * 1024 + c0 + 32 * wc + 8 * fq) = g8;
.LBB0_557:
	s_and_b64 vcc, exec, s[26:27]
	s_cbranch_vccz .LBB0_559
	s_waitcnt lgkmcnt(0)
	v_add_f32_e32 v16, v98, v134
	v_mul_f32_e32 v16, 0xbfb8aa3b, v16
	v_add_f32_e32 v134, v99, v135
	v_exp_f32_e32 v16, v16
	v_mul_f32_e32 v134, 0xbfb8aa3b, v134
	v_exp_f32_e32 v134, v134
	s_mov_b32 s26, 0x437f0000
	v_add_f32_e32 v16, 1.0, v16
	v_rcp_f32_e32 v166, v16
	v_add_f32_e32 v16, 1.0, v134
	v_add_f32_e32 v134, v100, v136
	v_mul_f32_e32 v134, 0xbfb8aa3b, v134
	v_exp_f32_e32 v154, v134
	v_add_f32_e32 v134, v101, v137
	v_mul_f32_e32 v134, 0xbfb8aa3b, v134
	v_exp_f32_e32 v155, v134
	ds_read_b128 v[134:137], v195 offset:16
	v_rcp_f32_e32 v168, v16
	v_add_f32_e32 v16, 1.0, v154
	v_rcp_f32_e32 v170, v16
	v_add_f32_e32 v16, 1.0, v155
	s_waitcnt lgkmcnt(0)
	v_add_f32_e32 v134, v94, v134
	v_mul_f32_e32 v134, 0xbfb8aa3b, v134
	v_exp_f32_e32 v154, v134
	v_add_f32_e32 v134, v95, v135
	v_mul_f32_e32 v134, 0xbfb8aa3b, v134
	v_exp_f32_e32 v135, v134
	v_rcp_f32_e32 v134, v16
	v_add_f32_e32 v16, 1.0, v154
	v_rcp_f32_e32 v167, v16
	v_add_f32_e32 v16, 1.0, v135
	v_add_f32_e32 v135, v96, v136
	v_mul_f32_e32 v135, 0xbfb8aa3b, v135
	v_add_f32_e32 v136, v97, v137
	v_exp_f32_e32 v135, v135
	v_mul_f32_e32 v136, 0xbfb8aa3b, v136
	v_exp_f32_e32 v136, v136
	v_rcp_f32_e32 v169, v16
	v_add_f32_e32 v16, 1.0, v135
	v_rcp_f32_e32 v171, v16
	v_add_f32_e32 v16, 1.0, v136
	v_pk_fma_f32 v[136:137], v[166:167], s[26:27], 0.5 op_sel_hi:[1,0,0]
	v_pk_fma_f32 v[166:167], v[168:169], s[26:27], 0.5 op_sel_hi:[1,0,0]
	v_rcp_f32_e32 v135, v16
	v_cvt_u32_f32_e32 v16, v167
	v_cvt_u32_f32_e32 v154, v166
	v_cvt_u32_f32_e32 v137, v137
	v_cvt_u32_f32_e32 v136, v136
	v_lshlrev_b32_e32 v16, 8, v16
	v_lshlrev_b32_e32 v154, 8, v154
	v_or_b32_e32 v16, v16, v137
	v_or_b32_e32 v154, v154, v136
	v_pk_fma_f32 v[136:137], v[170:171], s[26:27], 0.5 op_sel_hi:[1,0,0]
	v_pk_fma_f32 v[134:135], v[134:135], s[26:27], 0.5 op_sel_hi:[1,0,0]
	v_cvt_u32_f32_sdwa v136, v136 dst_sel:WORD_1 dst_unused:UNUSED_PAD src0_sel:DWORD
	v_cvt_u32_f32_sdwa v137, v137 dst_sel:WORD_1 dst_unused:UNUSED_PAD src0_sel:DWORD
	v_cvt_u32_f32_sdwa v134, v134 dst_sel:BYTE_3 dst_unused:UNUSED_PAD src0_sel:DWORD
	v_cvt_u32_f32_sdwa v135, v135 dst_sel:BYTE_3 dst_unused:UNUSED_PAD src0_sel:DWORD
	v_or_b32_e32 v136, v154, v136
	v_ashrrev_i32_e32 v165, 31, v164
	v_or_b32_e32 v16, v16, v137
	v_or_b32_e32 v134, v136, v134
	v_lshlrev_b64 v[136:137], 5, v[164:165]
	v_or_b32_e32 v135, v16, v135
	v_lshl_add_u64 v[136:137], v[162:163], 0, v[136:137]
	global_store_dwordx2 v[136:137], v[134:135], off

; DI float sigmoidf_(float x) { return __builtin_amdgcn_rcpf(1.f + __expf(-x)); }
;   template <int GRP>
;   DI void run(const f32x4 (&acc)[2][2][4][2], const pg8::Unit& u, int wr, int wc, int fr, int fq) const {
;     ...
;             if (act == 2) {
;               u32x2v g8;
; #pragma unroll
;               for (int n = 0; n < 2; ++n) {
;                 const f32x4 v = acc[ai][bj][m][n] + bp[n];
;                 unsigned q = 0u;
; #pragma unroll
;                 for (int j = 0; j < 4; ++j) q |= ((unsigned)(sigmoidf_(v[j]) * 255.f + 0.5f)) << (8 * j);
;                 if (n == 0) g8.x = q; else g8.y = q;
;               }
;               *reinterpret_cast<u32x2v*>(reinterpret_cast<unsigned char*>(ws + off) + (size_t)row * 1024 + c0 + 32 * wc + 8 * fq) = g8;
.LBB0_565:
	s_and_b64 vcc, exec, s[26:27]
	s_cbranch_vccz .LBB0_567
	s_waitcnt lgkmcnt(0)
	v_add_f32_e32 v16, v90, v134
	v_mul_f32_e32 v16, 0xbfb8aa3b, v16
	v_add_f32_e32 v134, v91, v135
	v_exp_f32_e32 v16, v16
	v_mul_f32_e32 v134, 0xbfb8aa3b, v134
	v_exp_f32_e32 v134, v134
	s_mov_b32 s26, 0x437f0000
	v_add_f32_e32 v16, 1.0, v16
	v_rcp_f32_e32 v166, v16
	v_add_f32_e32 v16, 1.0, v134
	v_add_f32_e32 v134, v92, v136
	v_mul_f32_e32 v134, 0xbfb8aa3b, v134
	v_exp_f32_e32 v154, v134
	v_add_f32_e32 v134, v93, v137
	v_mul_f32_e32 v134, 0xbfb8aa3b, v134
	v_exp_f32_e32 v155, v134
	ds_read_b128 v[134:137], v195 offset:16
	v_rcp_f32_e32 v168, v16
	v_add_f32_e32 v16, 1.0, v154
	v_rcp_f32_e32 v170, v16
	v_add_f32_e32 v16, 1.0, v155
	s_waitcnt lgkmcnt(0)
	v_add_f32_e32 v134, v86, v134
	v_mul_f32_e32 v134, 0xbfb8aa3b, v134
	v_exp_f32_e32 v154, v134
	v_add_f32_e32 v134, v87, v135
	v_mul_f32_e32 v134, 0xbfb8aa3b, v134
	v_exp_f32_e32 v135, v134
	v_rcp_f32_e32 v134, v16
	v_add_f32_e32 v16, 1.0, v154
	v_rcp_f32_e32 v167, v16
	v_add_f32_e32 v16, 1.0, v135
	v_add_f32_e32 v135, v88, v136
	v_mul_f32_e32 v135, 0xbfb8aa3b, v135
	v_add_f32_e32 v136, v89, v137
	v_exp_f32_e32 v135, v135
	v_mul_f32_e32 v136, 0xbfb8aa3b, v136
	v_exp_f32_e32 v136, v136
	v_rcp_f32_e32 v169, v16
	v_add_f32_e32 v16, 1.0, v135
	v_rcp_f32_e32 v171, v16
	v_add_f32_e32 v16, 1.0, v136
	v_pk_fma_f32 v[136:137], v[166:167], s[26:27], 0.5 op_sel_hi:[1,0,0]
	v_pk_fma_f32 v[166:167], v[168:169], s[26:27], 0.5 op_sel_hi:[1,0,0]
	v_rcp_f32_e32 v135, v16
	v_cvt_u32_f32_e32 v16, v167
	v_cvt_u32_f32_e32 v154, v166
	v_cvt_u32_f32_e32 v137, v137
	v_cvt_u32_f32_e32 v136, v136
	v_lshlrev_b32_e32 v16, 8, v16
	v_lshlrev_b32_e32 v154, 8, v154
	v_or_b32_e32 v16, v16, v137
	v_or_b32_e32 v154, v154, v136
	v_pk_fma_f32 v[136:137], v[170:171], s[26:27], 0.5 op_sel_hi:[1,0,0]
	v_pk_fma_f32 v[134:135], v[134:135], s[26:27], 0.5 op_sel_hi:[1,0,0]
	v_cvt_u32_f32_sdwa v136, v136 dst_sel:WORD_1 dst_unused:UNUSED_PAD src0_sel:DWORD
	v_cvt_u32_f32_sdwa v137, v137 dst_sel:WORD_1 dst_unused:UNUSED_PAD src0_sel:DWORD
	v_cvt_u32_f32_sdwa v134, v134 dst_sel:BYTE_3 dst_unused:UNUSED_PAD src0_sel:DWORD
	v_cvt_u32_f32_sdwa v135, v135 dst_sel:BYTE_3 dst_unused:UNUSED_PAD src0_sel:DWORD
	v_or_b32_e32 v136, v154, v136
	v_ashrrev_i32_e32 v165, 31, v164
	v_or_b32_e32 v16, v16, v137
	v_or_b32_e32 v134, v136, v134
	v_lshlrev_b64 v[136:137], 5, v[164:165]
	v_or_b32_e32 v135, v16, v135
	v_lshl_add_u64 v[136:137], v[162:163], 0, v[136:137]
	global_store_dwordx2 v[136:137], v[134:135], off

; DI float sigmoidf_(float x) { return __builtin_amdgcn_rcpf(1.f + __expf(-x)); }
;   template <int GRP>
;   DI void run(const f32x4 (&acc)[2][2][4][2], const pg8::Unit& u, int wr, int wc, int fr, int fq) const {
;     ...
;             if (act == 2) {
;               u32x2v g8;
; #pragma unroll
;               for (int n = 0; n < 2; ++n) {
;                 const f32x4 v = acc[ai][bj][m][n] + bp[n];
;                 unsigned q = 0u;
; #pragma unroll
;                 for (int j = 0; j < 4; ++j) q |= ((unsigned)(sigmoidf_(v[j]) * 255.f + 0.5f)) << (8 * j);
;                 if (n == 0) g8.x = q; else g8.y = q;
;               }
;               *reinterpret_cast<u32x2v*>(reinterpret_cast<unsigned char*>(ws + off) + (size_t)row * 1024 + c0 + 32 * wc + 8 * fq) = g8;
.LBB0_573:
	s_and_b64 vcc, exec, s[26:27]
	s_cbranch_vccz .LBB0_575
	s_waitcnt lgkmcnt(0)
	v_add_f32_e32 v16, v82, v134
	v_mul_f32_e32 v16, 0xbfb8aa3b, v16
	v_add_f32_e32 v134, v83, v135
	v_exp_f32_e32 v16, v16
	v_mul_f32_e32 v134, 0xbfb8aa3b, v134
	v_exp_f32_e32 v134, v134
	s_mov_b32 s26, 0x437f0000
	v_add_f32_e32 v16, 1.0, v16
	v_rcp_f32_e32 v166, v16
	v_add_f32_e32 v16, 1.0, v134
	v_add_f32_e32 v134, v84, v136
	v_mul_f32_e32 v134, 0xbfb8aa3b, v134
	v_exp_f32_e32 v154, v134
	v_add_f32_e32 v134, v85, v137
	v_mul_f32_e32 v134, 0xbfb8aa3b, v134
	v_exp_f32_e32 v155, v134
	ds_read_b128 v[134:137], v195 offset:16
	v_rcp_f32_e32 v168, v16
	v_add_f32_e32 v16, 1.0, v154
	v_rcp_f32_e32 v170, v16
	v_add_f32_e32 v16, 1.0, v155
	s_waitcnt lgkmcnt(0)
	v_add_f32_e32 v134, v78, v134
	v_mul_f32_e32 v134, 0xbfb8aa3b, v134
	v_exp_f32_e32 v154, v134
	v_add_f32_e32 v134, v79, v135
	v_mul_f32_e32 v134, 0xbfb8aa3b, v134
	v_exp_f32_e32 v135, v134
	v_rcp_f32_e32 v134, v16
	v_add_f32_e32 v16, 1.0, v154
	v_rcp_f32_e32 v167, v16
	v_add_f32_e32 v16, 1.0, v135
	v_add_f32_e32 v135, v80, v136
	v_mul_f32_e32 v135, 0xbfb8aa3b, v135
	v_add_f32_e32 v136, v81, v137
	v_exp_f32_e32 v135, v135
	v_mul_f32_e32 v136, 0xbfb8aa3b, v136
	v_exp_f32_e32 v136, v136
	v_rcp_f32_e32 v169, v16
	v_add_f32_e32 v16, 1.0, v135
	v_rcp_f32_e32 v171, v16
	v_add_f32_e32 v16, 1.0, v136
	v_pk_fma_f32 v[136:137], v[166:167], s[26:27], 0.5 op_sel_hi:[1,0,0]
	v_pk_fma_f32 v[166:167], v[168:169], s[26:27], 0.5 op_sel_hi:[1,0,0]
	v_rcp_f32_e32 v135, v16
	v_cvt_u32_f32_e32 v16, v167
	v_cvt_u32_f32_e32 v154, v166
	v_cvt_u32_f32_e32 v137, v137
	v_cvt_u32_f32_e32 v136, v136
	v_lshlrev_b32_e32 v16, 8, v16
	v_lshlrev_b32_e32 v154, 8, v154
	v_or_b32_e32 v16, v16, v137
	v_or_b32_e32 v154, v154, v136
	v_pk_fma_f32 v[136:137], v[170:171], s[26:27], 0.5 op_sel_hi:[1,0,0]
	v_pk_fma_f32 v[134:135], v[134:135], s[26:27], 0.5 op_sel_hi:[1,0,0]
	v_cvt_u32_f32_sdwa v136, v136 dst_sel:WORD_1 dst_unused:UNUSED_PAD src0_sel:DWORD
	v_cvt_u32_f32_sdwa v137, v137 dst_sel:WORD_1 dst_unused:UNUSED_PAD src0_sel:DWORD
	v_cvt_u32_f32_sdwa v134, v134 dst_sel:BYTE_3 dst_unused:UNUSED_PAD src0_sel:DWORD
	v_cvt_u32_f32_sdwa v135, v135 dst_sel:BYTE_3 dst_unused:UNUSED_PAD src0_sel:DWORD
	v_or_b32_e32 v136, v154, v136
	v_ashrrev_i32_e32 v165, 31, v164
	v_or_b32_e32 v16, v16, v137
	v_or_b32_e32 v134, v136, v134
	v_lshlrev_b64 v[136:137], 5, v[164:165]
	v_or_b32_e32 v135, v16, v135
	v_lshl_add_u64 v[136:137], v[162:163], 0, v[136:137]
	global_store_dwordx2 v[136:137], v[134:135], off

; DI float sigmoidf_(float x) { return __builtin_amdgcn_rcpf(1.f + __expf(-x)); }
;   template <int GRP>
;   DI void run(const f32x4 (&acc)[2][2][4][2], const pg8::Unit& u, int wr, int wc, int fr, int fq) const {
;     ...
;             if (act == 2) {
;               u32x2v g8;
; #pragma unroll
;               for (int n = 0; n < 2; ++n) {
;                 const f32x4 v = acc[ai][bj][m][n] + bp[n];
;                 unsigned q = 0u;
; #pragma unroll
;                 for (int j = 0; j < 4; ++j) q |= ((unsigned)(sigmoidf_(v[j]) * 255.f + 0.5f)) << (8 * j);
;                 if (n == 0) g8.x = q; else g8.y = q;
;               }
;               *reinterpret_cast<u32x2v*>(reinterpret_cast<unsigned char*>(ws + off) + (size_t)row * 1024 + c0 + 32 * wc + 8 * fq) = g8;
.LBB0_581:
	s_and_b64 vcc, exec, s[6:7]
	s_cbranch_vccz .LBB0_583
	s_waitcnt lgkmcnt(0)
	v_add_f32_e32 v16, v74, v134
	v_mul_f32_e32 v16, 0xbfb8aa3b, v16
	v_add_f32_e32 v134, v75, v135
	v_exp_f32_e32 v16, v16
	v_mul_f32_e32 v134, 0xbfb8aa3b, v134
	v_exp_f32_e32 v134, v134
	s_mov_b32 s4, 0x437f0000
	v_add_f32_e32 v16, 1.0, v16
	v_rcp_f32_e32 v150, v16
	v_add_f32_e32 v16, 1.0, v134
	v_add_f32_e32 v134, v76, v136
	v_mul_f32_e32 v134, 0xbfb8aa3b, v134
	v_exp_f32_e32 v151, v134
	v_add_f32_e32 v134, v77, v137
	v_mul_f32_e32 v134, 0xbfb8aa3b, v134
	v_exp_f32_e32 v154, v134
	ds_read_b128 v[134:137], v195 offset:16
	v_rcp_f32_e32 v166, v16
	v_add_f32_e32 v16, 1.0, v151
	v_rcp_f32_e32 v168, v16
	v_add_f32_e32 v16, 1.0, v154
	s_waitcnt lgkmcnt(0)
	v_add_f32_e32 v134, v70, v134
	v_mul_f32_e32 v134, 0xbfb8aa3b, v134
	v_exp_f32_e32 v151, v134
	v_add_f32_e32 v134, v71, v135
	v_mul_f32_e32 v134, 0xbfb8aa3b, v134
	v_exp_f32_e32 v135, v134
	v_rcp_f32_e32 v134, v16
	v_add_f32_e32 v16, 1.0, v151
	v_rcp_f32_e32 v151, v16
	v_add_f32_e32 v16, 1.0, v135
	v_add_f32_e32 v135, v72, v136
	v_mul_f32_e32 v135, 0xbfb8aa3b, v135
	v_add_f32_e32 v136, v73, v137
	v_exp_f32_e32 v135, v135
	v_mul_f32_e32 v136, 0xbfb8aa3b, v136
	v_exp_f32_e32 v136, v136
	v_rcp_f32_e32 v167, v16
	v_add_f32_e32 v16, 1.0, v135
	v_rcp_f32_e32 v169, v16
	v_add_f32_e32 v16, 1.0, v136
	v_pk_fma_f32 v[136:137], v[150:151], s[4:5], 0.5 op_sel_hi:[1,0,0]
	v_pk_fma_f32 v[150:151], v[166:167], s[4:5], 0.5 op_sel_hi:[1,0,0]
	v_rcp_f32_e32 v135, v16
	v_cvt_u32_f32_e32 v16, v151
	v_cvt_u32_f32_e32 v150, v150
	v_cvt_u32_f32_e32 v137, v137
	v_cvt_u32_f32_e32 v136, v136
	v_lshlrev_b32_e32 v16, 8, v16
	v_lshlrev_b32_e32 v150, 8, v150
	v_or_b32_e32 v16, v16, v137
	v_or_b32_e32 v150, v150, v136
	v_pk_fma_f32 v[136:137], v[168:169], s[4:5], 0.5 op_sel_hi:[1,0,0]
	v_pk_fma_f32 v[134:135], v[134:135], s[4:5], 0.5 op_sel_hi:[1,0,0]
	v_cvt_u32_f32_sdwa v136, v136 dst_sel:WORD_1 dst_unused:UNUSED_PAD src0_sel:DWORD
	v_cvt_u32_f32_sdwa v137, v137 dst_sel:WORD_1 dst_unused:UNUSED_PAD src0_sel:DWORD
	v_cvt_u32_f32_sdwa v134, v134 dst_sel:BYTE_3 dst_unused:UNUSED_PAD src0_sel:DWORD
	v_cvt_u32_f32_sdwa v135, v135 dst_sel:BYTE_3 dst_unused:UNUSED_PAD src0_sel:DWORD
	v_or_b32_e32 v136, v150, v136
	v_ashrrev_i32_e32 v165, 31, v164
	v_or_b32_e32 v16, v16, v137
	v_or_b32_e32 v134, v136, v134
	v_lshlrev_b64 v[136:137], 5, v[164:165]
	v_or_b32_e32 v135, v16, v135
	v_lshl_add_u64 v[136:137], v[162:163], 0, v[136:137]
	global_store_dwordx2 v[136:137], v[134:135], off

; DI float sigmoidf_(float x) { return __builtin_amdgcn_rcpf(1.f + __expf(-x)); }
;   template <int GRP>
;   DI void run(const f32x4 (&acc)[2][2][4][2], const pg8::Unit& u, int wr, int wc, int fr, int fq) const {
;     ...
;         if (nt < 4) { off = OFF_QAB; ld = 1024; c0 = nt * 128; act = 0; }
;         else if (nt < 16) { off = OFF_GA; ld = 512; c0 = (nt - 12) * 128; act = 1; }
;         else if (nt < 20) { off = OFF_QAB; ld = 1024; c0 = 512 + (nt - 16) * 128; act = 0; }
;         else if (nt < 25) { off = OFF_GB; ld = 512; c0 = (nt - 21) * 128; act = 1; }
;         else if (nt < 29) { off = OFF_QI; ld = 512; c0 = (nt - 25) * 128; act = 0; }
;         else if (nt < 38) { off = OFF_RA; ld = 1024; c0 = (nt - 30) * 128; act = 2; }
;         else { off = OFF_RB; ld = 1024; c0 = (nt - 38) * 128; act = 2; }
;         bf16_t* dst = reinterpret_cast<bf16_t*>(ws + off) + c0 + 32 * wc + 8 * fq;
; #pragma unroll
;         for (int ai = 0; ai < 2; ++ai)
; #pragma unroll
;           for (int m = 0; m < 4; ++m) {
;             int row = u.pm * 256 + 128 * ai + 64 * wr + 16 * m + fr;
;             asm volatile("" : "+v"(row));
;             if (act == 2) {
;               u32x2v g8;
; #pragma unroll
;               for (int n = 0; n < 2; ++n) {
;                 const f32x4 v = acc[ai][bj][m][n] + bp[n];
;                 unsigned q = 0u;
; #pragma unroll
;                 for (int j = 0; j < 4; ++j) q |= ((unsigned)(sigmoidf_(v[j]) * 255.f + 0.5f)) << (8 * j);
;                 if (n == 0) g8.x = q; else g8.y = q;
;               }
;               *reinterpret_cast<u32x2v*>(reinterpret_cast<unsigned char*>(ws + off) + (size_t)row * 1024 + c0 + 32 * wc + 8 * fq) = g8;
;               continue;
;             }
;             u32x4v pk;
; #pragma unroll
;             for (int n = 0; n < 2; ++n) {
;               f32x4 v = acc[ai][bj][m][n] + bp[n];
;               if (act != 0) {
; #pragma unroll
;                 for (int j = 0; j < 4; ++j) { const float sg = sigmoidf_(v[j]); v[j] = (act == 1) ? v[j] * sg : sg; }
.LBB0_858:
	s_xor_b64 s[28:29], s[28:29], -1
	v_readlane_b32 s50, v249, 0
	v_readlane_b32 s51, v249, 1
	s_add_u32 s11, s50, s4
	s_addc_u32 s23, s51, s5
	s_ashr_i32 s25, s24, 31
	s_lshl_b64 s[4:5], s[24:25], 1
	s_add_u32 s4, s11, s4
	s_addc_u32 s5, s23, s5
	s_lshl_b32 s33, s42, 1
	s_add_u32 s4, s4, s33
	s_addc_u32 s5, s5, 0
	v_lshlrev_b32_e32 v16, 1, v144
	v_lshl_add_u64 v[150:151], s[4:5], 0, v[16:17]
	s_add_u32 s4, s11, s24
	s_addc_u32 s5, s23, s25
	s_add_i32 s24, s24, s42
	s_lshr_b32 s24, s24, 5
	s_mul_i32 s24, s24, 0x204000
	s_add_u32 s24, s11, s24
	s_addc_u32 s25, s23, 0
	s_lshl_b32 s11, s48, 8
	v_add_u32_e32 v164, s11, v21
	s_waitcnt lgkmcnt(0)
	ds_read_b128 v[134:137], v176
	v_cndmask_b32_e64 v16, 0, 1, s[28:29]
	s_mov_b64 s[30:31], -1
	s_and_b64 vcc, exec, s[6:7]
	v_cmp_ne_u32_e64 s[4:5], 1, v16
	s_cbranch_vccnz .LBB0_864
	s_waitcnt lgkmcnt(0)
	v_pk_add_f32 v[162:163], v[68:69], v[136:137]
	s_and_b64 vcc, exec, s[4:5]
	v_pk_add_f32 v[166:167], v[66:67], v[134:135]
	s_cbranch_vccnz .LBB0_861
	v_mul_f32_e32 v16, 0xbfb8aa3b, v166
	v_exp_f32_e32 v16, v16
	v_mul_f32_e32 v155, 0xbfb8aa3b, v162
	v_mul_f32_e32 v154, 0xbfb8aa3b, v167
	v_exp_f32_e32 v154, v154
	v_add_f32_e32 v16, 1.0, v16
	v_rcp_f32_e32 v168, v16
	v_exp_f32_e32 v16, v155
	v_mul_f32_e32 v155, 0xbfb8aa3b, v163
	v_exp_f32_e32 v155, v155
	v_add_f32_e32 v154, 1.0, v154
	v_add_f32_e32 v16, 1.0, v16
	v_rcp_f32_e32 v170, v16
	v_add_f32_e32 v16, 1.0, v155
	v_rcp_f32_e32 v171, v16
	v_rcp_f32_e32 v169, v154
	v_pk_mul_f32 v[162:163], v[162:163], v[170:171]
	v_pk_mul_f32 v[166:167], v[166:167], v[168:169]

; DI float sigmoidf_(float x) { return __builtin_amdgcn_rcpf(1.f + __expf(-x)); }
;   template <int GRP>
;   DI void run(const f32x4 (&acc)[2][2][4][2], const pg8::Unit& u, int wr, int wc, int fr, int fq) const {
;     ...
;             if (act == 2) {
;               u32x2v g8;
; #pragma unroll
;               for (int n = 0; n < 2; ++n) {
;                 const f32x4 v = acc[ai][bj][m][n] + bp[n];
;                 unsigned q = 0u;
; #pragma unroll
;                 for (int j = 0; j < 4; ++j) q |= ((unsigned)(sigmoidf_(v[j]) * 255.f + 0.5f)) << (8 * j);
;                 if (n == 0) g8.x = q; else g8.y = q;
;               }
;               *reinterpret_cast<u32x2v*>(reinterpret_cast<unsigned char*>(ws + off) + (size_t)row * 1024 + c0 + 32 * wc + 8 * fq) = g8;
.LBB0_864:
	v_lshl_add_u64 v[162:163], s[24:25], 0, v[144:145]
	s_and_b64 vcc, exec, s[30:31]
	s_cbranch_vccz .LBB0_866
	s_waitcnt lgkmcnt(0)
	v_add_f32_e32 v16, v66, v134
	v_mul_f32_e32 v16, 0xbfb8aa3b, v16
	v_add_f32_e32 v134, v67, v135
	v_exp_f32_e32 v16, v16
	v_mul_f32_e32 v134, 0xbfb8aa3b, v134
	v_exp_f32_e32 v134, v134
	s_mov_b32 s24, 0x437f0000
	v_add_f32_e32 v16, 1.0, v16
	v_rcp_f32_e32 v166, v16
	v_add_f32_e32 v16, 1.0, v134
	v_add_f32_e32 v134, v68, v136
	v_mul_f32_e32 v134, 0xbfb8aa3b, v134
	v_exp_f32_e32 v154, v134
	v_add_f32_e32 v134, v69, v137
	v_mul_f32_e32 v134, 0xbfb8aa3b, v134
	v_exp_f32_e32 v155, v134
	ds_read_b128 v[134:137], v176 offset:16
	v_rcp_f32_e32 v168, v16
	v_add_f32_e32 v16, 1.0, v154
	v_rcp_f32_e32 v170, v16
	v_add_f32_e32 v16, 1.0, v155
	s_waitcnt lgkmcnt(0)
	v_add_f32_e32 v134, v62, v134
	v_mul_f32_e32 v134, 0xbfb8aa3b, v134
	v_exp_f32_e32 v154, v134
	v_add_f32_e32 v134, v63, v135
	v_mul_f32_e32 v134, 0xbfb8aa3b, v134
	v_exp_f32_e32 v135, v134
	v_rcp_f32_e32 v134, v16
	v_add_f32_e32 v16, 1.0, v154
	v_rcp_f32_e32 v167, v16
	v_add_f32_e32 v16, 1.0, v135
	v_add_f32_e32 v135, v64, v136
	v_mul_f32_e32 v135, 0xbfb8aa3b, v135
	v_add_f32_e32 v136, v65, v137
	v_exp_f32_e32 v135, v135
	v_mul_f32_e32 v136, 0xbfb8aa3b, v136
	v_exp_f32_e32 v136, v136
	v_rcp_f32_e32 v169, v16
	v_add_f32_e32 v16, 1.0, v135
	v_rcp_f32_e32 v171, v16
	v_add_f32_e32 v16, 1.0, v136
	v_pk_fma_f32 v[136:137], v[166:167], s[24:25], 0.5 op_sel_hi:[1,0,0]
	v_pk_fma_f32 v[166:167], v[168:169], s[24:25], 0.5 op_sel_hi:[1,0,0]
	v_rcp_f32_e32 v135, v16
	v_cvt_u32_f32_e32 v16, v167
	v_cvt_u32_f32_e32 v154, v166
	v_cvt_u32_f32_e32 v137, v137
	v_cvt_u32_f32_e32 v136, v136
	v_lshlrev_b32_e32 v16, 8, v16
	v_lshlrev_b32_e32 v154, 8, v154
	v_or_b32_e32 v16, v16, v137
	v_or_b32_e32 v154, v154, v136
	v_pk_fma_f32 v[136:137], v[170:171], s[24:25], 0.5 op_sel_hi:[1,0,0]
	v_pk_fma_f32 v[134:135], v[134:135], s[24:25], 0.5 op_sel_hi:[1,0,0]
	v_cvt_u32_f32_sdwa v136, v136 dst_sel:WORD_1 dst_unused:UNUSED_PAD src0_sel:DWORD
	v_cvt_u32_f32_sdwa v137, v137 dst_sel:WORD_1 dst_unused:UNUSED_PAD src0_sel:DWORD
	v_cvt_u32_f32_sdwa v134, v134 dst_sel:BYTE_3 dst_unused:UNUSED_PAD src0_sel:DWORD
	v_cvt_u32_f32_sdwa v135, v135 dst_sel:BYTE_3 dst_unused:UNUSED_PAD src0_sel:DWORD
	v_or_b32_e32 v136, v154, v136
	v_ashrrev_i32_e32 v165, 31, v164
	v_or_b32_e32 v16, v16, v137
	v_or_b32_e32 v134, v136, v134
	v_lshlrev_b64 v[136:137], 5, v[164:165]
	v_or_b32_e32 v135, v16, v135
	v_lshl_add_u64 v[136:137], v[162:163], 0, v[136:137]
	global_store_dwordx2 v[136:137], v[134:135], off

; DI float sigmoidf_(float x) { return __builtin_amdgcn_rcpf(1.f + __expf(-x)); }
;   template <int GRP>
;   DI void run(const f32x4 (&acc)[2][2][4][2], const pg8::Unit& u, int wr, int wc, int fr, int fq) const {
;     ...
;             if (act == 2) {
;               u32x2v g8;
; #pragma unroll
;               for (int n = 0; n < 2; ++n) {
;                 const f32x4 v = acc[ai][bj][m][n] + bp[n];
;                 unsigned q = 0u;
; #pragma unroll
;                 for (int j = 0; j < 4; ++j) q |= ((unsigned)(sigmoidf_(v[j]) * 255.f + 0.5f)) << (8 * j);
;                 if (n == 0) g8.x = q; else g8.y = q;
;               }
;               *reinterpret_cast<u32x2v*>(reinterpret_cast<unsigned char*>(ws + off) + (size_t)row * 1024 + c0 + 32 * wc + 8 * fq) = g8;
.LBB0_872:
	s_and_b64 vcc, exec, s[24:25]
	s_cbranch_vccz .LBB0_874
	s_waitcnt lgkmcnt(0)
	v_add_f32_e32 v16, v58, v134
	v_mul_f32_e32 v16, 0xbfb8aa3b, v16
	v_add_f32_e32 v134, v59, v135
	v_exp_f32_e32 v16, v16
	v_mul_f32_e32 v134, 0xbfb8aa3b, v134
	v_exp_f32_e32 v134, v134
	s_mov_b32 s24, 0x437f0000
	v_add_f32_e32 v16, 1.0, v16
	v_rcp_f32_e32 v166, v16
	v_add_f32_e32 v16, 1.0, v134
	v_add_f32_e32 v134, v60, v136
	v_mul_f32_e32 v134, 0xbfb8aa3b, v134
	v_exp_f32_e32 v154, v134
	v_add_f32_e32 v134, v61, v137
	v_mul_f32_e32 v134, 0xbfb8aa3b, v134
	v_exp_f32_e32 v155, v134
	ds_read_b128 v[134:137], v176 offset:16
	v_rcp_f32_e32 v168, v16
	v_add_f32_e32 v16, 1.0, v154
	v_rcp_f32_e32 v170, v16
	v_add_f32_e32 v16, 1.0, v155
	s_waitcnt lgkmcnt(0)
	v_add_f32_e32 v134, v54, v134
	v_mul_f32_e32 v134, 0xbfb8aa3b, v134
	v_exp_f32_e32 v154, v134
	v_add_f32_e32 v134, v55, v135
	v_mul_f32_e32 v134, 0xbfb8aa3b, v134
	v_exp_f32_e32 v135, v134
	v_rcp_f32_e32 v134, v16
	v_add_f32_e32 v16, 1.0, v154
	v_rcp_f32_e32 v167, v16
	v_add_f32_e32 v16, 1.0, v135
	v_add_f32_e32 v135, v56, v136
	v_mul_f32_e32 v135, 0xbfb8aa3b, v135
	v_add_f32_e32 v136, v57, v137
	v_exp_f32_e32 v135, v135
	v_mul_f32_e32 v136, 0xbfb8aa3b, v136
	v_exp_f32_e32 v136, v136
	v_rcp_f32_e32 v169, v16
	v_add_f32_e32 v16, 1.0, v135
	v_rcp_f32_e32 v171, v16
	v_add_f32_e32 v16, 1.0, v136
	v_pk_fma_f32 v[136:137], v[166:167], s[24:25], 0.5 op_sel_hi:[1,0,0]
	v_pk_fma_f32 v[166:167], v[168:169], s[24:25], 0.5 op_sel_hi:[1,0,0]
	v_rcp_f32_e32 v135, v16
	v_cvt_u32_f32_e32 v16, v167
	v_cvt_u32_f32_e32 v154, v166
	v_cvt_u32_f32_e32 v137, v137
	v_cvt_u32_f32_e32 v136, v136
	v_lshlrev_b32_e32 v16, 8, v16
	v_lshlrev_b32_e32 v154, 8, v154
	v_or_b32_e32 v16, v16, v137
	v_or_b32_e32 v154, v154, v136
	v_pk_fma_f32 v[136:137], v[170:171], s[24:25], 0.5 op_sel_hi:[1,0,0]
	v_pk_fma_f32 v[134:135], v[134:135], s[24:25], 0.5 op_sel_hi:[1,0,0]
	v_cvt_u32_f32_sdwa v136, v136 dst_sel:WORD_1 dst_unused:UNUSED_PAD src0_sel:DWORD
	v_cvt_u32_f32_sdwa v137, v137 dst_sel:WORD_1 dst_unused:UNUSED_PAD src0_sel:DWORD
	v_cvt_u32_f32_sdwa v134, v134 dst_sel:BYTE_3 dst_unused:UNUSED_PAD src0_sel:DWORD
	v_cvt_u32_f32_sdwa v135, v135 dst_sel:BYTE_3 dst_unused:UNUSED_PAD src0_sel:DWORD
	v_or_b32_e32 v136, v154, v136
	v_ashrrev_i32_e32 v165, 31, v164
	v_or_b32_e32 v16, v16, v137
	v_or_b32_e32 v134, v136, v134
	v_lshlrev_b64 v[136:137], 5, v[164:165]
	v_or_b32_e32 v135, v16, v135
	v_lshl_add_u64 v[136:137], v[162:163], 0, v[136:137]
	global_store_dwordx2 v[136:137], v[134:135], off

; DI float sigmoidf_(float x) { return __builtin_amdgcn_rcpf(1.f + __expf(-x)); }
;   template <int GRP>
;   DI void run(const f32x4 (&acc)[2][2][4][2], const pg8::Unit& u, int wr, int wc, int fr, int fq) const {
;     ...
;             if (act == 2) {
;               u32x2v g8;
; #pragma unroll
;               for (int n = 0; n < 2; ++n) {
;                 const f32x4 v = acc[ai][bj][m][n] + bp[n];
;                 unsigned q = 0u;
; #pragma unroll
;                 for (int j = 0; j < 4; ++j) q |= ((unsigned)(sigmoidf_(v[j]) * 255.f + 0.5f)) << (8 * j);
;                 if (n == 0) g8.x = q; else g8.y = q;
;               }
;               *reinterpret_cast<u32x2v*>(reinterpret_cast<unsigned char*>(ws + off) + (size_t)row * 1024 + c0 + 32 * wc + 8 * fq) = g8;
.LBB0_880:
	s_and_b64 vcc, exec, s[24:25]
	s_cbranch_vccz .LBB0_882
	s_waitcnt lgkmcnt(0)
	v_add_f32_e32 v16, v50, v134
	v_mul_f32_e32 v16, 0xbfb8aa3b, v16
	v_add_f32_e32 v134, v51, v135
	v_exp_f32_e32 v16, v16
	v_mul_f32_e32 v134, 0xbfb8aa3b, v134
	v_exp_f32_e32 v134, v134
	s_mov_b32 s24, 0x437f0000
	v_add_f32_e32 v16, 1.0, v16
	v_rcp_f32_e32 v166, v16
	v_add_f32_e32 v16, 1.0, v134
	v_add_f32_e32 v134, v52, v136
	v_mul_f32_e32 v134, 0xbfb8aa3b, v134
	v_exp_f32_e32 v154, v134
	v_add_f32_e32 v134, v53, v137
	v_mul_f32_e32 v134, 0xbfb8aa3b, v134
	v_exp_f32_e32 v155, v134
	ds_read_b128 v[134:137], v176 offset:16
	v_rcp_f32_e32 v168, v16
	v_add_f32_e32 v16, 1.0, v154
	v_rcp_f32_e32 v170, v16
	v_add_f32_e32 v16, 1.0, v155
	s_waitcnt lgkmcnt(0)
	v_add_f32_e32 v134, v46, v134
	v_mul_f32_e32 v134, 0xbfb8aa3b, v134
	v_exp_f32_e32 v154, v134
	v_add_f32_e32 v134, v47, v135
	v_mul_f32_e32 v134, 0xbfb8aa3b, v134
	v_exp_f32_e32 v135, v134
	v_rcp_f32_e32 v134, v16
	v_add_f32_e32 v16, 1.0, v154
	v_rcp_f32_e32 v167, v16
	v_add_f32_e32 v16, 1.0, v135
	v_add_f32_e32 v135, v48, v136
	v_mul_f32_e32 v135, 0xbfb8aa3b, v135
	v_add_f32_e32 v136, v49, v137
	v_exp_f32_e32 v135, v135
	v_mul_f32_e32 v136, 0xbfb8aa3b, v136
	v_exp_f32_e32 v136, v136
	v_rcp_f32_e32 v169, v16
	v_add_f32_e32 v16, 1.0, v135
	v_rcp_f32_e32 v171, v16
	v_add_f32_e32 v16, 1.0, v136
	v_pk_fma_f32 v[136:137], v[166:167], s[24:25], 0.5 op_sel_hi:[1,0,0]
	v_pk_fma_f32 v[166:167], v[168:169], s[24:25], 0.5 op_sel_hi:[1,0,0]
	v_rcp_f32_e32 v135, v16
	v_cvt_u32_f32_e32 v16, v167
	v_cvt_u32_f32_e32 v154, v166
	v_cvt_u32_f32_e32 v137, v137
	v_cvt_u32_f32_e32 v136, v136
	v_lshlrev_b32_e32 v16, 8, v16
	v_lshlrev_b32_e32 v154, 8, v154
	v_or_b32_e32 v16, v16, v137
	v_or_b32_e32 v154, v154, v136
	v_pk_fma_f32 v[136:137], v[170:171], s[24:25], 0.5 op_sel_hi:[1,0,0]
	v_pk_fma_f32 v[134:135], v[134:135], s[24:25], 0.5 op_sel_hi:[1,0,0]
	v_cvt_u32_f32_sdwa v136, v136 dst_sel:WORD_1 dst_unused:UNUSED_PAD src0_sel:DWORD
	v_cvt_u32_f32_sdwa v137, v137 dst_sel:WORD_1 dst_unused:UNUSED_PAD src0_sel:DWORD
	v_cvt_u32_f32_sdwa v134, v134 dst_sel:BYTE_3 dst_unused:UNUSED_PAD src0_sel:DWORD
	v_cvt_u32_f32_sdwa v135, v135 dst_sel:BYTE_3 dst_unused:UNUSED_PAD src0_sel:DWORD
	v_or_b32_e32 v136, v154, v136
	v_ashrrev_i32_e32 v165, 31, v164
	v_or_b32_e32 v16, v16, v137
	v_or_b32_e32 v134, v136, v134
	v_lshlrev_b64 v[136:137], 5, v[164:165]
	v_or_b32_e32 v135, v16, v135
	v_lshl_add_u64 v[136:137], v[162:163], 0, v[136:137]
	global_store_dwordx2 v[136:137], v[134:135], off

; DI float sigmoidf_(float x) { return __builtin_amdgcn_rcpf(1.f + __expf(-x)); }
;   template <int GRP>
;   DI void run(const f32x4 (&acc)[2][2][4][2], const pg8::Unit& u, int wr, int wc, int fr, int fq) const {
;     ...
;             if (act == 2) {
;               u32x2v g8;
; #pragma unroll
;               for (int n = 0; n < 2; ++n) {
;                 const f32x4 v = acc[ai][bj][m][n] + bp[n];
;                 unsigned q = 0u;
; #pragma unroll
;                 for (int j = 0; j < 4; ++j) q |= ((unsigned)(sigmoidf_(v[j]) * 255.f + 0.5f)) << (8 * j);
;                 if (n == 0) g8.x = q; else g8.y = q;
;               }
;               *reinterpret_cast<u32x2v*>(reinterpret_cast<unsigned char*>(ws + off) + (size_t)row * 1024 + c0 + 32 * wc + 8 * fq) = g8;
.LBB0_888:
	s_and_b64 vcc, exec, s[24:25]
	s_cbranch_vccz .LBB0_890
	s_waitcnt lgkmcnt(0)
	v_add_f32_e32 v16, v42, v134
	v_mul_f32_e32 v16, 0xbfb8aa3b, v16
	v_add_f32_e32 v134, v43, v135
	v_exp_f32_e32 v16, v16
	v_mul_f32_e32 v134, 0xbfb8aa3b, v134
	v_exp_f32_e32 v134, v134
	s_mov_b32 s24, 0x437f0000
	v_add_f32_e32 v16, 1.0, v16
	v_rcp_f32_e32 v166, v16
	v_add_f32_e32 v16, 1.0, v134
	v_add_f32_e32 v134, v44, v136
	v_mul_f32_e32 v134, 0xbfb8aa3b, v134
	v_exp_f32_e32 v154, v134
	v_add_f32_e32 v134, v45, v137
	v_mul_f32_e32 v134, 0xbfb8aa3b, v134
	v_exp_f32_e32 v155, v134
	ds_read_b128 v[134:137], v176 offset:16
	v_rcp_f32_e32 v168, v16
	v_add_f32_e32 v16, 1.0, v154
	v_rcp_f32_e32 v170, v16
	v_add_f32_e32 v16, 1.0, v155
	s_waitcnt lgkmcnt(0)
	v_add_f32_e32 v134, v38, v134
	v_mul_f32_e32 v134, 0xbfb8aa3b, v134
	v_exp_f32_e32 v154, v134
	v_add_f32_e32 v134, v39, v135
	v_mul_f32_e32 v134, 0xbfb8aa3b, v134
	v_exp_f32_e32 v135, v134
	v_rcp_f32_e32 v134, v16
	v_add_f32_e32 v16, 1.0, v154
	v_rcp_f32_e32 v167, v16
	v_add_f32_e32 v16, 1.0, v135
	v_add_f32_e32 v135, v40, v136
	v_mul_f32_e32 v135, 0xbfb8aa3b, v135
	v_add_f32_e32 v136, v41, v137
	v_exp_f32_e32 v135, v135
	v_mul_f32_e32 v136, 0xbfb8aa3b, v136
	v_exp_f32_e32 v136, v136
	v_rcp_f32_e32 v169, v16
	v_add_f32_e32 v16, 1.0, v135
	v_rcp_f32_e32 v171, v16
	v_add_f32_e32 v16, 1.0, v136
	v_pk_fma_f32 v[136:137], v[166:167], s[24:25], 0.5 op_sel_hi:[1,0,0]
	v_pk_fma_f32 v[166:167], v[168:169], s[24:25], 0.5 op_sel_hi:[1,0,0]
	v_rcp_f32_e32 v135, v16
	v_cvt_u32_f32_e32 v16, v167
	v_cvt_u32_f32_e32 v154, v166
	v_cvt_u32_f32_e32 v137, v137
	v_cvt_u32_f32_e32 v136, v136
	v_lshlrev_b32_e32 v16, 8, v16
	v_lshlrev_b32_e32 v154, 8, v154
	v_or_b32_e32 v16, v16, v137
	v_or_b32_e32 v154, v154, v136
	v_pk_fma_f32 v[136:137], v[170:171], s[24:25], 0.5 op_sel_hi:[1,0,0]
	v_pk_fma_f32 v[134:135], v[134:135], s[24:25], 0.5 op_sel_hi:[1,0,0]
	v_cvt_u32_f32_sdwa v136, v136 dst_sel:WORD_1 dst_unused:UNUSED_PAD src0_sel:DWORD
	v_cvt_u32_f32_sdwa v137, v137 dst_sel:WORD_1 dst_unused:UNUSED_PAD src0_sel:DWORD
	v_cvt_u32_f32_sdwa v134, v134 dst_sel:BYTE_3 dst_unused:UNUSED_PAD src0_sel:DWORD
	v_cvt_u32_f32_sdwa v135, v135 dst_sel:BYTE_3 dst_unused:UNUSED_PAD src0_sel:DWORD
	v_or_b32_e32 v136, v154, v136
	v_ashrrev_i32_e32 v165, 31, v164
	v_or_b32_e32 v16, v16, v137
	v_or_b32_e32 v134, v136, v134
	v_lshlrev_b64 v[136:137], 5, v[164:165]
	v_or_b32_e32 v135, v16, v135
	v_lshl_add_u64 v[136:137], v[162:163], 0, v[136:137]
	global_store_dwordx2 v[136:137], v[134:135], off

; DI float sigmoidf_(float x) { return __builtin_amdgcn_rcpf(1.f + __expf(-x)); }
;   template <int GRP>
;   DI void run(const f32x4 (&acc)[2][2][4][2], const pg8::Unit& u, int wr, int wc, int fr, int fq) const {
;     ...
;             if (act == 2) {
;               u32x2v g8;
; #pragma unroll
;               for (int n = 0; n < 2; ++n) {
;                 const f32x4 v = acc[ai][bj][m][n] + bp[n];
;                 unsigned q = 0u;
; #pragma unroll
;                 for (int j = 0; j < 4; ++j) q |= ((unsigned)(sigmoidf_(v[j]) * 255.f + 0.5f)) << (8 * j);
;                 if (n == 0) g8.x = q; else g8.y = q;
;               }
;               *reinterpret_cast<u32x2v*>(reinterpret_cast<unsigned char*>(ws + off) + (size_t)row * 1024 + c0 + 32 * wc + 8 * fq) = g8;
.LBB0_896:
	s_and_b64 vcc, exec, s[24:25]
	s_cbranch_vccz .LBB0_898
	s_waitcnt lgkmcnt(0)
	v_add_f32_e32 v16, v34, v134
	v_mul_f32_e32 v16, 0xbfb8aa3b, v16
	v_add_f32_e32 v134, v35, v135
	v_exp_f32_e32 v16, v16
	v_mul_f32_e32 v134, 0xbfb8aa3b, v134
	v_exp_f32_e32 v134, v134
	s_mov_b32 s24, 0x437f0000
	v_add_f32_e32 v16, 1.0, v16
	v_rcp_f32_e32 v166, v16
	v_add_f32_e32 v16, 1.0, v134
	v_add_f32_e32 v134, v36, v136
	v_mul_f32_e32 v134, 0xbfb8aa3b, v134
	v_exp_f32_e32 v154, v134
	v_add_f32_e32 v134, v37, v137
	v_mul_f32_e32 v134, 0xbfb8aa3b, v134
	v_exp_f32_e32 v155, v134
	ds_read_b128 v[134:137], v176 offset:16
	v_rcp_f32_e32 v168, v16
	v_add_f32_e32 v16, 1.0, v154
	v_rcp_f32_e32 v170, v16
	v_add_f32_e32 v16, 1.0, v155
	s_waitcnt lgkmcnt(0)
	v_add_f32_e32 v134, v30, v134
	v_mul_f32_e32 v134, 0xbfb8aa3b, v134
	v_exp_f32_e32 v154, v134
	v_add_f32_e32 v134, v31, v135
	v_mul_f32_e32 v134, 0xbfb8aa3b, v134
	v_exp_f32_e32 v135, v134
	v_rcp_f32_e32 v134, v16
	v_add_f32_e32 v16, 1.0, v154
	v_rcp_f32_e32 v167, v16
	v_add_f32_e32 v16, 1.0, v135
	v_add_f32_e32 v135, v32, v136
	v_mul_f32_e32 v135, 0xbfb8aa3b, v135
	v_add_f32_e32 v136, v33, v137
	v_exp_f32_e32 v135, v135
	v_mul_f32_e32 v136, 0xbfb8aa3b, v136
	v_exp_f32_e32 v136, v136
	v_rcp_f32_e32 v169, v16
	v_add_f32_e32 v16, 1.0, v135
	v_rcp_f32_e32 v171, v16
	v_add_f32_e32 v16, 1.0, v136
	v_pk_fma_f32 v[136:137], v[166:167], s[24:25], 0.5 op_sel_hi:[1,0,0]
	v_pk_fma_f32 v[166:167], v[168:169], s[24:25], 0.5 op_sel_hi:[1,0,0]
	v_rcp_f32_e32 v135, v16
	v_cvt_u32_f32_e32 v16, v167
	v_cvt_u32_f32_e32 v154, v166
	v_cvt_u32_f32_e32 v137, v137
	v_cvt_u32_f32_e32 v136, v136
	v_lshlrev_b32_e32 v16, 8, v16
	v_lshlrev_b32_e32 v154, 8, v154
	v_or_b32_e32 v16, v16, v137
	v_or_b32_e32 v154, v154, v136
	v_pk_fma_f32 v[136:137], v[170:171], s[24:25], 0.5 op_sel_hi:[1,0,0]
	v_pk_fma_f32 v[134:135], v[134:135], s[24:25], 0.5 op_sel_hi:[1,0,0]
	v_cvt_u32_f32_sdwa v136, v136 dst_sel:WORD_1 dst_unused:UNUSED_PAD src0_sel:DWORD
	v_cvt_u32_f32_sdwa v137, v137 dst_sel:WORD_1 dst_unused:UNUSED_PAD src0_sel:DWORD
	v_cvt_u32_f32_sdwa v134, v134 dst_sel:BYTE_3 dst_unused:UNUSED_PAD src0_sel:DWORD
	v_cvt_u32_f32_sdwa v135, v135 dst_sel:BYTE_3 dst_unused:UNUSED_PAD src0_sel:DWORD
	v_or_b32_e32 v136, v154, v136
	v_ashrrev_i32_e32 v165, 31, v164
	v_or_b32_e32 v16, v16, v137
	v_or_b32_e32 v134, v136, v134
	v_lshlrev_b64 v[136:137], 5, v[164:165]
	v_or_b32_e32 v135, v16, v135
	v_lshl_add_u64 v[136:137], v[162:163], 0, v[136:137]
	global_store_dwordx2 v[136:137], v[134:135], off

; DI float sigmoidf_(float x) { return __builtin_amdgcn_rcpf(1.f + __expf(-x)); }
;   template <int GRP>
;   DI void run(const f32x4 (&acc)[2][2][4][2], const pg8::Unit& u, int wr, int wc, int fr, int fq) const {
;     ...
;             if (act == 2) {
;               u32x2v g8;
; #pragma unroll
;               for (int n = 0; n < 2; ++n) {
;                 const f32x4 v = acc[ai][bj][m][n] + bp[n];
;                 unsigned q = 0u;
; #pragma unroll
;                 for (int j = 0; j < 4; ++j) q |= ((unsigned)(sigmoidf_(v[j]) * 255.f + 0.5f)) << (8 * j);
;                 if (n == 0) g8.x = q; else g8.y = q;
;               }
;               *reinterpret_cast<u32x2v*>(reinterpret_cast<unsigned char*>(ws + off) + (size_t)row * 1024 + c0 + 32 * wc + 8 * fq) = g8;
.LBB0_904:
	s_and_b64 vcc, exec, s[24:25]
	s_cbranch_vccz .LBB0_906
	s_waitcnt lgkmcnt(0)
	v_add_f32_e32 v16, v26, v134
	v_mul_f32_e32 v16, 0xbfb8aa3b, v16
	v_add_f32_e32 v134, v27, v135
	v_exp_f32_e32 v16, v16
	v_mul_f32_e32 v134, 0xbfb8aa3b, v134
	v_exp_f32_e32 v134, v134
	s_mov_b32 s24, 0x437f0000
	v_add_f32_e32 v16, 1.0, v16
	v_rcp_f32_e32 v166, v16
	v_add_f32_e32 v16, 1.0, v134
	v_add_f32_e32 v134, v28, v136
	v_mul_f32_e32 v134, 0xbfb8aa3b, v134
	v_exp_f32_e32 v154, v134
	v_add_f32_e32 v134, v29, v137
	v_mul_f32_e32 v134, 0xbfb8aa3b, v134
	v_exp_f32_e32 v155, v134
	ds_read_b128 v[134:137], v176 offset:16
	v_rcp_f32_e32 v168, v16
	v_add_f32_e32 v16, 1.0, v154
	v_rcp_f32_e32 v170, v16
	v_add_f32_e32 v16, 1.0, v155
	s_waitcnt lgkmcnt(0)
	v_add_f32_e32 v134, v22, v134
	v_mul_f32_e32 v134, 0xbfb8aa3b, v134
	v_exp_f32_e32 v154, v134
	v_add_f32_e32 v134, v23, v135
	v_mul_f32_e32 v134, 0xbfb8aa3b, v134
	v_exp_f32_e32 v135, v134
	v_rcp_f32_e32 v134, v16
	v_add_f32_e32 v16, 1.0, v154
	v_rcp_f32_e32 v167, v16
	v_add_f32_e32 v16, 1.0, v135
	v_add_f32_e32 v135, v24, v136
	v_mul_f32_e32 v135, 0xbfb8aa3b, v135
	v_add_f32_e32 v136, v25, v137
	v_exp_f32_e32 v135, v135
	v_mul_f32_e32 v136, 0xbfb8aa3b, v136
	v_exp_f32_e32 v136, v136
	v_rcp_f32_e32 v169, v16
	v_add_f32_e32 v16, 1.0, v135
	v_rcp_f32_e32 v171, v16
	v_add_f32_e32 v16, 1.0, v136
	v_pk_fma_f32 v[136:137], v[166:167], s[24:25], 0.5 op_sel_hi:[1,0,0]
	v_pk_fma_f32 v[166:167], v[168:169], s[24:25], 0.5 op_sel_hi:[1,0,0]
	v_rcp_f32_e32 v135, v16
	v_cvt_u32_f32_e32 v16, v167
	v_cvt_u32_f32_e32 v154, v166
	v_cvt_u32_f32_e32 v137, v137
	v_cvt_u32_f32_e32 v136, v136
	v_lshlrev_b32_e32 v16, 8, v16
	v_lshlrev_b32_e32 v154, 8, v154
	v_or_b32_e32 v16, v16, v137
	v_or_b32_e32 v154, v154, v136
	v_pk_fma_f32 v[136:137], v[170:171], s[24:25], 0.5 op_sel_hi:[1,0,0]
	v_pk_fma_f32 v[134:135], v[134:135], s[24:25], 0.5 op_sel_hi:[1,0,0]
	v_cvt_u32_f32_sdwa v136, v136 dst_sel:WORD_1 dst_unused:UNUSED_PAD src0_sel:DWORD
	v_cvt_u32_f32_sdwa v137, v137 dst_sel:WORD_1 dst_unused:UNUSED_PAD src0_sel:DWORD
	v_cvt_u32_f32_sdwa v134, v134 dst_sel:BYTE_3 dst_unused:UNUSED_PAD src0_sel:DWORD
	v_cvt_u32_f32_sdwa v135, v135 dst_sel:BYTE_3 dst_unused:UNUSED_PAD src0_sel:DWORD
	v_or_b32_e32 v136, v154, v136
	v_ashrrev_i32_e32 v165, 31, v164
	v_or_b32_e32 v16, v16, v137
	v_or_b32_e32 v134, v136, v134
	v_lshlrev_b64 v[136:137], 5, v[164:165]
	v_or_b32_e32 v135, v16, v135
	v_lshl_add_u64 v[136:137], v[162:163], 0, v[136:137]
	global_store_dwordx2 v[136:137], v[134:135], off

; DI float sigmoidf_(float x) { return __builtin_amdgcn_rcpf(1.f + __expf(-x)); }
;   template <int GRP>
;   DI void run(const f32x4 (&acc)[2][2][4][2], const pg8::Unit& u, int wr, int wc, int fr, int fq) const {
;     ...
;             if (act == 2) {
;               u32x2v g8;
; #pragma unroll
;               for (int n = 0; n < 2; ++n) {
;                 const f32x4 v = acc[ai][bj][m][n] + bp[n];
;                 unsigned q = 0u;
; #pragma unroll
;                 for (int j = 0; j < 4; ++j) q |= ((unsigned)(sigmoidf_(v[j]) * 255.f + 0.5f)) << (8 * j);
;                 if (n == 0) g8.x = q; else g8.y = q;
;               }
;               *reinterpret_cast<u32x2v*>(reinterpret_cast<unsigned char*>(ws + off) + (size_t)row * 1024 + c0 + 32 * wc + 8 * fq) = g8;
.LBB0_912:
	s_and_b64 vcc, exec, s[24:25]
	s_cbranch_vccz .LBB0_914
	s_waitcnt lgkmcnt(0)
	v_add_f32_e32 v16, v12, v134
	v_mul_f32_e32 v16, 0xbfb8aa3b, v16
	v_add_f32_e32 v134, v13, v135
	v_exp_f32_e32 v16, v16
	v_mul_f32_e32 v134, 0xbfb8aa3b, v134
	v_exp_f32_e32 v134, v134
	s_mov_b32 s24, 0x437f0000
	v_add_f32_e32 v16, 1.0, v16
	v_rcp_f32_e32 v166, v16
	v_add_f32_e32 v16, 1.0, v134
	v_add_f32_e32 v134, v14, v136
	v_mul_f32_e32 v134, 0xbfb8aa3b, v134
	v_exp_f32_e32 v154, v134
	v_add_f32_e32 v134, v15, v137
	v_mul_f32_e32 v134, 0xbfb8aa3b, v134
	v_exp_f32_e32 v155, v134
	ds_read_b128 v[134:137], v176 offset:16
	v_rcp_f32_e32 v168, v16
	v_add_f32_e32 v16, 1.0, v154
	v_rcp_f32_e32 v170, v16
	v_add_f32_e32 v16, 1.0, v155
	s_waitcnt lgkmcnt(0)
	v_add_f32_e32 v134, v8, v134
	v_mul_f32_e32 v134, 0xbfb8aa3b, v134
	v_exp_f32_e32 v154, v134
	v_add_f32_e32 v134, v9, v135
	v_mul_f32_e32 v134, 0xbfb8aa3b, v134
	v_exp_f32_e32 v135, v134
	v_rcp_f32_e32 v134, v16
	v_add_f32_e32 v16, 1.0, v154
	v_rcp_f32_e32 v167, v16
	v_add_f32_e32 v16, 1.0, v135
	v_add_f32_e32 v135, v10, v136
	v_mul_f32_e32 v135, 0xbfb8aa3b, v135
	v_add_f32_e32 v136, v11, v137
	v_exp_f32_e32 v135, v135
	v_mul_f32_e32 v136, 0xbfb8aa3b, v136
	v_exp_f32_e32 v136, v136
	v_rcp_f32_e32 v169, v16
	v_add_f32_e32 v16, 1.0, v135
	v_rcp_f32_e32 v171, v16
	v_add_f32_e32 v16, 1.0, v136
	v_pk_fma_f32 v[136:137], v[166:167], s[24:25], 0.5 op_sel_hi:[1,0,0]
	v_pk_fma_f32 v[166:167], v[168:169], s[24:25], 0.5 op_sel_hi:[1,0,0]
	v_rcp_f32_e32 v135, v16
	v_cvt_u32_f32_e32 v16, v167
	v_cvt_u32_f32_e32 v154, v166
	v_cvt_u32_f32_e32 v137, v137
	v_cvt_u32_f32_e32 v136, v136
	v_lshlrev_b32_e32 v16, 8, v16
	v_lshlrev_b32_e32 v154, 8, v154
	v_or_b32_e32 v16, v16, v137
	v_or_b32_e32 v154, v154, v136
	v_pk_fma_f32 v[136:137], v[170:171], s[24:25], 0.5 op_sel_hi:[1,0,0]
	v_pk_fma_f32 v[134:135], v[134:135], s[24:25], 0.5 op_sel_hi:[1,0,0]
	v_cvt_u32_f32_sdwa v136, v136 dst_sel:WORD_1 dst_unused:UNUSED_PAD src0_sel:DWORD
	v_cvt_u32_f32_sdwa v137, v137 dst_sel:WORD_1 dst_unused:UNUSED_PAD src0_sel:DWORD
	v_cvt_u32_f32_sdwa v134, v134 dst_sel:BYTE_3 dst_unused:UNUSED_PAD src0_sel:DWORD
	v_cvt_u32_f32_sdwa v135, v135 dst_sel:BYTE_3 dst_unused:UNUSED_PAD src0_sel:DWORD
	v_or_b32_e32 v136, v154, v136
	v_ashrrev_i32_e32 v165, 31, v164
	v_or_b32_e32 v16, v16, v137
	v_or_b32_e32 v134, v136, v134
	v_lshlrev_b64 v[136:137], 5, v[164:165]
	v_or_b32_e32 v135, v16, v135
	v_lshl_add_u64 v[136:137], v[162:163], 0, v[136:137]
	global_store_dwordx2 v[136:137], v[134:135], off

; DI float sigmoidf_(float x) { return __builtin_amdgcn_rcpf(1.f + __expf(-x)); }
;   template <int GRP>
;   DI void run(const f32x4 (&acc)[2][2][4][2], const pg8::Unit& u, int wr, int wc, int fr, int fq) const {
;     ...
;             if (act == 2) {
;               u32x2v g8;
; #pragma unroll
;               for (int n = 0; n < 2; ++n) {
;                 const f32x4 v = acc[ai][bj][m][n] + bp[n];
;                 unsigned q = 0u;
; #pragma unroll
;                 for (int j = 0; j < 4; ++j) q |= ((unsigned)(sigmoidf_(v[j]) * 255.f + 0.5f)) << (8 * j);
;                 if (n == 0) g8.x = q; else g8.y = q;
;               }
;               *reinterpret_cast<u32x2v*>(reinterpret_cast<unsigned char*>(ws + off) + (size_t)row * 1024 + c0 + 32 * wc + 8 * fq) = g8;
.LBB0_920:
	s_and_b64 vcc, exec, s[6:7]
	s_cbranch_vccz .LBB0_922
	s_waitcnt lgkmcnt(0)
	v_add_f32_e32 v16, v4, v134
	v_mul_f32_e32 v16, 0xbfb8aa3b, v16
	v_add_f32_e32 v134, v5, v135
	v_exp_f32_e32 v16, v16
	v_mul_f32_e32 v134, 0xbfb8aa3b, v134
	v_exp_f32_e32 v134, v134
	s_mov_b32 s4, 0x437f0000
	v_add_f32_e32 v16, 1.0, v16
	v_rcp_f32_e32 v150, v16
	v_add_f32_e32 v16, 1.0, v134
	v_add_f32_e32 v134, v6, v136
	v_mul_f32_e32 v134, 0xbfb8aa3b, v134
	v_exp_f32_e32 v151, v134
	v_add_f32_e32 v134, v7, v137
	v_mul_f32_e32 v134, 0xbfb8aa3b, v134
	v_exp_f32_e32 v154, v134
	ds_read_b128 v[134:137], v176 offset:16
	v_rcp_f32_e32 v166, v16
	v_add_f32_e32 v16, 1.0, v151
	v_rcp_f32_e32 v168, v16
	v_add_f32_e32 v16, 1.0, v154
	s_waitcnt lgkmcnt(0)
	v_add_f32_e32 v134, v0, v134
	v_mul_f32_e32 v134, 0xbfb8aa3b, v134
	v_exp_f32_e32 v151, v134
	v_add_f32_e32 v134, v1, v135
	v_mul_f32_e32 v134, 0xbfb8aa3b, v134
	v_exp_f32_e32 v135, v134
	v_rcp_f32_e32 v134, v16
	v_add_f32_e32 v16, 1.0, v151
	v_rcp_f32_e32 v151, v16
	v_add_f32_e32 v16, 1.0, v135
	v_add_f32_e32 v135, v2, v136
	v_mul_f32_e32 v135, 0xbfb8aa3b, v135
	v_add_f32_e32 v136, v3, v137
	v_exp_f32_e32 v135, v135
	v_mul_f32_e32 v136, 0xbfb8aa3b, v136
	v_exp_f32_e32 v136, v136
	v_rcp_f32_e32 v167, v16
	v_add_f32_e32 v16, 1.0, v135
	v_rcp_f32_e32 v169, v16
	v_add_f32_e32 v16, 1.0, v136
	v_pk_fma_f32 v[136:137], v[150:151], s[4:5], 0.5 op_sel_hi:[1,0,0]
	v_pk_fma_f32 v[150:151], v[166:167], s[4:5], 0.5 op_sel_hi:[1,0,0]
	v_rcp_f32_e32 v135, v16
	v_cvt_u32_f32_e32 v16, v151
	v_cvt_u32_f32_e32 v150, v150
	v_cvt_u32_f32_e32 v137, v137
	v_cvt_u32_f32_e32 v136, v136
	v_lshlrev_b32_e32 v16, 8, v16
	v_lshlrev_b32_e32 v150, 8, v150
	v_or_b32_e32 v16, v16, v137
	v_or_b32_e32 v150, v150, v136
	v_pk_fma_f32 v[136:137], v[168:169], s[4:5], 0.5 op_sel_hi:[1,0,0]
	v_pk_fma_f32 v[134:135], v[134:135], s[4:5], 0.5 op_sel_hi:[1,0,0]
	v_cvt_u32_f32_sdwa v136, v136 dst_sel:WORD_1 dst_unused:UNUSED_PAD src0_sel:DWORD
	v_cvt_u32_f32_sdwa v137, v137 dst_sel:WORD_1 dst_unused:UNUSED_PAD src0_sel:DWORD
	v_cvt_u32_f32_sdwa v134, v134 dst_sel:BYTE_3 dst_unused:UNUSED_PAD src0_sel:DWORD
	v_cvt_u32_f32_sdwa v135, v135 dst_sel:BYTE_3 dst_unused:UNUSED_PAD src0_sel:DWORD
	v_or_b32_e32 v136, v150, v136
	v_ashrrev_i32_e32 v165, 31, v164
	v_or_b32_e32 v16, v16, v137
	v_or_b32_e32 v134, v136, v134
	v_lshlrev_b64 v[136:137], 5, v[164:165]
	v_or_b32_e32 v135, v16, v135
	v_lshl_add_u64 v[136:137], v[162:163], 0, v[136:137]
	global_store_dwordx2 v[136:137], v[134:135], off

; DI float sigmoidf_(float x) { return __builtin_amdgcn_rcpf(1.f + __expf(-x)); }
;   template <int GRP>
;   DI void run(const f32x4 (&acc)[2][2][4][2], const pg8::Unit& u, int wr, int wc, int fr, int fq) const {
;     ...
;         if (nt < 4) { off = OFF_QAB; ld = 1024; c0 = nt * 128; act = 0; }
;         else if (nt < 16) { off = OFF_GA; ld = 512; c0 = (nt - 12) * 128; act = 1; }
;         else if (nt < 20) { off = OFF_QAB; ld = 1024; c0 = 512 + (nt - 16) * 128; act = 0; }
;         else if (nt < 25) { off = OFF_GB; ld = 512; c0 = (nt - 21) * 128; act = 1; }
;         else if (nt < 29) { off = OFF_QI; ld = 512; c0 = (nt - 25) * 128; act = 0; }
;         else if (nt < 38) { off = OFF_RA; ld = 1024; c0 = (nt - 30) * 128; act = 2; }
;         else { off = OFF_RB; ld = 1024; c0 = (nt - 38) * 128; act = 2; }
;         bf16_t* dst = reinterpret_cast<bf16_t*>(ws + off) + c0 + 32 * wc + 8 * fq;
; #pragma unroll
;         for (int ai = 0; ai < 2; ++ai)
; #pragma unroll
;           for (int m = 0; m < 4; ++m) {
;             int row = u.pm * 256 + 128 * ai + 64 * wr + 16 * m + fr;
;             asm volatile("" : "+v"(row));
;             if (act == 2) {
;               u32x2v g8;
; #pragma unroll
;               for (int n = 0; n < 2; ++n) {
;                 const f32x4 v = acc[ai][bj][m][n] + bp[n];
;                 unsigned q = 0u;
; #pragma unroll
;                 for (int j = 0; j < 4; ++j) q |= ((unsigned)(sigmoidf_(v[j]) * 255.f + 0.5f)) << (8 * j);
;                 if (n == 0) g8.x = q; else g8.y = q;
;               }
;               *reinterpret_cast<u32x2v*>(reinterpret_cast<unsigned char*>(ws + off) + (size_t)row * 1024 + c0 + 32 * wc + 8 * fq) = g8;
;               continue;
;             }
;             u32x4v pk;
; #pragma unroll
;             for (int n = 0; n < 2; ++n) {
;               f32x4 v = acc[ai][bj][m][n] + bp[n];
;               if (act != 0) {
; #pragma unroll
;                 for (int j = 0; j < 4; ++j) { const float sg = sigmoidf_(v[j]); v[j] = (act == 1) ? v[j] * sg : sg; }
.LBB0_1311:
	s_xor_b64 s[24:25], s[24:25], -1
	v_readlane_b32 s28, v249, 0
	v_readlane_b32 s29, v249, 1
	s_add_u32 s11, s28, s4
	s_addc_u32 s30, s29, s5
	s_ashr_i32 s23, s22, 31
	s_lshl_b64 s[4:5], s[22:23], 1
	s_add_u32 s4, s11, s4
	s_addc_u32 s5, s30, s5
	s_lshl_b32 s28, s42, 1
	s_add_u32 s28, s4, s28
	s_addc_u32 s29, s5, 0
	s_add_u32 s4, s11, s22
	s_addc_u32 s5, s30, s23
	s_add_i32 s4, s22, s42
	s_lshr_b32 s4, s4, 5
	s_mul_i32 s4, s4, 0x204000
	s_add_u32 s4, s11, s4
	s_addc_u32 s5, s30, 0
	s_lshl_b32 s11, s48, 8
	v_add_u32_e32 v164, s11, v21
	s_waitcnt lgkmcnt(0)
	ds_read_b128 v[134:137], v195
	s_mov_b64 s[26:27], -1
	v_lshl_add_u64 v[150:151], s[28:29], 0, v[16:17]
	s_and_b64 vcc, exec, s[2:3]
	s_cbranch_vccnz .LBB0_1317
	s_waitcnt lgkmcnt(0)
	v_pk_add_f32 v[162:163], v[132:133], v[136:137]
	v_pk_add_f32 v[166:167], v[130:131], v[134:135]
	s_and_b64 vcc, exec, s[24:25]
	s_cbranch_vccz .LBB0_1314
	v_mul_f32_e32 v154, 0xbfb8aa3b, v166
	v_exp_f32_e32 v154, v154
	v_mul_f32_e32 v156, 0xbfb8aa3b, v162
	v_mul_f32_e32 v155, 0xbfb8aa3b, v167
	v_exp_f32_e32 v155, v155
	v_add_f32_e32 v154, 1.0, v154
	v_rcp_f32_e32 v168, v154
	v_exp_f32_e32 v154, v156
	v_mul_f32_e32 v156, 0xbfb8aa3b, v163
	v_exp_f32_e32 v156, v156
	v_add_f32_e32 v155, 1.0, v155
	v_add_f32_e32 v154, 1.0, v154
	v_rcp_f32_e32 v170, v154
	v_add_f32_e32 v154, 1.0, v156
	v_rcp_f32_e32 v171, v154
	v_rcp_f32_e32 v169, v155
	v_pk_mul_f32 v[162:163], v[162:163], v[170:171]
	v_pk_mul_f32 v[166:167], v[166:167], v[168:169]

; DI float sigmoidf_(float x) { return __builtin_amdgcn_rcpf(1.f + __expf(-x)); }
;   template <int GRP>
;   DI void run(const f32x4 (&acc)[2][2][4][2], const pg8::Unit& u, int wr, int wc, int fr, int fq) const {
;     ...
;             if (act == 2) {
;               u32x2v g8;
; #pragma unroll
;               for (int n = 0; n < 2; ++n) {
;                 const f32x4 v = acc[ai][bj][m][n] + bp[n];
;                 unsigned q = 0u;
; #pragma unroll
;                 for (int j = 0; j < 4; ++j) q |= ((unsigned)(sigmoidf_(v[j]) * 255.f + 0.5f)) << (8 * j);
;                 if (n == 0) g8.x = q; else g8.y = q;
;               }
;               *reinterpret_cast<u32x2v*>(reinterpret_cast<unsigned char*>(ws + off) + (size_t)row * 1024 + c0 + 32 * wc + 8 * fq) = g8;
.LBB0_1317:
	v_lshl_add_u64 v[162:163], s[4:5], 0, v[144:145]
	s_and_b64 vcc, exec, s[26:27]
	s_cbranch_vccz .LBB0_1319
	s_waitcnt lgkmcnt(0)
	v_add_f32_e32 v130, v130, v134
	v_mul_f32_e32 v130, 0xbfb8aa3b, v130
	v_exp_f32_e32 v130, v130
	v_add_f32_e32 v131, v131, v135
	v_mul_f32_e32 v131, 0xbfb8aa3b, v131
	v_exp_f32_e32 v131, v131
	v_add_f32_e32 v130, 1.0, v130
	v_rcp_f32_e32 v134, v130
	v_add_f32_e32 v130, v132, v136
	v_mul_f32_e32 v130, 0xbfb8aa3b, v130
	v_exp_f32_e32 v154, v130
	v_add_f32_e32 v130, v133, v137
	v_mul_f32_e32 v130, 0xbfb8aa3b, v130
	v_add_f32_e32 v135, 1.0, v131
	v_exp_f32_e32 v137, v130
	ds_read_b128 v[130:133], v195 offset:16
	v_rcp_f32_e32 v136, v135
	v_add_f32_e32 v135, 1.0, v154
	v_rcp_f32_e32 v166, v135
	v_add_f32_e32 v135, 1.0, v137
	s_waitcnt lgkmcnt(0)
	v_add_f32_e32 v126, v126, v130
	v_mul_f32_e32 v126, 0xbfb8aa3b, v126
	v_exp_f32_e32 v130, v126
	v_add_f32_e32 v126, v127, v131
	v_mul_f32_e32 v126, 0xbfb8aa3b, v126
	v_exp_f32_e32 v127, v126
	v_add_f32_e32 v128, v128, v132
	v_mul_f32_e32 v128, 0xbfb8aa3b, v128
	v_add_f32_e32 v129, v129, v133
	v_add_f32_e32 v127, 1.0, v127
	v_add_f32_e32 v130, 1.0, v130
	v_exp_f32_e32 v128, v128
	v_mul_f32_e32 v129, 0xbfb8aa3b, v129
	v_rcp_f32_e32 v137, v127
	v_rcp_f32_e32 v126, v135
	v_rcp_f32_e32 v135, v130
	v_exp_f32_e32 v129, v129
	s_mov_b32 s4, 0x437f0000
	v_add_f32_e32 v127, 1.0, v128
	v_pk_fma_f32 v[130:131], v[136:137], s[4:5], 0.5 op_sel_hi:[1,0,0]
	v_rcp_f32_e32 v167, v127
	v_add_f32_e32 v127, 1.0, v129
	v_pk_fma_f32 v[128:129], v[134:135], s[4:5], 0.5 op_sel_hi:[1,0,0]
	v_cvt_u32_f32_e32 v131, v131
	v_cvt_u32_f32_e32 v130, v130
	v_cvt_u32_f32_e32 v129, v129
	v_cvt_u32_f32_e32 v128, v128
	v_rcp_f32_e32 v127, v127
	v_lshlrev_b32_e32 v131, 8, v131
	v_lshlrev_b32_e32 v130, 8, v130
	v_or_b32_e32 v131, v131, v129
	v_or_b32_e32 v130, v130, v128
	v_pk_fma_f32 v[128:129], v[166:167], s[4:5], 0.5 op_sel_hi:[1,0,0]
	v_pk_fma_f32 v[126:127], v[126:127], s[4:5], 0.5 op_sel_hi:[1,0,0]
	v_cvt_u32_f32_sdwa v128, v128 dst_sel:WORD_1 dst_unused:UNUSED_PAD src0_sel:DWORD
	v_cvt_u32_f32_sdwa v129, v129 dst_sel:WORD_1 dst_unused:UNUSED_PAD src0_sel:DWORD
	v_cvt_u32_f32_sdwa v127, v127 dst_sel:BYTE_3 dst_unused:UNUSED_PAD src0_sel:DWORD
	v_cvt_u32_f32_sdwa v126, v126 dst_sel:BYTE_3 dst_unused:UNUSED_PAD src0_sel:DWORD
	v_or_b32_e32 v128, v130, v128
	v_or_b32_e32 v129, v131, v129
	v_ashrrev_i32_e32 v165, 31, v164
	v_or_b32_e32 v127, v129, v127
	v_or_b32_e32 v126, v128, v126
	v_lshlrev_b64 v[128:129], 5, v[164:165]
	v_lshl_add_u64 v[128:129], v[162:163], 0, v[128:129]
	global_store_dwordx2 v[128:129], v[126:127], off

; DI float sigmoidf_(float x) { return __builtin_amdgcn_rcpf(1.f + __expf(-x)); }
;   template <int GRP>
;   DI void run(const f32x4 (&acc)[2][2][4][2], const pg8::Unit& u, int wr, int wc, int fr, int fq) const {
;     ...
;             if (act == 2) {
;               u32x2v g8;
; #pragma unroll
;               for (int n = 0; n < 2; ++n) {
;                 const f32x4 v = acc[ai][bj][m][n] + bp[n];
;                 unsigned q = 0u;
; #pragma unroll
;                 for (int j = 0; j < 4; ++j) q |= ((unsigned)(sigmoidf_(v[j]) * 255.f + 0.5f)) << (8 * j);
;                 if (n == 0) g8.x = q; else g8.y = q;
;               }
;               *reinterpret_cast<u32x2v*>(reinterpret_cast<unsigned char*>(ws + off) + (size_t)row * 1024 + c0 + 32 * wc + 8 * fq) = g8;
.LBB0_1325:
	s_and_b64 vcc, exec, s[22:23]
	s_cbranch_vccz .LBB0_1327
	s_waitcnt lgkmcnt(0)
	v_add_f32_e32 v122, v122, v126
	v_mul_f32_e32 v122, 0xbfb8aa3b, v122
	v_exp_f32_e32 v122, v122
	v_add_f32_e32 v123, v123, v127
	v_mul_f32_e32 v123, 0xbfb8aa3b, v123
	v_exp_f32_e32 v123, v123
	v_add_f32_e32 v122, 1.0, v122
	v_rcp_f32_e32 v126, v122
	v_add_f32_e32 v122, v124, v128
	v_mul_f32_e32 v122, 0xbfb8aa3b, v122
	v_exp_f32_e32 v131, v122
	v_add_f32_e32 v122, v125, v129
	v_mul_f32_e32 v122, 0xbfb8aa3b, v122
	v_add_f32_e32 v127, 1.0, v123
	v_exp_f32_e32 v129, v122
	ds_read_b128 v[122:125], v195 offset:16
	v_rcp_f32_e32 v128, v127
	v_add_f32_e32 v127, 1.0, v131
	v_rcp_f32_e32 v132, v127
	v_add_f32_e32 v127, 1.0, v129
	s_waitcnt lgkmcnt(0)
	v_add_f32_e32 v118, v118, v122
	v_mul_f32_e32 v118, 0xbfb8aa3b, v118
	v_exp_f32_e32 v122, v118
	v_add_f32_e32 v118, v119, v123
	v_mul_f32_e32 v118, 0xbfb8aa3b, v118
	v_exp_f32_e32 v119, v118
	v_add_f32_e32 v120, v120, v124
	v_mul_f32_e32 v120, 0xbfb8aa3b, v120
	v_add_f32_e32 v121, v121, v125
	v_add_f32_e32 v119, 1.0, v119
	v_add_f32_e32 v122, 1.0, v122
	v_exp_f32_e32 v120, v120
	v_mul_f32_e32 v121, 0xbfb8aa3b, v121
	v_rcp_f32_e32 v129, v119
	v_rcp_f32_e32 v118, v127
	v_rcp_f32_e32 v127, v122
	v_exp_f32_e32 v121, v121
	s_mov_b32 s22, 0x437f0000
	v_add_f32_e32 v119, 1.0, v120
	v_pk_fma_f32 v[122:123], v[128:129], s[22:23], 0.5 op_sel_hi:[1,0,0]
	v_rcp_f32_e32 v133, v119
	v_add_f32_e32 v119, 1.0, v121
	v_pk_fma_f32 v[120:121], v[126:127], s[22:23], 0.5 op_sel_hi:[1,0,0]
	v_cvt_u32_f32_e32 v123, v123
	v_cvt_u32_f32_e32 v122, v122
	v_cvt_u32_f32_e32 v121, v121
	v_cvt_u32_f32_e32 v120, v120
	v_rcp_f32_e32 v119, v119
	v_lshlrev_b32_e32 v123, 8, v123
	v_lshlrev_b32_e32 v122, 8, v122
	v_or_b32_e32 v123, v123, v121
	v_or_b32_e32 v122, v122, v120
	v_pk_fma_f32 v[120:121], v[132:133], s[22:23], 0.5 op_sel_hi:[1,0,0]
	v_pk_fma_f32 v[118:119], v[118:119], s[22:23], 0.5 op_sel_hi:[1,0,0]
	v_cvt_u32_f32_sdwa v120, v120 dst_sel:WORD_1 dst_unused:UNUSED_PAD src0_sel:DWORD
	v_cvt_u32_f32_sdwa v121, v121 dst_sel:WORD_1 dst_unused:UNUSED_PAD src0_sel:DWORD
	v_cvt_u32_f32_sdwa v119, v119 dst_sel:BYTE_3 dst_unused:UNUSED_PAD src0_sel:DWORD
	v_cvt_u32_f32_sdwa v118, v118 dst_sel:BYTE_3 dst_unused:UNUSED_PAD src0_sel:DWORD
	v_or_b32_e32 v120, v122, v120
	v_or_b32_e32 v121, v123, v121
	v_ashrrev_i32_e32 v131, 31, v130
	v_or_b32_e32 v119, v121, v119
	v_or_b32_e32 v118, v120, v118
	v_lshlrev_b64 v[120:121], 5, v[130:131]
	v_lshl_add_u64 v[120:121], v[162:163], 0, v[120:121]
	global_store_dwordx2 v[120:121], v[118:119], off

; DI float sigmoidf_(float x) { return __builtin_amdgcn_rcpf(1.f + __expf(-x)); }
;   template <int GRP>
;   DI void run(const f32x4 (&acc)[2][2][4][2], const pg8::Unit& u, int wr, int wc, int fr, int fq) const {
;     ...
;             if (act == 2) {
;               u32x2v g8;
; #pragma unroll
;               for (int n = 0; n < 2; ++n) {
;                 const f32x4 v = acc[ai][bj][m][n] + bp[n];
;                 unsigned q = 0u;
; #pragma unroll
;                 for (int j = 0; j < 4; ++j) q |= ((unsigned)(sigmoidf_(v[j]) * 255.f + 0.5f)) << (8 * j);
;                 if (n == 0) g8.x = q; else g8.y = q;
;               }
;               *reinterpret_cast<u32x2v*>(reinterpret_cast<unsigned char*>(ws + off) + (size_t)row * 1024 + c0 + 32 * wc + 8 * fq) = g8;
.LBB0_1333:
	s_and_b64 vcc, exec, s[22:23]
	s_cbranch_vccz .LBB0_1335
	s_waitcnt lgkmcnt(0)
	v_add_f32_e32 v114, v114, v118
	v_mul_f32_e32 v114, 0xbfb8aa3b, v114
	v_exp_f32_e32 v114, v114
	v_add_f32_e32 v115, v115, v119
	v_mul_f32_e32 v115, 0xbfb8aa3b, v115
	v_exp_f32_e32 v115, v115
	v_add_f32_e32 v114, 1.0, v114
	v_rcp_f32_e32 v118, v114
	v_add_f32_e32 v114, v116, v120
	v_mul_f32_e32 v114, 0xbfb8aa3b, v114
	v_exp_f32_e32 v123, v114
	v_add_f32_e32 v114, v117, v121
	v_mul_f32_e32 v114, 0xbfb8aa3b, v114
	v_add_f32_e32 v119, 1.0, v115
	v_exp_f32_e32 v121, v114
	ds_read_b128 v[114:117], v195 offset:16
	v_rcp_f32_e32 v120, v119
	v_add_f32_e32 v119, 1.0, v123
	v_rcp_f32_e32 v124, v119
	v_add_f32_e32 v119, 1.0, v121
	s_waitcnt lgkmcnt(0)
	v_add_f32_e32 v110, v110, v114
	v_mul_f32_e32 v110, 0xbfb8aa3b, v110
	v_exp_f32_e32 v114, v110
	v_add_f32_e32 v110, v111, v115
	v_mul_f32_e32 v110, 0xbfb8aa3b, v110
	v_exp_f32_e32 v111, v110
	v_add_f32_e32 v112, v112, v116
	v_mul_f32_e32 v112, 0xbfb8aa3b, v112
	v_add_f32_e32 v113, v113, v117
	v_add_f32_e32 v111, 1.0, v111
	v_add_f32_e32 v114, 1.0, v114
	v_exp_f32_e32 v112, v112
	v_mul_f32_e32 v113, 0xbfb8aa3b, v113
	v_rcp_f32_e32 v121, v111
	v_rcp_f32_e32 v110, v119
	v_rcp_f32_e32 v119, v114
	v_exp_f32_e32 v113, v113
	s_mov_b32 s22, 0x437f0000
	v_add_f32_e32 v111, 1.0, v112
	v_pk_fma_f32 v[114:115], v[120:121], s[22:23], 0.5 op_sel_hi:[1,0,0]
	v_rcp_f32_e32 v125, v111
	v_add_f32_e32 v111, 1.0, v113
	v_pk_fma_f32 v[112:113], v[118:119], s[22:23], 0.5 op_sel_hi:[1,0,0]
	v_cvt_u32_f32_e32 v115, v115
	v_cvt_u32_f32_e32 v114, v114
	v_cvt_u32_f32_e32 v113, v113
	v_cvt_u32_f32_e32 v112, v112
	v_rcp_f32_e32 v111, v111
	v_lshlrev_b32_e32 v115, 8, v115
	v_lshlrev_b32_e32 v114, 8, v114
	v_or_b32_e32 v115, v115, v113
	v_or_b32_e32 v114, v114, v112
	v_pk_fma_f32 v[112:113], v[124:125], s[22:23], 0.5 op_sel_hi:[1,0,0]
	v_pk_fma_f32 v[110:111], v[110:111], s[22:23], 0.5 op_sel_hi:[1,0,0]
	v_cvt_u32_f32_sdwa v112, v112 dst_sel:WORD_1 dst_unused:UNUSED_PAD src0_sel:DWORD
	v_cvt_u32_f32_sdwa v113, v113 dst_sel:WORD_1 dst_unused:UNUSED_PAD src0_sel:DWORD
	v_cvt_u32_f32_sdwa v111, v111 dst_sel:BYTE_3 dst_unused:UNUSED_PAD src0_sel:DWORD
	v_cvt_u32_f32_sdwa v110, v110 dst_sel:BYTE_3 dst_unused:UNUSED_PAD src0_sel:DWORD
	v_or_b32_e32 v112, v114, v112
	v_or_b32_e32 v113, v115, v113
	v_ashrrev_i32_e32 v123, 31, v122
	v_or_b32_e32 v111, v113, v111
	v_or_b32_e32 v110, v112, v110
	v_lshlrev_b64 v[112:113], 5, v[122:123]
	v_lshl_add_u64 v[112:113], v[162:163], 0, v[112:113]
	global_store_dwordx2 v[112:113], v[110:111], off

; DI float sigmoidf_(float x) { return __builtin_amdgcn_rcpf(1.f + __expf(-x)); }
;   template <int GRP>
;   DI void run(const f32x4 (&acc)[2][2][4][2], const pg8::Unit& u, int wr, int wc, int fr, int fq) const {
;     ...
;             if (act == 2) {
;               u32x2v g8;
; #pragma unroll
;               for (int n = 0; n < 2; ++n) {
;                 const f32x4 v = acc[ai][bj][m][n] + bp[n];
;                 unsigned q = 0u;
; #pragma unroll
;                 for (int j = 0; j < 4; ++j) q |= ((unsigned)(sigmoidf_(v[j]) * 255.f + 0.5f)) << (8 * j);
;                 if (n == 0) g8.x = q; else g8.y = q;
;               }
;               *reinterpret_cast<u32x2v*>(reinterpret_cast<unsigned char*>(ws + off) + (size_t)row * 1024 + c0 + 32 * wc + 8 * fq) = g8;
.LBB0_1341:
	s_and_b64 vcc, exec, s[22:23]
	s_cbranch_vccz .LBB0_1343
	s_waitcnt lgkmcnt(0)
	v_add_f32_e32 v106, v106, v110
	v_mul_f32_e32 v106, 0xbfb8aa3b, v106
	v_exp_f32_e32 v106, v106
	v_add_f32_e32 v107, v107, v111
	v_mul_f32_e32 v107, 0xbfb8aa3b, v107
	v_exp_f32_e32 v107, v107
	v_add_f32_e32 v106, 1.0, v106
	v_rcp_f32_e32 v110, v106
	v_add_f32_e32 v106, v108, v112
	v_mul_f32_e32 v106, 0xbfb8aa3b, v106
	v_exp_f32_e32 v115, v106
	v_add_f32_e32 v106, v109, v113
	v_mul_f32_e32 v106, 0xbfb8aa3b, v106
	v_add_f32_e32 v111, 1.0, v107
	v_exp_f32_e32 v113, v106
	ds_read_b128 v[106:109], v195 offset:16
	v_rcp_f32_e32 v112, v111
	v_add_f32_e32 v111, 1.0, v115
	v_rcp_f32_e32 v116, v111
	v_add_f32_e32 v111, 1.0, v113
	s_waitcnt lgkmcnt(0)
	v_add_f32_e32 v102, v102, v106
	v_mul_f32_e32 v102, 0xbfb8aa3b, v102
	v_exp_f32_e32 v106, v102
	v_add_f32_e32 v102, v103, v107
	v_mul_f32_e32 v102, 0xbfb8aa3b, v102
	v_exp_f32_e32 v103, v102
	v_add_f32_e32 v104, v104, v108
	v_mul_f32_e32 v104, 0xbfb8aa3b, v104
	v_add_f32_e32 v105, v105, v109
	v_add_f32_e32 v103, 1.0, v103
	v_add_f32_e32 v106, 1.0, v106
	v_exp_f32_e32 v104, v104
	v_mul_f32_e32 v105, 0xbfb8aa3b, v105
	v_rcp_f32_e32 v113, v103
	v_rcp_f32_e32 v102, v111
	v_rcp_f32_e32 v111, v106
	v_exp_f32_e32 v105, v105
	s_mov_b32 s22, 0x437f0000
	v_add_f32_e32 v103, 1.0, v104
	v_pk_fma_f32 v[106:107], v[112:113], s[22:23], 0.5 op_sel_hi:[1,0,0]
	v_rcp_f32_e32 v117, v103
	v_add_f32_e32 v103, 1.0, v105
	v_pk_fma_f32 v[104:105], v[110:111], s[22:23], 0.5 op_sel_hi:[1,0,0]
	v_cvt_u32_f32_e32 v107, v107
	v_cvt_u32_f32_e32 v106, v106
	v_cvt_u32_f32_e32 v105, v105
	v_cvt_u32_f32_e32 v104, v104
	v_rcp_f32_e32 v103, v103
	v_lshlrev_b32_e32 v107, 8, v107
	v_lshlrev_b32_e32 v106, 8, v106
	v_or_b32_e32 v107, v107, v105
	v_or_b32_e32 v106, v106, v104
	v_pk_fma_f32 v[104:105], v[116:117], s[22:23], 0.5 op_sel_hi:[1,0,0]
	v_pk_fma_f32 v[102:103], v[102:103], s[22:23], 0.5 op_sel_hi:[1,0,0]
	v_cvt_u32_f32_sdwa v104, v104 dst_sel:WORD_1 dst_unused:UNUSED_PAD src0_sel:DWORD
	v_cvt_u32_f32_sdwa v105, v105 dst_sel:WORD_1 dst_unused:UNUSED_PAD src0_sel:DWORD
	v_cvt_u32_f32_sdwa v103, v103 dst_sel:BYTE_3 dst_unused:UNUSED_PAD src0_sel:DWORD
	v_cvt_u32_f32_sdwa v102, v102 dst_sel:BYTE_3 dst_unused:UNUSED_PAD src0_sel:DWORD
	v_or_b32_e32 v104, v106, v104
	v_or_b32_e32 v105, v107, v105
	v_ashrrev_i32_e32 v115, 31, v114
	v_or_b32_e32 v103, v105, v103
	v_or_b32_e32 v102, v104, v102
	v_lshlrev_b64 v[104:105], 5, v[114:115]
	v_lshl_add_u64 v[104:105], v[162:163], 0, v[104:105]
	global_store_dwordx2 v[104:105], v[102:103], off

; DI float sigmoidf_(float x) { return __builtin_amdgcn_rcpf(1.f + __expf(-x)); }
;   template <int GRP>
;   DI void run(const f32x4 (&acc)[2][2][4][2], const pg8::Unit& u, int wr, int wc, int fr, int fq) const {
;     ...
;             if (act == 2) {
;               u32x2v g8;
; #pragma unroll
;               for (int n = 0; n < 2; ++n) {
;                 const f32x4 v = acc[ai][bj][m][n] + bp[n];
;                 unsigned q = 0u;
; #pragma unroll
;                 for (int j = 0; j < 4; ++j) q |= ((unsigned)(sigmoidf_(v[j]) * 255.f + 0.5f)) << (8 * j);
;                 if (n == 0) g8.x = q; else g8.y = q;
;               }
;               *reinterpret_cast<u32x2v*>(reinterpret_cast<unsigned char*>(ws + off) + (size_t)row * 1024 + c0 + 32 * wc + 8 * fq) = g8;
.LBB0_1349:
	s_and_b64 vcc, exec, s[22:23]
	s_cbranch_vccz .LBB0_1351
	s_waitcnt lgkmcnt(0)
	v_add_f32_e32 v98, v98, v102
	v_mul_f32_e32 v98, 0xbfb8aa3b, v98
	v_exp_f32_e32 v98, v98
	v_add_f32_e32 v99, v99, v103
	v_mul_f32_e32 v99, 0xbfb8aa3b, v99
	v_exp_f32_e32 v99, v99
	v_add_f32_e32 v98, 1.0, v98
	v_rcp_f32_e32 v102, v98
	v_add_f32_e32 v98, v100, v104
	v_mul_f32_e32 v98, 0xbfb8aa3b, v98
	v_exp_f32_e32 v107, v98
	v_add_f32_e32 v98, v101, v105
	v_mul_f32_e32 v98, 0xbfb8aa3b, v98
	v_add_f32_e32 v103, 1.0, v99
	v_exp_f32_e32 v105, v98
	ds_read_b128 v[98:101], v195 offset:16
	v_rcp_f32_e32 v104, v103
	v_add_f32_e32 v103, 1.0, v107
	v_rcp_f32_e32 v108, v103
	v_add_f32_e32 v103, 1.0, v105
	s_waitcnt lgkmcnt(0)
	v_add_f32_e32 v94, v94, v98
	v_mul_f32_e32 v94, 0xbfb8aa3b, v94
	v_exp_f32_e32 v98, v94
	v_add_f32_e32 v94, v95, v99
	v_mul_f32_e32 v94, 0xbfb8aa3b, v94
	v_exp_f32_e32 v95, v94
	v_add_f32_e32 v96, v96, v100
	v_mul_f32_e32 v96, 0xbfb8aa3b, v96
	v_add_f32_e32 v97, v97, v101
	v_add_f32_e32 v95, 1.0, v95
	v_add_f32_e32 v98, 1.0, v98
	v_exp_f32_e32 v96, v96
	v_mul_f32_e32 v97, 0xbfb8aa3b, v97
	v_rcp_f32_e32 v105, v95
	v_rcp_f32_e32 v94, v103
	v_rcp_f32_e32 v103, v98
	v_exp_f32_e32 v97, v97
	s_mov_b32 s22, 0x437f0000
	v_add_f32_e32 v95, 1.0, v96
	v_pk_fma_f32 v[98:99], v[104:105], s[22:23], 0.5 op_sel_hi:[1,0,0]
	v_rcp_f32_e32 v109, v95
	v_add_f32_e32 v95, 1.0, v97
	v_pk_fma_f32 v[96:97], v[102:103], s[22:23], 0.5 op_sel_hi:[1,0,0]
	v_cvt_u32_f32_e32 v99, v99
	v_cvt_u32_f32_e32 v98, v98
	v_cvt_u32_f32_e32 v97, v97
	v_cvt_u32_f32_e32 v96, v96
	v_rcp_f32_e32 v95, v95
	v_lshlrev_b32_e32 v99, 8, v99
	v_lshlrev_b32_e32 v98, 8, v98
	v_or_b32_e32 v99, v99, v97
	v_or_b32_e32 v98, v98, v96
	v_pk_fma_f32 v[96:97], v[108:109], s[22:23], 0.5 op_sel_hi:[1,0,0]
	v_pk_fma_f32 v[94:95], v[94:95], s[22:23], 0.5 op_sel_hi:[1,0,0]
	v_cvt_u32_f32_sdwa v96, v96 dst_sel:WORD_1 dst_unused:UNUSED_PAD src0_sel:DWORD
	v_cvt_u32_f32_sdwa v97, v97 dst_sel:WORD_1 dst_unused:UNUSED_PAD src0_sel:DWORD
	v_cvt_u32_f32_sdwa v95, v95 dst_sel:BYTE_3 dst_unused:UNUSED_PAD src0_sel:DWORD
	v_cvt_u32_f32_sdwa v94, v94 dst_sel:BYTE_3 dst_unused:UNUSED_PAD src0_sel:DWORD
	v_or_b32_e32 v96, v98, v96
	v_or_b32_e32 v97, v99, v97
	v_ashrrev_i32_e32 v107, 31, v106
	v_or_b32_e32 v95, v97, v95
	v_or_b32_e32 v94, v96, v94
	v_lshlrev_b64 v[96:97], 5, v[106:107]
	v_lshl_add_u64 v[96:97], v[162:163], 0, v[96:97]
	global_store_dwordx2 v[96:97], v[94:95], off

; DI float sigmoidf_(float x) { return __builtin_amdgcn_rcpf(1.f + __expf(-x)); }
;   template <int GRP>
;   DI void run(const f32x4 (&acc)[2][2][4][2], const pg8::Unit& u, int wr, int wc, int fr, int fq) const {
;     ...
;             if (act == 2) {
;               u32x2v g8;
; #pragma unroll
;               for (int n = 0; n < 2; ++n) {
;                 const f32x4 v = acc[ai][bj][m][n] + bp[n];
;                 unsigned q = 0u;
; #pragma unroll
;                 for (int j = 0; j < 4; ++j) q |= ((unsigned)(sigmoidf_(v[j]) * 255.f + 0.5f)) << (8 * j);
;                 if (n == 0) g8.x = q; else g8.y = q;
;               }
;               *reinterpret_cast<u32x2v*>(reinterpret_cast<unsigned char*>(ws + off) + (size_t)row * 1024 + c0 + 32 * wc + 8 * fq) = g8;
.LBB0_1357:
	s_and_b64 vcc, exec, s[22:23]
	s_cbranch_vccz .LBB0_1359
	s_waitcnt lgkmcnt(0)
	v_add_f32_e32 v90, v90, v94
	v_mul_f32_e32 v90, 0xbfb8aa3b, v90
	v_exp_f32_e32 v90, v90
	v_add_f32_e32 v91, v91, v95
	v_mul_f32_e32 v91, 0xbfb8aa3b, v91
	v_exp_f32_e32 v91, v91
	v_add_f32_e32 v90, 1.0, v90
	v_rcp_f32_e32 v94, v90
	v_add_f32_e32 v90, v92, v96
	v_mul_f32_e32 v90, 0xbfb8aa3b, v90
	v_exp_f32_e32 v99, v90
	v_add_f32_e32 v90, v93, v97
	v_mul_f32_e32 v90, 0xbfb8aa3b, v90
	v_add_f32_e32 v95, 1.0, v91
	v_exp_f32_e32 v97, v90
	ds_read_b128 v[90:93], v195 offset:16
	v_rcp_f32_e32 v96, v95
	v_add_f32_e32 v95, 1.0, v99
	v_rcp_f32_e32 v100, v95
	v_add_f32_e32 v95, 1.0, v97
	s_waitcnt lgkmcnt(0)
	v_add_f32_e32 v86, v86, v90
	v_mul_f32_e32 v86, 0xbfb8aa3b, v86
	v_exp_f32_e32 v90, v86
	v_add_f32_e32 v86, v87, v91
	v_mul_f32_e32 v86, 0xbfb8aa3b, v86
	v_exp_f32_e32 v87, v86
	v_add_f32_e32 v88, v88, v92
	v_mul_f32_e32 v88, 0xbfb8aa3b, v88
	v_add_f32_e32 v89, v89, v93
	v_add_f32_e32 v87, 1.0, v87
	v_add_f32_e32 v90, 1.0, v90
	v_exp_f32_e32 v88, v88
	v_mul_f32_e32 v89, 0xbfb8aa3b, v89
	v_rcp_f32_e32 v97, v87
	v_rcp_f32_e32 v86, v95
	v_rcp_f32_e32 v95, v90
	v_exp_f32_e32 v89, v89
	s_mov_b32 s22, 0x437f0000
	v_add_f32_e32 v87, 1.0, v88
	v_pk_fma_f32 v[90:91], v[96:97], s[22:23], 0.5 op_sel_hi:[1,0,0]
	v_rcp_f32_e32 v101, v87
	v_add_f32_e32 v87, 1.0, v89
	v_pk_fma_f32 v[88:89], v[94:95], s[22:23], 0.5 op_sel_hi:[1,0,0]
	v_cvt_u32_f32_e32 v91, v91
	v_cvt_u32_f32_e32 v90, v90
	v_cvt_u32_f32_e32 v89, v89
	v_cvt_u32_f32_e32 v88, v88
	v_rcp_f32_e32 v87, v87
	v_lshlrev_b32_e32 v91, 8, v91
	v_lshlrev_b32_e32 v90, 8, v90
	v_or_b32_e32 v91, v91, v89
	v_or_b32_e32 v90, v90, v88
	v_pk_fma_f32 v[88:89], v[100:101], s[22:23], 0.5 op_sel_hi:[1,0,0]
	v_pk_fma_f32 v[86:87], v[86:87], s[22:23], 0.5 op_sel_hi:[1,0,0]
	v_cvt_u32_f32_sdwa v88, v88 dst_sel:WORD_1 dst_unused:UNUSED_PAD src0_sel:DWORD
	v_cvt_u32_f32_sdwa v89, v89 dst_sel:WORD_1 dst_unused:UNUSED_PAD src0_sel:DWORD
	v_cvt_u32_f32_sdwa v87, v87 dst_sel:BYTE_3 dst_unused:UNUSED_PAD src0_sel:DWORD
	v_cvt_u32_f32_sdwa v86, v86 dst_sel:BYTE_3 dst_unused:UNUSED_PAD src0_sel:DWORD
	v_or_b32_e32 v88, v90, v88
	v_or_b32_e32 v89, v91, v89
	v_ashrrev_i32_e32 v99, 31, v98
	v_or_b32_e32 v87, v89, v87
	v_or_b32_e32 v86, v88, v86
	v_lshlrev_b64 v[88:89], 5, v[98:99]
	v_lshl_add_u64 v[88:89], v[162:163], 0, v[88:89]
	global_store_dwordx2 v[88:89], v[86:87], off

; DI float sigmoidf_(float x) { return __builtin_amdgcn_rcpf(1.f + __expf(-x)); }
;   template <int GRP>
;   DI void run(const f32x4 (&acc)[2][2][4][2], const pg8::Unit& u, int wr, int wc, int fr, int fq) const {
;     ...
;             if (act == 2) {
;               u32x2v g8;
; #pragma unroll
;               for (int n = 0; n < 2; ++n) {
;                 const f32x4 v = acc[ai][bj][m][n] + bp[n];
;                 unsigned q = 0u;
; #pragma unroll
;                 for (int j = 0; j < 4; ++j) q |= ((unsigned)(sigmoidf_(v[j]) * 255.f + 0.5f)) << (8 * j);
;                 if (n == 0) g8.x = q; else g8.y = q;
;               }
;               *reinterpret_cast<u32x2v*>(reinterpret_cast<unsigned char*>(ws + off) + (size_t)row * 1024 + c0 + 32 * wc + 8 * fq) = g8;
.LBB0_1365:
	s_and_b64 vcc, exec, s[22:23]
	s_cbranch_vccz .LBB0_1367
	s_waitcnt lgkmcnt(0)
	v_add_f32_e32 v82, v82, v86
	v_mul_f32_e32 v82, 0xbfb8aa3b, v82
	v_exp_f32_e32 v82, v82
	v_add_f32_e32 v83, v83, v87
	v_mul_f32_e32 v83, 0xbfb8aa3b, v83
	v_exp_f32_e32 v83, v83
	v_add_f32_e32 v82, 1.0, v82
	v_rcp_f32_e32 v86, v82
	v_add_f32_e32 v82, v84, v88
	v_mul_f32_e32 v82, 0xbfb8aa3b, v82
	v_exp_f32_e32 v91, v82
	v_add_f32_e32 v82, v85, v89
	v_mul_f32_e32 v82, 0xbfb8aa3b, v82
	v_add_f32_e32 v87, 1.0, v83
	v_exp_f32_e32 v89, v82
	ds_read_b128 v[82:85], v195 offset:16
	v_rcp_f32_e32 v88, v87
	v_add_f32_e32 v87, 1.0, v91
	v_rcp_f32_e32 v92, v87
	v_add_f32_e32 v87, 1.0, v89
	s_waitcnt lgkmcnt(0)
	v_add_f32_e32 v78, v78, v82
	v_mul_f32_e32 v78, 0xbfb8aa3b, v78
	v_exp_f32_e32 v82, v78
	v_add_f32_e32 v78, v79, v83
	v_mul_f32_e32 v78, 0xbfb8aa3b, v78
	v_exp_f32_e32 v79, v78
	v_add_f32_e32 v80, v80, v84
	v_mul_f32_e32 v80, 0xbfb8aa3b, v80
	v_add_f32_e32 v81, v81, v85
	v_add_f32_e32 v79, 1.0, v79
	v_add_f32_e32 v82, 1.0, v82
	v_exp_f32_e32 v80, v80
	v_mul_f32_e32 v81, 0xbfb8aa3b, v81
	v_rcp_f32_e32 v89, v79
	v_rcp_f32_e32 v78, v87
	v_rcp_f32_e32 v87, v82
	v_exp_f32_e32 v81, v81
	s_mov_b32 s22, 0x437f0000
	v_add_f32_e32 v79, 1.0, v80
	v_pk_fma_f32 v[82:83], v[88:89], s[22:23], 0.5 op_sel_hi:[1,0,0]
	v_rcp_f32_e32 v93, v79
	v_add_f32_e32 v79, 1.0, v81
	v_pk_fma_f32 v[80:81], v[86:87], s[22:23], 0.5 op_sel_hi:[1,0,0]
	v_cvt_u32_f32_e32 v83, v83
	v_cvt_u32_f32_e32 v82, v82
	v_cvt_u32_f32_e32 v81, v81
	v_cvt_u32_f32_e32 v80, v80
	v_rcp_f32_e32 v79, v79
	v_lshlrev_b32_e32 v83, 8, v83
	v_lshlrev_b32_e32 v82, 8, v82
	v_or_b32_e32 v83, v83, v81
	v_or_b32_e32 v82, v82, v80
	v_pk_fma_f32 v[80:81], v[92:93], s[22:23], 0.5 op_sel_hi:[1,0,0]
	v_pk_fma_f32 v[78:79], v[78:79], s[22:23], 0.5 op_sel_hi:[1,0,0]
	v_cvt_u32_f32_sdwa v80, v80 dst_sel:WORD_1 dst_unused:UNUSED_PAD src0_sel:DWORD
	v_cvt_u32_f32_sdwa v81, v81 dst_sel:WORD_1 dst_unused:UNUSED_PAD src0_sel:DWORD
	v_cvt_u32_f32_sdwa v79, v79 dst_sel:BYTE_3 dst_unused:UNUSED_PAD src0_sel:DWORD
	v_cvt_u32_f32_sdwa v78, v78 dst_sel:BYTE_3 dst_unused:UNUSED_PAD src0_sel:DWORD
	v_or_b32_e32 v80, v82, v80
	v_or_b32_e32 v81, v83, v81
	v_ashrrev_i32_e32 v91, 31, v90
	v_or_b32_e32 v79, v81, v79
	v_or_b32_e32 v78, v80, v78
	v_lshlrev_b64 v[80:81], 5, v[90:91]
	v_lshl_add_u64 v[80:81], v[162:163], 0, v[80:81]
	global_store_dwordx2 v[80:81], v[78:79], off

; DI float sigmoidf_(float x) { return __builtin_amdgcn_rcpf(1.f + __expf(-x)); }
;   template <int GRP>
;   DI void run(const f32x4 (&acc)[2][2][4][2], const pg8::Unit& u, int wr, int wc, int fr, int fq) const {
;     ...
;             if (act == 2) {
;               u32x2v g8;
; #pragma unroll
;               for (int n = 0; n < 2; ++n) {
;                 const f32x4 v = acc[ai][bj][m][n] + bp[n];
;                 unsigned q = 0u;
; #pragma unroll
;                 for (int j = 0; j < 4; ++j) q |= ((unsigned)(sigmoidf_(v[j]) * 255.f + 0.5f)) << (8 * j);
;                 if (n == 0) g8.x = q; else g8.y = q;
;               }
;               *reinterpret_cast<u32x2v*>(reinterpret_cast<unsigned char*>(ws + off) + (size_t)row * 1024 + c0 + 32 * wc + 8 * fq) = g8;
.LBB0_1373:
	s_and_b64 vcc, exec, s[4:5]
	s_cbranch_vccz .LBB0_1375
	s_waitcnt lgkmcnt(0)
	v_add_f32_e32 v74, v74, v78
	v_mul_f32_e32 v74, 0xbfb8aa3b, v74
	v_exp_f32_e32 v74, v74
	v_add_f32_e32 v75, v75, v79
	v_mul_f32_e32 v75, 0xbfb8aa3b, v75
	v_exp_f32_e32 v75, v75
	v_add_f32_e32 v74, 1.0, v74
	v_rcp_f32_e32 v78, v74
	v_add_f32_e32 v74, v76, v80
	v_mul_f32_e32 v74, 0xbfb8aa3b, v74
	v_exp_f32_e32 v83, v74
	v_add_f32_e32 v74, v77, v81
	v_mul_f32_e32 v74, 0xbfb8aa3b, v74
	v_add_f32_e32 v79, 1.0, v75
	v_exp_f32_e32 v81, v74
	ds_read_b128 v[74:77], v195 offset:16
	v_rcp_f32_e32 v80, v79
	v_add_f32_e32 v79, 1.0, v83
	v_rcp_f32_e32 v84, v79
	v_add_f32_e32 v79, 1.0, v81
	s_waitcnt lgkmcnt(0)
	v_add_f32_e32 v70, v70, v74
	v_mul_f32_e32 v70, 0xbfb8aa3b, v70
	v_exp_f32_e32 v74, v70
	v_add_f32_e32 v70, v71, v75
	v_mul_f32_e32 v70, 0xbfb8aa3b, v70
	v_exp_f32_e32 v71, v70
	v_add_f32_e32 v72, v72, v76
	v_mul_f32_e32 v72, 0xbfb8aa3b, v72
	v_add_f32_e32 v73, v73, v77
	v_add_f32_e32 v71, 1.0, v71
	v_add_f32_e32 v74, 1.0, v74
	v_exp_f32_e32 v72, v72
	v_mul_f32_e32 v73, 0xbfb8aa3b, v73
	v_rcp_f32_e32 v81, v71
	v_rcp_f32_e32 v70, v79
	v_rcp_f32_e32 v79, v74
	v_exp_f32_e32 v73, v73
	s_mov_b32 s2, 0x437f0000
	v_add_f32_e32 v71, 1.0, v72
	v_pk_fma_f32 v[74:75], v[80:81], s[2:3], 0.5 op_sel_hi:[1,0,0]
	v_rcp_f32_e32 v85, v71
	v_add_f32_e32 v71, 1.0, v73
	v_pk_fma_f32 v[72:73], v[78:79], s[2:3], 0.5 op_sel_hi:[1,0,0]
	v_cvt_u32_f32_e32 v75, v75
	v_cvt_u32_f32_e32 v74, v74
	v_cvt_u32_f32_e32 v73, v73
	v_cvt_u32_f32_e32 v72, v72
	v_rcp_f32_e32 v71, v71
	v_lshlrev_b32_e32 v75, 8, v75
	v_lshlrev_b32_e32 v74, 8, v74
	v_or_b32_e32 v75, v75, v73
	v_or_b32_e32 v74, v74, v72
	v_pk_fma_f32 v[72:73], v[84:85], s[2:3], 0.5 op_sel_hi:[1,0,0]
	v_pk_fma_f32 v[70:71], v[70:71], s[2:3], 0.5 op_sel_hi:[1,0,0]
	v_cvt_u32_f32_sdwa v72, v72 dst_sel:WORD_1 dst_unused:UNUSED_PAD src0_sel:DWORD
	v_cvt_u32_f32_sdwa v73, v73 dst_sel:WORD_1 dst_unused:UNUSED_PAD src0_sel:DWORD
	v_cvt_u32_f32_sdwa v71, v71 dst_sel:BYTE_3 dst_unused:UNUSED_PAD src0_sel:DWORD
	v_cvt_u32_f32_sdwa v70, v70 dst_sel:BYTE_3 dst_unused:UNUSED_PAD src0_sel:DWORD
	v_or_b32_e32 v72, v74, v72
	v_or_b32_e32 v73, v75, v73
	v_ashrrev_i32_e32 v83, 31, v82
	v_or_b32_e32 v71, v73, v71
	v_or_b32_e32 v70, v72, v70
	v_lshlrev_b64 v[72:73], 5, v[82:83]
	v_lshl_add_u64 v[72:73], v[162:163], 0, v[72:73]
	global_store_dwordx2 v[72:73], v[70:71], off

; DI float sigmoidf_(float x) { return __builtin_amdgcn_rcpf(1.f + __expf(-x)); }
;   template <int GRP>
;   DI void run(const f32x4 (&acc)[2][2][4][2], const pg8::Unit& u, int wr, int wc, int fr, int fq) const {
;     ...
;         if (nt < 4) { off = OFF_QAB; ld = 1024; c0 = nt * 128; act = 0; }
;         else if (nt < 16) { off = OFF_GA; ld = 512; c0 = (nt - 12) * 128; act = 1; }
;         else if (nt < 20) { off = OFF_QAB; ld = 1024; c0 = 512 + (nt - 16) * 128; act = 0; }
;         else if (nt < 25) { off = OFF_GB; ld = 512; c0 = (nt - 21) * 128; act = 1; }
;         else if (nt < 29) { off = OFF_QI; ld = 512; c0 = (nt - 25) * 128; act = 0; }
;         else if (nt < 38) { off = OFF_RA; ld = 1024; c0 = (nt - 30) * 128; act = 2; }
;         else { off = OFF_RB; ld = 1024; c0 = (nt - 38) * 128; act = 2; }
;         bf16_t* dst = reinterpret_cast<bf16_t*>(ws + off) + c0 + 32 * wc + 8 * fq;
; #pragma unroll
;         for (int ai = 0; ai < 2; ++ai)
; #pragma unroll
;           for (int m = 0; m < 4; ++m) {
;             int row = u.pm * 256 + 128 * ai + 64 * wr + 16 * m + fr;
;             asm volatile("" : "+v"(row));
;             if (act == 2) {
;               u32x2v g8;
; #pragma unroll
;               for (int n = 0; n < 2; ++n) {
;                 const f32x4 v = acc[ai][bj][m][n] + bp[n];
;                 unsigned q = 0u;
; #pragma unroll
;                 for (int j = 0; j < 4; ++j) q |= ((unsigned)(sigmoidf_(v[j]) * 255.f + 0.5f)) << (8 * j);
;                 if (n == 0) g8.x = q; else g8.y = q;
;               }
;               *reinterpret_cast<u32x2v*>(reinterpret_cast<unsigned char*>(ws + off) + (size_t)row * 1024 + c0 + 32 * wc + 8 * fq) = g8;
;               continue;
;             }
;             u32x4v pk;
; #pragma unroll
;             for (int n = 0; n < 2; ++n) {
;               f32x4 v = acc[ai][bj][m][n] + bp[n];
;               if (act != 0) {
; #pragma unroll
;                 for (int j = 0; j < 4; ++j) { const float sg = sigmoidf_(v[j]); v[j] = (act == 1) ? v[j] * sg : sg; }
.LBB0_1650:
	s_xor_b64 s[24:25], s[24:25], -1
	v_readlane_b32 s28, v249, 0
	v_readlane_b32 s29, v249, 1
	s_add_u32 s9, s28, s2
	s_addc_u32 s11, s29, s3
	s_ashr_i32 s7, s6, 31
	s_lshl_b64 s[2:3], s[6:7], 1
	s_add_u32 s2, s9, s2
	s_addc_u32 s3, s11, s3
	s_lshl_b32 s28, s42, 1
	s_add_u32 s2, s2, s28
	s_addc_u32 s3, s3, 0
	v_lshl_add_u64 v[74:75], s[2:3], 0, v[16:17]
	s_add_u32 s2, s9, s6
	s_addc_u32 s3, s11, s7
	s_add_i32 s6, s6, s42
	s_lshr_b32 s6, s6, 5
	s_mul_i32 s6, s6, 0x204000
	s_add_u32 s6, s9, s6
	s_addc_u32 s7, s11, 0
	s_lshl_b32 s9, s48, 8
	s_waitcnt lgkmcnt(0)
	v_add_u32_e32 v78, s9, v21
	ds_read_b128 v[70:73], v90
	v_cndmask_b32_e64 v16, 0, 1, s[24:25]
	s_mov_b64 s[26:27], -1
	s_and_b64 vcc, exec, s[4:5]
	v_cmp_ne_u32_e64 s[2:3], 1, v16
	s_cbranch_vccnz .LBB0_1656
	s_waitcnt lgkmcnt(0)
	v_pk_add_f32 v[76:77], v[68:69], v[72:73]
	s_and_b64 vcc, exec, s[2:3]
	v_pk_add_f32 v[80:81], v[66:67], v[70:71]
	s_cbranch_vccnz .LBB0_1653
	v_mul_f32_e32 v16, 0xbfb8aa3b, v80
	v_exp_f32_e32 v16, v16
	v_mul_f32_e32 v83, 0xbfb8aa3b, v76
	v_mul_f32_e32 v79, 0xbfb8aa3b, v81
	v_exp_f32_e32 v79, v79
	v_add_f32_e32 v16, 1.0, v16
	v_rcp_f32_e32 v82, v16
	v_exp_f32_e32 v16, v83
	v_mul_f32_e32 v83, 0xbfb8aa3b, v77
	v_exp_f32_e32 v83, v83
	v_add_f32_e32 v79, 1.0, v79
	v_add_f32_e32 v16, 1.0, v16
	v_rcp_f32_e32 v84, v16
	v_add_f32_e32 v16, 1.0, v83
	v_rcp_f32_e32 v85, v16
	v_rcp_f32_e32 v83, v79
	v_pk_mul_f32 v[76:77], v[76:77], v[84:85]
	v_pk_mul_f32 v[80:81], v[80:81], v[82:83]

; DI float sigmoidf_(float x) { return __builtin_amdgcn_rcpf(1.f + __expf(-x)); }
;   template <int GRP>
;   DI void run(const f32x4 (&acc)[2][2][4][2], const pg8::Unit& u, int wr, int wc, int fr, int fq) const {
;     ...
;             if (act == 2) {
;               u32x2v g8;
; #pragma unroll
;               for (int n = 0; n < 2; ++n) {
;                 const f32x4 v = acc[ai][bj][m][n] + bp[n];
;                 unsigned q = 0u;
; #pragma unroll
;                 for (int j = 0; j < 4; ++j) q |= ((unsigned)(sigmoidf_(v[j]) * 255.f + 0.5f)) << (8 * j);
;                 if (n == 0) g8.x = q; else g8.y = q;
;               }
;               *reinterpret_cast<u32x2v*>(reinterpret_cast<unsigned char*>(ws + off) + (size_t)row * 1024 + c0 + 32 * wc + 8 * fq) = g8;
.LBB0_1656:
	v_lshl_add_u64 v[76:77], s[6:7], 0, v[144:145]
	s_and_b64 vcc, exec, s[26:27]
	s_cbranch_vccz .LBB0_1658
	s_waitcnt lgkmcnt(0)
	v_add_f32_e32 v16, v66, v70
	v_mul_f32_e32 v16, 0xbfb8aa3b, v16
	v_add_f32_e32 v66, v67, v71
	v_exp_f32_e32 v16, v16
	v_mul_f32_e32 v66, 0xbfb8aa3b, v66
	v_exp_f32_e32 v66, v66
	s_mov_b32 s6, 0x437f0000
	v_add_f32_e32 v16, 1.0, v16
	v_rcp_f32_e32 v70, v16
	v_add_f32_e32 v16, 1.0, v66
	v_add_f32_e32 v66, v68, v72
	v_mul_f32_e32 v66, 0xbfb8aa3b, v66
	v_exp_f32_e32 v71, v66
	v_add_f32_e32 v66, v69, v73
	v_mul_f32_e32 v66, 0xbfb8aa3b, v66
	v_exp_f32_e32 v73, v66
	ds_read_b128 v[66:69], v90 offset:16
	v_rcp_f32_e32 v72, v16
	v_add_f32_e32 v16, 1.0, v71
	v_rcp_f32_e32 v80, v16
	v_add_f32_e32 v16, 1.0, v73
	s_waitcnt lgkmcnt(0)
	v_add_f32_e32 v62, v62, v66
	v_mul_f32_e32 v62, 0xbfb8aa3b, v62
	v_exp_f32_e32 v66, v62
	v_add_f32_e32 v62, v63, v67
	v_mul_f32_e32 v62, 0xbfb8aa3b, v62
	v_exp_f32_e32 v63, v62
	v_rcp_f32_e32 v62, v16
	v_add_f32_e32 v16, 1.0, v66
	v_rcp_f32_e32 v71, v16
	v_add_f32_e32 v16, 1.0, v63
	v_add_f32_e32 v63, v64, v68
	v_mul_f32_e32 v63, 0xbfb8aa3b, v63
	v_add_f32_e32 v64, v65, v69
	v_exp_f32_e32 v63, v63
	v_mul_f32_e32 v64, 0xbfb8aa3b, v64
	v_exp_f32_e32 v64, v64
	v_rcp_f32_e32 v73, v16
	v_add_f32_e32 v16, 1.0, v63
	v_rcp_f32_e32 v81, v16
	v_add_f32_e32 v16, 1.0, v64
	v_pk_fma_f32 v[66:67], v[72:73], s[6:7], 0.5 op_sel_hi:[1,0,0]
	v_rcp_f32_e32 v63, v16
	v_pk_fma_f32 v[64:65], v[70:71], s[6:7], 0.5 op_sel_hi:[1,0,0]
	v_cvt_u32_f32_e32 v16, v67
	v_cvt_u32_f32_e32 v66, v66
	v_cvt_u32_f32_e32 v65, v65
	v_cvt_u32_f32_e32 v64, v64
	v_lshlrev_b32_e32 v16, 8, v16
	v_lshlrev_b32_e32 v66, 8, v66
	v_or_b32_e32 v16, v16, v65
	v_or_b32_e32 v66, v66, v64
	v_pk_fma_f32 v[64:65], v[80:81], s[6:7], 0.5 op_sel_hi:[1,0,0]
	v_pk_fma_f32 v[62:63], v[62:63], s[6:7], 0.5 op_sel_hi:[1,0,0]
	v_cvt_u32_f32_sdwa v64, v64 dst_sel:WORD_1 dst_unused:UNUSED_PAD src0_sel:DWORD
	v_cvt_u32_f32_sdwa v65, v65 dst_sel:WORD_1 dst_unused:UNUSED_PAD src0_sel:DWORD
	v_cvt_u32_f32_sdwa v62, v62 dst_sel:BYTE_3 dst_unused:UNUSED_PAD src0_sel:DWORD
	v_cvt_u32_f32_sdwa v63, v63 dst_sel:BYTE_3 dst_unused:UNUSED_PAD src0_sel:DWORD
	v_or_b32_e32 v64, v66, v64
	v_ashrrev_i32_e32 v79, 31, v78
	v_or_b32_e32 v16, v16, v65
	v_or_b32_e32 v62, v64, v62
	v_lshlrev_b64 v[64:65], 5, v[78:79]
	v_or_b32_e32 v63, v16, v63
	v_lshl_add_u64 v[64:65], v[76:77], 0, v[64:65]
	global_store_dwordx2 v[64:65], v[62:63], off

; DI float sigmoidf_(float x) { return __builtin_amdgcn_rcpf(1.f + __expf(-x)); }
;   template <int GRP>
;   DI void run(const f32x4 (&acc)[2][2][4][2], const pg8::Unit& u, int wr, int wc, int fr, int fq) const {
;     ...
;             if (act == 2) {
;               u32x2v g8;
; #pragma unroll
;               for (int n = 0; n < 2; ++n) {
;                 const f32x4 v = acc[ai][bj][m][n] + bp[n];
;                 unsigned q = 0u;
; #pragma unroll
;                 for (int j = 0; j < 4; ++j) q |= ((unsigned)(sigmoidf_(v[j]) * 255.f + 0.5f)) << (8 * j);
;                 if (n == 0) g8.x = q; else g8.y = q;
;               }
;               *reinterpret_cast<u32x2v*>(reinterpret_cast<unsigned char*>(ws + off) + (size_t)row * 1024 + c0 + 32 * wc + 8 * fq) = g8;
.LBB0_1664:
	s_and_b64 vcc, exec, s[6:7]
	s_cbranch_vccz .LBB0_1666
	s_waitcnt lgkmcnt(0)
	v_add_f32_e32 v16, v58, v62
	v_mul_f32_e32 v16, 0xbfb8aa3b, v16
	v_add_f32_e32 v58, v59, v63
	v_exp_f32_e32 v16, v16
	v_mul_f32_e32 v58, 0xbfb8aa3b, v58
	v_exp_f32_e32 v58, v58
	s_mov_b32 s6, 0x437f0000
	v_add_f32_e32 v16, 1.0, v16
	v_rcp_f32_e32 v62, v16
	v_add_f32_e32 v16, 1.0, v58
	v_add_f32_e32 v58, v60, v64
	v_mul_f32_e32 v58, 0xbfb8aa3b, v58
	v_exp_f32_e32 v63, v58
	v_add_f32_e32 v58, v61, v65
	v_mul_f32_e32 v58, 0xbfb8aa3b, v58
	v_exp_f32_e32 v65, v58
	ds_read_b128 v[58:61], v90 offset:16
	v_rcp_f32_e32 v64, v16
	v_add_f32_e32 v16, 1.0, v63
	v_rcp_f32_e32 v68, v16
	v_add_f32_e32 v16, 1.0, v65
	s_waitcnt lgkmcnt(0)
	v_add_f32_e32 v54, v54, v58
	v_mul_f32_e32 v54, 0xbfb8aa3b, v54
	v_exp_f32_e32 v58, v54
	v_add_f32_e32 v54, v55, v59
	v_mul_f32_e32 v54, 0xbfb8aa3b, v54
	v_exp_f32_e32 v55, v54
	v_rcp_f32_e32 v54, v16
	v_add_f32_e32 v16, 1.0, v58
	v_rcp_f32_e32 v63, v16
	v_add_f32_e32 v16, 1.0, v55
	v_add_f32_e32 v55, v56, v60
	v_mul_f32_e32 v55, 0xbfb8aa3b, v55
	v_add_f32_e32 v56, v57, v61
	v_exp_f32_e32 v55, v55
	v_mul_f32_e32 v56, 0xbfb8aa3b, v56
	v_exp_f32_e32 v56, v56
	v_rcp_f32_e32 v65, v16
	v_add_f32_e32 v16, 1.0, v55
	v_rcp_f32_e32 v69, v16
	v_add_f32_e32 v16, 1.0, v56
	v_pk_fma_f32 v[58:59], v[64:65], s[6:7], 0.5 op_sel_hi:[1,0,0]
	v_rcp_f32_e32 v55, v16
	v_pk_fma_f32 v[56:57], v[62:63], s[6:7], 0.5 op_sel_hi:[1,0,0]
	v_cvt_u32_f32_e32 v16, v59
	v_cvt_u32_f32_e32 v58, v58
	v_cvt_u32_f32_e32 v57, v57
	v_cvt_u32_f32_e32 v56, v56
	v_lshlrev_b32_e32 v16, 8, v16
	v_lshlrev_b32_e32 v58, 8, v58
	v_or_b32_e32 v16, v16, v57
	v_or_b32_e32 v58, v58, v56
	v_pk_fma_f32 v[56:57], v[68:69], s[6:7], 0.5 op_sel_hi:[1,0,0]
	v_pk_fma_f32 v[54:55], v[54:55], s[6:7], 0.5 op_sel_hi:[1,0,0]
	v_cvt_u32_f32_sdwa v56, v56 dst_sel:WORD_1 dst_unused:UNUSED_PAD src0_sel:DWORD
	v_cvt_u32_f32_sdwa v57, v57 dst_sel:WORD_1 dst_unused:UNUSED_PAD src0_sel:DWORD
	v_cvt_u32_f32_sdwa v54, v54 dst_sel:BYTE_3 dst_unused:UNUSED_PAD src0_sel:DWORD
	v_cvt_u32_f32_sdwa v55, v55 dst_sel:BYTE_3 dst_unused:UNUSED_PAD src0_sel:DWORD
	v_or_b32_e32 v56, v58, v56
	v_ashrrev_i32_e32 v67, 31, v66
	v_or_b32_e32 v16, v16, v57
	v_or_b32_e32 v54, v56, v54
	v_lshlrev_b64 v[56:57], 5, v[66:67]
	v_or_b32_e32 v55, v16, v55
	v_lshl_add_u64 v[56:57], v[76:77], 0, v[56:57]
	global_store_dwordx2 v[56:57], v[54:55], off

; DI float sigmoidf_(float x) { return __builtin_amdgcn_rcpf(1.f + __expf(-x)); }
;   template <int GRP>
;   DI void run(const f32x4 (&acc)[2][2][4][2], const pg8::Unit& u, int wr, int wc, int fr, int fq) const {
;     ...
;             if (act == 2) {
;               u32x2v g8;
; #pragma unroll
;               for (int n = 0; n < 2; ++n) {
;                 const f32x4 v = acc[ai][bj][m][n] + bp[n];
;                 unsigned q = 0u;
; #pragma unroll
;                 for (int j = 0; j < 4; ++j) q |= ((unsigned)(sigmoidf_(v[j]) * 255.f + 0.5f)) << (8 * j);
;                 if (n == 0) g8.x = q; else g8.y = q;
;               }
;               *reinterpret_cast<u32x2v*>(reinterpret_cast<unsigned char*>(ws + off) + (size_t)row * 1024 + c0 + 32 * wc + 8 * fq) = g8;
.LBB0_1672:
	s_and_b64 vcc, exec, s[6:7]
	s_cbranch_vccz .LBB0_1674
	s_waitcnt lgkmcnt(0)
	v_add_f32_e32 v16, v50, v54
	v_mul_f32_e32 v16, 0xbfb8aa3b, v16
	v_add_f32_e32 v50, v51, v55
	v_exp_f32_e32 v16, v16
	v_mul_f32_e32 v50, 0xbfb8aa3b, v50
	v_exp_f32_e32 v50, v50
	s_mov_b32 s6, 0x437f0000
	v_add_f32_e32 v16, 1.0, v16
	v_rcp_f32_e32 v54, v16
	v_add_f32_e32 v16, 1.0, v50
	v_add_f32_e32 v50, v52, v56
	v_mul_f32_e32 v50, 0xbfb8aa3b, v50
	v_exp_f32_e32 v55, v50
	v_add_f32_e32 v50, v53, v57
	v_mul_f32_e32 v50, 0xbfb8aa3b, v50
	v_exp_f32_e32 v57, v50
	ds_read_b128 v[50:53], v90 offset:16
	v_rcp_f32_e32 v56, v16
	v_add_f32_e32 v16, 1.0, v55
	v_rcp_f32_e32 v60, v16
	v_add_f32_e32 v16, 1.0, v57
	s_waitcnt lgkmcnt(0)
	v_add_f32_e32 v46, v46, v50
	v_mul_f32_e32 v46, 0xbfb8aa3b, v46
	v_exp_f32_e32 v50, v46
	v_add_f32_e32 v46, v47, v51
	v_mul_f32_e32 v46, 0xbfb8aa3b, v46
	v_exp_f32_e32 v47, v46
	v_rcp_f32_e32 v46, v16
	v_add_f32_e32 v16, 1.0, v50
	v_rcp_f32_e32 v55, v16
	v_add_f32_e32 v16, 1.0, v47
	v_add_f32_e32 v47, v48, v52
	v_mul_f32_e32 v47, 0xbfb8aa3b, v47
	v_add_f32_e32 v48, v49, v53
	v_exp_f32_e32 v47, v47
	v_mul_f32_e32 v48, 0xbfb8aa3b, v48
	v_exp_f32_e32 v48, v48
	v_rcp_f32_e32 v57, v16
	v_add_f32_e32 v16, 1.0, v47
	v_rcp_f32_e32 v61, v16
	v_add_f32_e32 v16, 1.0, v48
	v_pk_fma_f32 v[50:51], v[56:57], s[6:7], 0.5 op_sel_hi:[1,0,0]
	v_rcp_f32_e32 v47, v16
	v_pk_fma_f32 v[48:49], v[54:55], s[6:7], 0.5 op_sel_hi:[1,0,0]
	v_cvt_u32_f32_e32 v16, v51
	v_cvt_u32_f32_e32 v50, v50
	v_cvt_u32_f32_e32 v49, v49
	v_cvt_u32_f32_e32 v48, v48
	v_lshlrev_b32_e32 v16, 8, v16
	v_lshlrev_b32_e32 v50, 8, v50
	v_or_b32_e32 v16, v16, v49
	v_or_b32_e32 v50, v50, v48
	v_pk_fma_f32 v[48:49], v[60:61], s[6:7], 0.5 op_sel_hi:[1,0,0]
	v_pk_fma_f32 v[46:47], v[46:47], s[6:7], 0.5 op_sel_hi:[1,0,0]
	v_cvt_u32_f32_sdwa v48, v48 dst_sel:WORD_1 dst_unused:UNUSED_PAD src0_sel:DWORD
	v_cvt_u32_f32_sdwa v49, v49 dst_sel:WORD_1 dst_unused:UNUSED_PAD src0_sel:DWORD
	v_cvt_u32_f32_sdwa v46, v46 dst_sel:BYTE_3 dst_unused:UNUSED_PAD src0_sel:DWORD
	v_cvt_u32_f32_sdwa v47, v47 dst_sel:BYTE_3 dst_unused:UNUSED_PAD src0_sel:DWORD
	v_or_b32_e32 v48, v50, v48
	v_ashrrev_i32_e32 v59, 31, v58
	v_or_b32_e32 v16, v16, v49
	v_or_b32_e32 v46, v48, v46
	v_lshlrev_b64 v[48:49], 5, v[58:59]
	v_or_b32_e32 v47, v16, v47
	v_lshl_add_u64 v[48:49], v[76:77], 0, v[48:49]
	global_store_dwordx2 v[48:49], v[46:47], off

; DI float sigmoidf_(float x) { return __builtin_amdgcn_rcpf(1.f + __expf(-x)); }
;   template <int GRP>
;   DI void run(const f32x4 (&acc)[2][2][4][2], const pg8::Unit& u, int wr, int wc, int fr, int fq) const {
;     ...
;             if (act == 2) {
;               u32x2v g8;
; #pragma unroll
;               for (int n = 0; n < 2; ++n) {
;                 const f32x4 v = acc[ai][bj][m][n] + bp[n];
;                 unsigned q = 0u;
; #pragma unroll
;                 for (int j = 0; j < 4; ++j) q |= ((unsigned)(sigmoidf_(v[j]) * 255.f + 0.5f)) << (8 * j);
;                 if (n == 0) g8.x = q; else g8.y = q;
;               }
;               *reinterpret_cast<u32x2v*>(reinterpret_cast<unsigned char*>(ws + off) + (size_t)row * 1024 + c0 + 32 * wc + 8 * fq) = g8;
.LBB0_1680:
	s_and_b64 vcc, exec, s[6:7]
	s_cbranch_vccz .LBB0_1682
	s_waitcnt lgkmcnt(0)
	v_add_f32_e32 v16, v42, v46
	v_mul_f32_e32 v16, 0xbfb8aa3b, v16
	v_add_f32_e32 v42, v43, v47
	v_exp_f32_e32 v16, v16
	v_mul_f32_e32 v42, 0xbfb8aa3b, v42
	v_exp_f32_e32 v42, v42
	s_mov_b32 s6, 0x437f0000
	v_add_f32_e32 v16, 1.0, v16
	v_rcp_f32_e32 v46, v16
	v_add_f32_e32 v16, 1.0, v42
	v_add_f32_e32 v42, v44, v48
	v_mul_f32_e32 v42, 0xbfb8aa3b, v42
	v_exp_f32_e32 v47, v42
	v_add_f32_e32 v42, v45, v49
	v_mul_f32_e32 v42, 0xbfb8aa3b, v42
	v_exp_f32_e32 v49, v42
	ds_read_b128 v[42:45], v90 offset:16
	v_rcp_f32_e32 v48, v16
	v_add_f32_e32 v16, 1.0, v47
	v_rcp_f32_e32 v52, v16
	v_add_f32_e32 v16, 1.0, v49
	s_waitcnt lgkmcnt(0)
	v_add_f32_e32 v38, v38, v42
	v_mul_f32_e32 v38, 0xbfb8aa3b, v38
	v_exp_f32_e32 v42, v38
	v_add_f32_e32 v38, v39, v43
	v_mul_f32_e32 v38, 0xbfb8aa3b, v38
	v_exp_f32_e32 v39, v38
	v_rcp_f32_e32 v38, v16
	v_add_f32_e32 v16, 1.0, v42
	v_rcp_f32_e32 v47, v16
	v_add_f32_e32 v16, 1.0, v39
	v_add_f32_e32 v39, v40, v44
	v_mul_f32_e32 v39, 0xbfb8aa3b, v39
	v_add_f32_e32 v40, v41, v45
	v_exp_f32_e32 v39, v39
	v_mul_f32_e32 v40, 0xbfb8aa3b, v40
	v_exp_f32_e32 v40, v40
	v_rcp_f32_e32 v49, v16
	v_add_f32_e32 v16, 1.0, v39
	v_rcp_f32_e32 v53, v16
	v_add_f32_e32 v16, 1.0, v40
	v_pk_fma_f32 v[42:43], v[48:49], s[6:7], 0.5 op_sel_hi:[1,0,0]
	v_rcp_f32_e32 v39, v16
	v_pk_fma_f32 v[40:41], v[46:47], s[6:7], 0.5 op_sel_hi:[1,0,0]
	v_cvt_u32_f32_e32 v16, v43
	v_cvt_u32_f32_e32 v42, v42
	v_cvt_u32_f32_e32 v41, v41
	v_cvt_u32_f32_e32 v40, v40
	v_lshlrev_b32_e32 v16, 8, v16
	v_lshlrev_b32_e32 v42, 8, v42
	v_or_b32_e32 v16, v16, v41
	v_or_b32_e32 v42, v42, v40
	v_pk_fma_f32 v[40:41], v[52:53], s[6:7], 0.5 op_sel_hi:[1,0,0]
	v_pk_fma_f32 v[38:39], v[38:39], s[6:7], 0.5 op_sel_hi:[1,0,0]
	v_cvt_u32_f32_sdwa v40, v40 dst_sel:WORD_1 dst_unused:UNUSED_PAD src0_sel:DWORD
	v_cvt_u32_f32_sdwa v41, v41 dst_sel:WORD_1 dst_unused:UNUSED_PAD src0_sel:DWORD
	v_cvt_u32_f32_sdwa v38, v38 dst_sel:BYTE_3 dst_unused:UNUSED_PAD src0_sel:DWORD
	v_cvt_u32_f32_sdwa v39, v39 dst_sel:BYTE_3 dst_unused:UNUSED_PAD src0_sel:DWORD
	v_or_b32_e32 v40, v42, v40
	v_ashrrev_i32_e32 v51, 31, v50
	v_or_b32_e32 v16, v16, v41
	v_or_b32_e32 v38, v40, v38
	v_lshlrev_b64 v[40:41], 5, v[50:51]
	v_or_b32_e32 v39, v16, v39
	v_lshl_add_u64 v[40:41], v[76:77], 0, v[40:41]
	global_store_dwordx2 v[40:41], v[38:39], off

; DI float sigmoidf_(float x) { return __builtin_amdgcn_rcpf(1.f + __expf(-x)); }
;   template <int GRP>
;   DI void run(const f32x4 (&acc)[2][2][4][2], const pg8::Unit& u, int wr, int wc, int fr, int fq) const {
;     ...
;             if (act == 2) {
;               u32x2v g8;
; #pragma unroll
;               for (int n = 0; n < 2; ++n) {
;                 const f32x4 v = acc[ai][bj][m][n] + bp[n];
;                 unsigned q = 0u;
; #pragma unroll
;                 for (int j = 0; j < 4; ++j) q |= ((unsigned)(sigmoidf_(v[j]) * 255.f + 0.5f)) << (8 * j);
;                 if (n == 0) g8.x = q; else g8.y = q;
;               }
;               *reinterpret_cast<u32x2v*>(reinterpret_cast<unsigned char*>(ws + off) + (size_t)row * 1024 + c0 + 32 * wc + 8 * fq) = g8;
.LBB0_1688:
	s_and_b64 vcc, exec, s[6:7]
	s_cbranch_vccz .LBB0_1690
	s_waitcnt lgkmcnt(0)
	v_add_f32_e32 v16, v34, v38
	v_mul_f32_e32 v16, 0xbfb8aa3b, v16
	v_add_f32_e32 v34, v35, v39
	v_exp_f32_e32 v16, v16
	v_mul_f32_e32 v34, 0xbfb8aa3b, v34
	v_exp_f32_e32 v34, v34
	s_mov_b32 s6, 0x437f0000
	v_add_f32_e32 v16, 1.0, v16
	v_rcp_f32_e32 v38, v16
	v_add_f32_e32 v16, 1.0, v34
	v_add_f32_e32 v34, v36, v40
	v_mul_f32_e32 v34, 0xbfb8aa3b, v34
	v_exp_f32_e32 v39, v34
	v_add_f32_e32 v34, v37, v41
	v_mul_f32_e32 v34, 0xbfb8aa3b, v34
	v_exp_f32_e32 v41, v34
	ds_read_b128 v[34:37], v90 offset:16
	v_rcp_f32_e32 v40, v16
	v_add_f32_e32 v16, 1.0, v39
	v_rcp_f32_e32 v44, v16
	v_add_f32_e32 v16, 1.0, v41
	s_waitcnt lgkmcnt(0)
	v_add_f32_e32 v30, v30, v34
	v_mul_f32_e32 v30, 0xbfb8aa3b, v30
	v_exp_f32_e32 v34, v30
	v_add_f32_e32 v30, v31, v35
	v_mul_f32_e32 v30, 0xbfb8aa3b, v30
	v_exp_f32_e32 v31, v30
	v_rcp_f32_e32 v30, v16
	v_add_f32_e32 v16, 1.0, v34
	v_rcp_f32_e32 v39, v16
	v_add_f32_e32 v16, 1.0, v31
	v_add_f32_e32 v31, v32, v36
	v_mul_f32_e32 v31, 0xbfb8aa3b, v31
	v_add_f32_e32 v32, v33, v37
	v_exp_f32_e32 v31, v31
	v_mul_f32_e32 v32, 0xbfb8aa3b, v32
	v_exp_f32_e32 v32, v32
	v_rcp_f32_e32 v41, v16
	v_add_f32_e32 v16, 1.0, v31
	v_rcp_f32_e32 v45, v16
	v_add_f32_e32 v16, 1.0, v32
	v_pk_fma_f32 v[34:35], v[40:41], s[6:7], 0.5 op_sel_hi:[1,0,0]
	v_rcp_f32_e32 v31, v16
	v_pk_fma_f32 v[32:33], v[38:39], s[6:7], 0.5 op_sel_hi:[1,0,0]
	v_cvt_u32_f32_e32 v16, v35
	v_cvt_u32_f32_e32 v34, v34
	v_cvt_u32_f32_e32 v33, v33
	v_cvt_u32_f32_e32 v32, v32
	v_lshlrev_b32_e32 v16, 8, v16
	v_lshlrev_b32_e32 v34, 8, v34
	v_or_b32_e32 v16, v16, v33
	v_or_b32_e32 v34, v34, v32
	v_pk_fma_f32 v[32:33], v[44:45], s[6:7], 0.5 op_sel_hi:[1,0,0]
	v_pk_fma_f32 v[30:31], v[30:31], s[6:7], 0.5 op_sel_hi:[1,0,0]
	v_cvt_u32_f32_sdwa v32, v32 dst_sel:WORD_1 dst_unused:UNUSED_PAD src0_sel:DWORD
	v_cvt_u32_f32_sdwa v33, v33 dst_sel:WORD_1 dst_unused:UNUSED_PAD src0_sel:DWORD
	v_cvt_u32_f32_sdwa v30, v30 dst_sel:BYTE_3 dst_unused:UNUSED_PAD src0_sel:DWORD
	v_cvt_u32_f32_sdwa v31, v31 dst_sel:BYTE_3 dst_unused:UNUSED_PAD src0_sel:DWORD
	v_or_b32_e32 v32, v34, v32
	v_ashrrev_i32_e32 v43, 31, v42
	v_or_b32_e32 v16, v16, v33
	v_or_b32_e32 v30, v32, v30
	v_lshlrev_b64 v[32:33], 5, v[42:43]
	v_or_b32_e32 v31, v16, v31
	v_lshl_add_u64 v[32:33], v[76:77], 0, v[32:33]
	global_store_dwordx2 v[32:33], v[30:31], off

; DI float sigmoidf_(float x) { return __builtin_amdgcn_rcpf(1.f + __expf(-x)); }
;   template <int GRP>
;   DI void run(const f32x4 (&acc)[2][2][4][2], const pg8::Unit& u, int wr, int wc, int fr, int fq) const {
;     ...
;             if (act == 2) {
;               u32x2v g8;
; #pragma unroll
;               for (int n = 0; n < 2; ++n) {
;                 const f32x4 v = acc[ai][bj][m][n] + bp[n];
;                 unsigned q = 0u;
; #pragma unroll
;                 for (int j = 0; j < 4; ++j) q |= ((unsigned)(sigmoidf_(v[j]) * 255.f + 0.5f)) << (8 * j);
;                 if (n == 0) g8.x = q; else g8.y = q;
;               }
;               *reinterpret_cast<u32x2v*>(reinterpret_cast<unsigned char*>(ws + off) + (size_t)row * 1024 + c0 + 32 * wc + 8 * fq) = g8;
.LBB0_1696:
	s_and_b64 vcc, exec, s[6:7]
	s_cbranch_vccz .LBB0_1698
	s_waitcnt lgkmcnt(0)
	v_add_f32_e32 v16, v26, v30
	v_mul_f32_e32 v16, 0xbfb8aa3b, v16
	v_add_f32_e32 v26, v27, v31
	v_exp_f32_e32 v16, v16
	v_mul_f32_e32 v26, 0xbfb8aa3b, v26
	v_exp_f32_e32 v26, v26
	s_mov_b32 s6, 0x437f0000
	v_add_f32_e32 v16, 1.0, v16
	v_rcp_f32_e32 v30, v16
	v_add_f32_e32 v16, 1.0, v26
	v_add_f32_e32 v26, v28, v32
	v_mul_f32_e32 v26, 0xbfb8aa3b, v26
	v_exp_f32_e32 v31, v26
	v_add_f32_e32 v26, v29, v33
	v_mul_f32_e32 v26, 0xbfb8aa3b, v26
	v_exp_f32_e32 v33, v26
	ds_read_b128 v[26:29], v90 offset:16
	v_rcp_f32_e32 v32, v16
	v_add_f32_e32 v16, 1.0, v31
	v_rcp_f32_e32 v36, v16
	v_add_f32_e32 v16, 1.0, v33
	s_waitcnt lgkmcnt(0)
	v_add_f32_e32 v22, v22, v26
	v_mul_f32_e32 v22, 0xbfb8aa3b, v22
	v_exp_f32_e32 v26, v22
	v_add_f32_e32 v22, v23, v27
	v_mul_f32_e32 v22, 0xbfb8aa3b, v22
	v_exp_f32_e32 v23, v22
	v_rcp_f32_e32 v22, v16
	v_add_f32_e32 v16, 1.0, v26
	v_rcp_f32_e32 v31, v16
	v_add_f32_e32 v16, 1.0, v23
	v_add_f32_e32 v23, v24, v28
	v_mul_f32_e32 v23, 0xbfb8aa3b, v23
	v_add_f32_e32 v24, v25, v29
	v_exp_f32_e32 v23, v23
	v_mul_f32_e32 v24, 0xbfb8aa3b, v24
	v_exp_f32_e32 v24, v24
	v_rcp_f32_e32 v33, v16
	v_add_f32_e32 v16, 1.0, v23
	v_rcp_f32_e32 v37, v16
	v_add_f32_e32 v16, 1.0, v24
	v_pk_fma_f32 v[26:27], v[32:33], s[6:7], 0.5 op_sel_hi:[1,0,0]
	v_rcp_f32_e32 v23, v16
	v_pk_fma_f32 v[24:25], v[30:31], s[6:7], 0.5 op_sel_hi:[1,0,0]
	v_cvt_u32_f32_e32 v16, v27
	v_cvt_u32_f32_e32 v26, v26
	v_cvt_u32_f32_e32 v25, v25
	v_cvt_u32_f32_e32 v24, v24
	v_lshlrev_b32_e32 v16, 8, v16
	v_lshlrev_b32_e32 v26, 8, v26
	v_or_b32_e32 v16, v16, v25
	v_or_b32_e32 v26, v26, v24
	v_pk_fma_f32 v[24:25], v[36:37], s[6:7], 0.5 op_sel_hi:[1,0,0]
	v_pk_fma_f32 v[22:23], v[22:23], s[6:7], 0.5 op_sel_hi:[1,0,0]
	v_cvt_u32_f32_sdwa v24, v24 dst_sel:WORD_1 dst_unused:UNUSED_PAD src0_sel:DWORD
	v_cvt_u32_f32_sdwa v25, v25 dst_sel:WORD_1 dst_unused:UNUSED_PAD src0_sel:DWORD
	v_cvt_u32_f32_sdwa v22, v22 dst_sel:BYTE_3 dst_unused:UNUSED_PAD src0_sel:DWORD
	v_cvt_u32_f32_sdwa v23, v23 dst_sel:BYTE_3 dst_unused:UNUSED_PAD src0_sel:DWORD
	v_or_b32_e32 v24, v26, v24
	v_ashrrev_i32_e32 v35, 31, v34
	v_or_b32_e32 v16, v16, v25
	v_or_b32_e32 v22, v24, v22
	v_lshlrev_b64 v[24:25], 5, v[34:35]
	v_or_b32_e32 v23, v16, v23
	v_lshl_add_u64 v[24:25], v[76:77], 0, v[24:25]
	global_store_dwordx2 v[24:25], v[22:23], off

; DI float sigmoidf_(float x) { return __builtin_amdgcn_rcpf(1.f + __expf(-x)); }
;   template <int GRP>
;   DI void run(const f32x4 (&acc)[2][2][4][2], const pg8::Unit& u, int wr, int wc, int fr, int fq) const {
;     ...
;             if (act == 2) {
;               u32x2v g8;
; #pragma unroll
;               for (int n = 0; n < 2; ++n) {
;                 const f32x4 v = acc[ai][bj][m][n] + bp[n];
;                 unsigned q = 0u;
; #pragma unroll
;                 for (int j = 0; j < 4; ++j) q |= ((unsigned)(sigmoidf_(v[j]) * 255.f + 0.5f)) << (8 * j);
;                 if (n == 0) g8.x = q; else g8.y = q;
;               }
;               *reinterpret_cast<u32x2v*>(reinterpret_cast<unsigned char*>(ws + off) + (size_t)row * 1024 + c0 + 32 * wc + 8 * fq) = g8;
.LBB0_1704:
	s_and_b64 vcc, exec, s[6:7]
	s_cbranch_vccz .LBB0_1706
	s_waitcnt lgkmcnt(0)
	v_add_f32_e32 v12, v12, v22
	v_mul_f32_e32 v12, 0xbfb8aa3b, v12
	v_exp_f32_e32 v12, v12
	v_add_f32_e32 v13, v13, v23
	v_mul_f32_e32 v13, 0xbfb8aa3b, v13
	v_exp_f32_e32 v13, v13
	v_add_f32_e32 v12, 1.0, v12
	v_rcp_f32_e32 v22, v12
	v_add_f32_e32 v12, v14, v24
	v_mul_f32_e32 v12, 0xbfb8aa3b, v12
	v_exp_f32_e32 v23, v12
	v_add_f32_e32 v12, v15, v25
	v_mul_f32_e32 v12, 0xbfb8aa3b, v12
	v_add_f32_e32 v16, 1.0, v13
	v_exp_f32_e32 v25, v12
	ds_read_b128 v[12:15], v90 offset:16
	v_rcp_f32_e32 v24, v16
	v_add_f32_e32 v16, 1.0, v23
	v_rcp_f32_e32 v28, v16
	v_add_f32_e32 v16, 1.0, v25
	s_waitcnt lgkmcnt(0)
	v_add_f32_e32 v8, v8, v12
	v_mul_f32_e32 v8, 0xbfb8aa3b, v8
	v_exp_f32_e32 v12, v8
	v_add_f32_e32 v8, v9, v13
	v_mul_f32_e32 v8, 0xbfb8aa3b, v8
	v_exp_f32_e32 v9, v8
	v_add_f32_e32 v10, v10, v14
	v_mul_f32_e32 v10, 0xbfb8aa3b, v10
	v_add_f32_e32 v11, v11, v15
	v_add_f32_e32 v9, 1.0, v9
	v_add_f32_e32 v12, 1.0, v12
	v_exp_f32_e32 v10, v10
	v_mul_f32_e32 v11, 0xbfb8aa3b, v11
	v_rcp_f32_e32 v25, v9
	v_rcp_f32_e32 v23, v12
	v_exp_f32_e32 v11, v11
	s_mov_b32 s6, 0x437f0000
	v_add_f32_e32 v9, 1.0, v10
	v_pk_fma_f32 v[12:13], v[24:25], s[6:7], 0.5 op_sel_hi:[1,0,0]
	v_rcp_f32_e32 v29, v9
	v_add_f32_e32 v9, 1.0, v11
	v_pk_fma_f32 v[10:11], v[22:23], s[6:7], 0.5 op_sel_hi:[1,0,0]
	v_cvt_u32_f32_e32 v13, v13
	v_cvt_u32_f32_e32 v12, v12
	v_cvt_u32_f32_e32 v11, v11
	v_cvt_u32_f32_e32 v10, v10
	v_rcp_f32_e32 v8, v16
	v_rcp_f32_e32 v9, v9
	v_lshlrev_b32_e32 v13, 8, v13
	v_lshlrev_b32_e32 v12, 8, v12
	v_or_b32_e32 v13, v13, v11
	v_or_b32_e32 v12, v12, v10
	v_pk_fma_f32 v[10:11], v[28:29], s[6:7], 0.5 op_sel_hi:[1,0,0]
	v_pk_fma_f32 v[8:9], v[8:9], s[6:7], 0.5 op_sel_hi:[1,0,0]
	v_cvt_u32_f32_sdwa v10, v10 dst_sel:WORD_1 dst_unused:UNUSED_PAD src0_sel:DWORD
	v_cvt_u32_f32_sdwa v11, v11 dst_sel:WORD_1 dst_unused:UNUSED_PAD src0_sel:DWORD
	v_cvt_u32_f32_sdwa v9, v9 dst_sel:BYTE_3 dst_unused:UNUSED_PAD src0_sel:DWORD
	v_cvt_u32_f32_sdwa v8, v8 dst_sel:BYTE_3 dst_unused:UNUSED_PAD src0_sel:DWORD
	v_or_b32_e32 v10, v12, v10
	v_or_b32_e32 v11, v13, v11
	v_ashrrev_i32_e32 v27, 31, v26
	v_or_b32_e32 v9, v11, v9
	v_or_b32_e32 v8, v10, v8
	v_lshlrev_b64 v[10:11], 5, v[26:27]
	v_lshl_add_u64 v[10:11], v[76:77], 0, v[10:11]
	global_store_dwordx2 v[10:11], v[8:9], off

; DI float sigmoidf_(float x) { return __builtin_amdgcn_rcpf(1.f + __expf(-x)); }
;   template <int GRP>
;   DI void run(const f32x4 (&acc)[2][2][4][2], const pg8::Unit& u, int wr, int wc, int fr, int fq) const {
;     ...
;             if (act == 2) {
;               u32x2v g8;
; #pragma unroll
;               for (int n = 0; n < 2; ++n) {
;                 const f32x4 v = acc[ai][bj][m][n] + bp[n];
;                 unsigned q = 0u;
; #pragma unroll
;                 for (int j = 0; j < 4; ++j) q |= ((unsigned)(sigmoidf_(v[j]) * 255.f + 0.5f)) << (8 * j);
;                 if (n == 0) g8.x = q; else g8.y = q;
;               }
;               *reinterpret_cast<u32x2v*>(reinterpret_cast<unsigned char*>(ws + off) + (size_t)row * 1024 + c0 + 32 * wc + 8 * fq) = g8;
.LBB0_1712:
	s_and_b64 vcc, exec, s[4:5]
	s_cbranch_vccz .LBB0_122
	s_waitcnt lgkmcnt(0)
	v_add_f32_e32 v4, v4, v8
	v_mul_f32_e32 v4, 0xbfb8aa3b, v4
	v_exp_f32_e32 v4, v4
	v_add_f32_e32 v5, v5, v9
	v_mul_f32_e32 v5, 0xbfb8aa3b, v5
	v_exp_f32_e32 v5, v5
	v_add_f32_e32 v4, 1.0, v4
	v_rcp_f32_e32 v8, v4
	v_add_f32_e32 v4, v6, v10
	v_mul_f32_e32 v4, 0xbfb8aa3b, v4
	v_exp_f32_e32 v13, v4
	v_add_f32_e32 v4, v7, v11
	v_mul_f32_e32 v4, 0xbfb8aa3b, v4
	v_add_f32_e32 v9, 1.0, v5
	v_exp_f32_e32 v11, v4
	ds_read_b128 v[4:7], v90 offset:16
	v_rcp_f32_e32 v10, v9
	v_add_f32_e32 v9, 1.0, v13
	v_rcp_f32_e32 v14, v9
	v_add_f32_e32 v9, 1.0, v11
	s_waitcnt lgkmcnt(0)
	v_add_f32_e32 v0, v0, v4
	v_mul_f32_e32 v0, 0xbfb8aa3b, v0
	v_exp_f32_e32 v4, v0
	v_add_f32_e32 v0, v1, v5
	v_mul_f32_e32 v0, 0xbfb8aa3b, v0
	v_exp_f32_e32 v1, v0
	v_add_f32_e32 v2, v2, v6
	v_mul_f32_e32 v2, 0xbfb8aa3b, v2
	v_add_f32_e32 v3, v3, v7
	v_add_f32_e32 v1, 1.0, v1
	v_add_f32_e32 v4, 1.0, v4
	v_exp_f32_e32 v2, v2
	v_mul_f32_e32 v3, 0xbfb8aa3b, v3
	v_rcp_f32_e32 v11, v1
	v_rcp_f32_e32 v0, v9
	v_rcp_f32_e32 v9, v4
	v_exp_f32_e32 v3, v3
	s_mov_b32 s2, 0x437f0000
	v_add_f32_e32 v1, 1.0, v2
	v_pk_fma_f32 v[4:5], v[10:11], s[2:3], 0.5 op_sel_hi:[1,0,0]
	v_rcp_f32_e32 v15, v1
	v_add_f32_e32 v1, 1.0, v3
	v_pk_fma_f32 v[2:3], v[8:9], s[2:3], 0.5 op_sel_hi:[1,0,0]
	v_cvt_u32_f32_e32 v5, v5
	v_cvt_u32_f32_e32 v4, v4
	v_cvt_u32_f32_e32 v3, v3
	v_cvt_u32_f32_e32 v2, v2
	v_rcp_f32_e32 v1, v1
	v_lshlrev_b32_e32 v5, 8, v5
	v_lshlrev_b32_e32 v4, 8, v4
	v_or_b32_e32 v5, v5, v3
	v_or_b32_e32 v4, v4, v2
	v_pk_fma_f32 v[2:3], v[14:15], s[2:3], 0.5 op_sel_hi:[1,0,0]
	v_pk_fma_f32 v[0:1], v[0:1], s[2:3], 0.5 op_sel_hi:[1,0,0]
	v_cvt_u32_f32_sdwa v2, v2 dst_sel:WORD_1 dst_unused:UNUSED_PAD src0_sel:DWORD
	v_cvt_u32_f32_sdwa v3, v3 dst_sel:WORD_1 dst_unused:UNUSED_PAD src0_sel:DWORD
	v_cvt_u32_f32_sdwa v1, v1 dst_sel:BYTE_3 dst_unused:UNUSED_PAD src0_sel:DWORD
	v_cvt_u32_f32_sdwa v0, v0 dst_sel:BYTE_3 dst_unused:UNUSED_PAD src0_sel:DWORD
	v_or_b32_e32 v2, v4, v2
	v_or_b32_e32 v3, v5, v3
	v_ashrrev_i32_e32 v13, 31, v12
	v_or_b32_e32 v1, v3, v1
	v_or_b32_e32 v0, v2, v0
	v_lshlrev_b64 v[2:3], 5, v[12:13]
	v_lshl_add_u64 v[2:3], v[76:77], 0, v[2:3]
	global_store_dwordx2 v[2:3], v[0:1], off
	s_branch .LBB0_122

; DI bf16x4 pack4(float a, float b, float c, float d) { u32x2v u; u.x = pk2(a, b); u.y = pk2(c, d); return __builtin_bit_cast(bf16x4, u); }
;   DI void operator()(const f32x4 (&acc)[2][2][4][2], const pg8::Unit& u, int wr, int wc, int fr, int fq) const {
;     bf16_t* MERGED = (reinterpret_cast<bf16_t*>(p.ws + OFF_GA));
; #pragma unroll
;     for (int ai = 0; ai < 2; ++ai)
; #pragma unroll
;       for (int m = 0; m < 4; ++m) {
;         const int row = u.pm * 256 + 128 * ai + 64 * wr + 16 * m + fr;
; #pragma unroll
;         for (int bj = 0; bj < 2; ++bj)
; #pragma unroll
;           for (int n = 0; n < 2; ++n) {
;             const size_t idx = (size_t)row * 1024 + u.pn * 256 + 128 * bj + 32 * wc + 16 * n + 4 * fq;
;             const f32x4 a = acc[ai][bj][m][n];
;             if (MODE == 0) {
;               const unsigned g = *reinterpret_cast<const unsigned*>(reinterpret_cast<const unsigned char*>(p.ws + OFF_RB) + idx);
;               const float k = 1.f / 255.f;
;               st4(MERGED + idx, pack4((float)(g & 255u) * k * a[0], (float)((g >> 8) & 255u) * k * a[1], (float)((g >> 16) & 255u) * k * a[2], (float)(g >> 24) * k * a[3]));
.LBB0_2731:
	v_lshl_or_b32 v16, v148, 10, v138
	v_readlane_b32 s12, v250, 30
	v_readlane_b32 s13, v250, 31
	s_or_b32 s56, s29, s10
	s_mov_b32 s14, 0x3b808081
	v_or_b32_e32 v16, s56, v16
	v_lshlrev_b32_e32 v18, 1, v16
	v_lshlrev_b32_e32 v19, 1, v138
	v_lshl_add_u32 v19, v148, 5, v19
	s_lshr_b32 s56, s56, 5
	s_mul_i32 s56, s56, 0x204000
	s_add_u32 s64, s48, s56
	s_addc_u32 s65, s49, 0
	s_add_u32 s66, s64, 0
	s_addc_u32 s67, s65, 0
	s_add_u32 s68, s64, 0x1000
	s_addc_u32 s69, s65, 0
	s_add_u32 s70, s64, 0x810000
	s_addc_u32 s71, s65, 0
	s_add_u32 s72, s64, 0x811000
	s_addc_u32 s73, s65, 0
	global_load_dwordx2 v[204:205], v19, s[66:67]
	global_load_dwordx2 v[206:207], v19, s[70:71]
	global_load_dwordx2 v[208:209], v19, s[66:67] offset:512
	global_load_dwordx2 v[210:211], v19, s[70:71] offset:512
	global_load_dwordx2 v[212:213], v19, s[66:67] offset:1024
	global_load_dwordx2 v[214:215], v19, s[70:71] offset:1024
	global_load_dwordx2 v[216:217], v19, s[66:67] offset:1536
	global_load_dwordx2 v[218:219], v19, s[70:71] offset:1536
	global_load_dwordx2 v[220:221], v19, s[68:69]
	global_load_dwordx2 v[222:223], v19, s[72:73]
	global_load_dwordx2 v[224:225], v19, s[68:69] offset:512
	global_load_dwordx2 v[226:227], v19, s[72:73] offset:512
	global_load_dwordx2 v[228:229], v19, s[68:69] offset:1024
	global_load_dwordx2 v[230:231], v19, s[72:73] offset:1024
	global_load_dwordx2 v[232:233], v19, s[68:69] offset:1536
	global_load_dwordx2 v[234:235], v19, s[72:73] offset:1536
	s_add_u32 s60, s12, 0x0
	s_addc_u32 s61, s13, 0
	s_waitcnt vmcnt(15)
	v_permlane16_swap_b32_e32 v204, v205
	s_nop 1
	v_permlane32_swap_b32_e32 v204, v205
	v_cvt_f32_ubyte1_e32 v155, v204
	v_cvt_f32_ubyte0_e32 v154, v204
	v_cvt_f32_ubyte3_e32 v157, v204
	v_cvt_f32_ubyte2_e32 v156, v204
	v_pk_mul_f32 v[154:155], v[154:155], s[14:15] op_sel_hi:[1,0]
	v_pk_mul_f32 v[156:157], v[156:157], s[14:15] op_sel_hi:[1,0]
	v_pk_mul_f32 v[130:131], v[130:131], v[154:155]
	v_pk_mul_f32 v[132:133], v[132:133], v[156:157]
	v_cvt_pk_bf16_f32 v130, v130, v131
	v_cvt_pk_bf16_f32 v131, v132, v133
	global_store_dwordx2 v18, v[130:131], s[60:61]
	v_cvt_f32_ubyte1_e32 v155, v205
	v_cvt_f32_ubyte0_e32 v154, v205
	v_cvt_f32_ubyte3_e32 v157, v205
	v_cvt_f32_ubyte2_e32 v156, v205
	v_pk_mul_f32 v[154:155], v[154:155], s[14:15] op_sel_hi:[1,0]
	v_pk_mul_f32 v[156:157], v[156:157], s[14:15] op_sel_hi:[1,0]
	v_pk_mul_f32 v[126:127], v[126:127], v[154:155]
	v_pk_mul_f32 v[128:129], v[128:129], v[156:157]
	v_cvt_pk_bf16_f32 v126, v126, v127
	v_cvt_pk_bf16_f32 v127, v128, v129
	global_store_dwordx2 v18, v[126:127], s[60:61] offset:32
	s_waitcnt vmcnt(16)
	v_permlane16_swap_b32_e32 v206, v207
	s_nop 1
	v_permlane32_swap_b32_e32 v206, v207
	v_cvt_f32_ubyte1_e32 v155, v206
	v_cvt_f32_ubyte0_e32 v154, v206
	v_cvt_f32_ubyte3_e32 v157, v206
	v_cvt_f32_ubyte2_e32 v156, v206
	v_pk_mul_f32 v[154:155], v[154:155], s[14:15] op_sel_hi:[1,0]
	v_pk_mul_f32 v[156:157], v[156:157], s[14:15] op_sel_hi:[1,0]
	v_pk_mul_f32 v[122:123], v[122:123], v[154:155]
	v_pk_mul_f32 v[124:125], v[124:125], v[156:157]
	v_cvt_pk_bf16_f32 v122, v122, v123
	v_cvt_pk_bf16_f32 v123, v124, v125
	global_store_dwordx2 v18, v[122:123], s[60:61] offset:256
	v_cvt_f32_ubyte1_e32 v155, v207
	v_cvt_f32_ubyte0_e32 v154, v207
	v_cvt_f32_ubyte3_e32 v157, v207
	v_cvt_f32_ubyte2_e32 v156, v207
	v_pk_mul_f32 v[154:155], v[154:155], s[14:15] op_sel_hi:[1,0]
	v_pk_mul_f32 v[156:157], v[156:157], s[14:15] op_sel_hi:[1,0]
	v_pk_mul_f32 v[118:119], v[118:119], v[154:155]
	v_pk_mul_f32 v[120:121], v[120:121], v[156:157]
	v_cvt_pk_bf16_f32 v118, v118, v119
	v_cvt_pk_bf16_f32 v119, v120, v121
	global_store_dwordx2 v18, v[118:119], s[60:61] offset:288
	s_add_u32 s62, s12, 0x8000
	s_addc_u32 s63, s13, 0
	s_waitcnt vmcnt(17)
	v_permlane16_swap_b32_e32 v208, v209
	s_nop 1
	v_permlane32_swap_b32_e32 v208, v209
	v_cvt_f32_ubyte1_e32 v155, v208
	v_cvt_f32_ubyte0_e32 v154, v208
	v_cvt_f32_ubyte3_e32 v157, v208
	v_cvt_f32_ubyte2_e32 v156, v208
	v_pk_mul_f32 v[154:155], v[154:155], s[14:15] op_sel_hi:[1,0]
	v_pk_mul_f32 v[156:157], v[156:157], s[14:15] op_sel_hi:[1,0]
	v_pk_mul_f32 v[114:115], v[114:115], v[154:155]
	v_pk_mul_f32 v[116:117], v[116:117], v[156:157]
	v_cvt_pk_bf16_f32 v114, v114, v115
	v_cvt_pk_bf16_f32 v115, v116, v117
	global_store_dwordx2 v18, v[114:115], s[62:63]
	v_cvt_f32_ubyte1_e32 v155, v209
	v_cvt_f32_ubyte0_e32 v154, v209
	v_cvt_f32_ubyte3_e32 v157, v209
	v_cvt_f32_ubyte2_e32 v156, v209
	v_pk_mul_f32 v[154:155], v[154:155], s[14:15] op_sel_hi:[1,0]
	v_pk_mul_f32 v[156:157], v[156:157], s[14:15] op_sel_hi:[1,0]
	v_pk_mul_f32 v[110:111], v[110:111], v[154:155]
	v_pk_mul_f32 v[112:113], v[112:113], v[156:157]
	v_cvt_pk_bf16_f32 v110, v110, v111
	v_cvt_pk_bf16_f32 v111, v112, v113
	global_store_dwordx2 v18, v[110:111], s[62:63] offset:32
	s_waitcnt vmcnt(18)
	v_permlane16_swap_b32_e32 v210, v211
	s_nop 1
	v_permlane32_swap_b32_e32 v210, v211
	v_cvt_f32_ubyte1_e32 v155, v210
	v_cvt_f32_ubyte0_e32 v154, v210
	v_cvt_f32_ubyte3_e32 v157, v210
	v_cvt_f32_ubyte2_e32 v156, v210
	v_pk_mul_f32 v[154:155], v[154:155], s[14:15] op_sel_hi:[1,0]
	v_pk_mul_f32 v[156:157], v[156:157], s[14:15] op_sel_hi:[1,0]
	v_pk_mul_f32 v[106:107], v[106:107], v[154:155]
	v_pk_mul_f32 v[108:109], v[108:109], v[156:157]
	v_cvt_pk_bf16_f32 v106, v106, v107
	v_cvt_pk_bf16_f32 v107, v108, v109
	global_store_dwordx2 v18, v[106:107], s[62:63] offset:256
	v_cvt_f32_ubyte1_e32 v155, v211
	v_cvt_f32_ubyte0_e32 v154, v211
	v_cvt_f32_ubyte3_e32 v157, v211
	v_cvt_f32_ubyte2_e32 v156, v211
	v_pk_mul_f32 v[154:155], v[154:155], s[14:15] op_sel_hi:[1,0]
	v_pk_mul_f32 v[156:157], v[156:157], s[14:15] op_sel_hi:[1,0]
	v_pk_mul_f32 v[102:103], v[102:103], v[154:155]
	v_pk_mul_f32 v[104:105], v[104:105], v[156:157]
	v_cvt_pk_bf16_f32 v102, v102, v103
	v_cvt_pk_bf16_f32 v103, v104, v105
	global_store_dwordx2 v18, v[102:103], s[62:63] offset:288
	s_add_u32 s60, s12, 0x10000
	s_addc_u32 s61, s13, 0
	s_waitcnt vmcnt(19)
; DI bf16x4 pack4(float a, float b, float c, float d) { u32x2v u; u.x = pk2(a, b); u.y = pk2(c, d); return __builtin_bit_cast(bf16x4, u); }
;   DI void operator()(const f32x4 (&acc)[2][2][4][2], const pg8::Unit& u, int wr, int wc, int fr, int fq) const {
;     bf16_t* MERGED = (reinterpret_cast<bf16_t*>(p.ws + OFF_GA));
; #pragma unroll
;     for (int ai = 0; ai < 2; ++ai)
; #pragma unroll
;       for (int m = 0; m < 4; ++m) {
;         const int row = u.pm * 256 + 128 * ai + 64 * wr + 16 * m + fr;
; #pragma unroll
;         for (int bj = 0; bj < 2; ++bj)
; #pragma unroll
;           for (int n = 0; n < 2; ++n) {
;             const size_t idx = (size_t)row * 1024 + u.pn * 256 + 128 * bj + 32 * wc + 16 * n + 4 * fq;
;             const f32x4 a = acc[ai][bj][m][n];
;             if (MODE == 0) {
;               const unsigned g = *reinterpret_cast<const unsigned*>(reinterpret_cast<const unsigned char*>(p.ws + OFF_RB) + idx);
;               const float k = 1.f / 255.f;
;               st4(MERGED + idx, pack4((float)(g & 255u) * k * a[0], (float)((g >> 8) & 255u) * k * a[1], (float)((g >> 16) & 255u) * k * a[2], (float)(g >> 24) * k * a[3]));
	v_permlane16_swap_b32_e32 v212, v213
	s_nop 1
	v_permlane32_swap_b32_e32 v212, v213
	v_cvt_f32_ubyte1_e32 v155, v212
	v_cvt_f32_ubyte0_e32 v154, v212
	v_cvt_f32_ubyte3_e32 v157, v212
	v_cvt_f32_ubyte2_e32 v156, v212
	v_pk_mul_f32 v[154:155], v[154:155], s[14:15] op_sel_hi:[1,0]
	v_pk_mul_f32 v[156:157], v[156:157], s[14:15] op_sel_hi:[1,0]
	v_pk_mul_f32 v[98:99], v[98:99], v[154:155]
	v_pk_mul_f32 v[100:101], v[100:101], v[156:157]
	v_cvt_pk_bf16_f32 v98, v98, v99
	v_cvt_pk_bf16_f32 v99, v100, v101
	global_store_dwordx2 v18, v[98:99], s[60:61]
	v_cvt_f32_ubyte1_e32 v155, v213
	v_cvt_f32_ubyte0_e32 v154, v213
	v_cvt_f32_ubyte3_e32 v157, v213
	v_cvt_f32_ubyte2_e32 v156, v213
	v_pk_mul_f32 v[154:155], v[154:155], s[14:15] op_sel_hi:[1,0]
	v_pk_mul_f32 v[156:157], v[156:157], s[14:15] op_sel_hi:[1,0]
	v_pk_mul_f32 v[94:95], v[94:95], v[154:155]
	v_pk_mul_f32 v[96:97], v[96:97], v[156:157]
	v_cvt_pk_bf16_f32 v94, v94, v95
	v_cvt_pk_bf16_f32 v95, v96, v97
	global_store_dwordx2 v18, v[94:95], s[60:61] offset:32
	s_waitcnt vmcnt(20)
	v_permlane16_swap_b32_e32 v214, v215
	s_nop 1
	v_permlane32_swap_b32_e32 v214, v215
	v_cvt_f32_ubyte1_e32 v155, v214
	v_cvt_f32_ubyte0_e32 v154, v214
	v_cvt_f32_ubyte3_e32 v157, v214
	v_cvt_f32_ubyte2_e32 v156, v214
	v_pk_mul_f32 v[154:155], v[154:155], s[14:15] op_sel_hi:[1,0]
	v_pk_mul_f32 v[156:157], v[156:157], s[14:15] op_sel_hi:[1,0]
	v_pk_mul_f32 v[90:91], v[90:91], v[154:155]
	v_pk_mul_f32 v[92:93], v[92:93], v[156:157]
	v_cvt_pk_bf16_f32 v90, v90, v91
	v_cvt_pk_bf16_f32 v91, v92, v93
	global_store_dwordx2 v18, v[90:91], s[60:61] offset:256
	v_cvt_f32_ubyte1_e32 v155, v215
	v_cvt_f32_ubyte0_e32 v154, v215
	v_cvt_f32_ubyte3_e32 v157, v215
	v_cvt_f32_ubyte2_e32 v156, v215
	v_pk_mul_f32 v[154:155], v[154:155], s[14:15] op_sel_hi:[1,0]
	v_pk_mul_f32 v[156:157], v[156:157], s[14:15] op_sel_hi:[1,0]
	v_pk_mul_f32 v[86:87], v[86:87], v[154:155]
	v_pk_mul_f32 v[88:89], v[88:89], v[156:157]
	v_cvt_pk_bf16_f32 v86, v86, v87
	v_cvt_pk_bf16_f32 v87, v88, v89
	global_store_dwordx2 v18, v[86:87], s[60:61] offset:288
	s_add_u32 s62, s12, 0x18000
	s_addc_u32 s63, s13, 0
	s_waitcnt vmcnt(21)
	v_permlane16_swap_b32_e32 v216, v217
	s_nop 1
	v_permlane32_swap_b32_e32 v216, v217
	v_cvt_f32_ubyte1_e32 v155, v216
	v_cvt_f32_ubyte0_e32 v154, v216
	v_cvt_f32_ubyte3_e32 v157, v216
	v_cvt_f32_ubyte2_e32 v156, v216
	v_pk_mul_f32 v[154:155], v[154:155], s[14:15] op_sel_hi:[1,0]
	v_pk_mul_f32 v[156:157], v[156:157], s[14:15] op_sel_hi:[1,0]
	v_pk_mul_f32 v[82:83], v[82:83], v[154:155]
	v_pk_mul_f32 v[84:85], v[84:85], v[156:157]
	v_cvt_pk_bf16_f32 v82, v82, v83
	v_cvt_pk_bf16_f32 v83, v84, v85
	global_store_dwordx2 v18, v[82:83], s[62:63]
	v_cvt_f32_ubyte1_e32 v155, v217
	v_cvt_f32_ubyte0_e32 v154, v217
	v_cvt_f32_ubyte3_e32 v157, v217
	v_cvt_f32_ubyte2_e32 v156, v217
	v_pk_mul_f32 v[154:155], v[154:155], s[14:15] op_sel_hi:[1,0]
	v_pk_mul_f32 v[156:157], v[156:157], s[14:15] op_sel_hi:[1,0]
	v_pk_mul_f32 v[78:79], v[78:79], v[154:155]
	v_pk_mul_f32 v[80:81], v[80:81], v[156:157]
	v_cvt_pk_bf16_f32 v78, v78, v79
	v_cvt_pk_bf16_f32 v79, v80, v81
	global_store_dwordx2 v18, v[78:79], s[62:63] offset:32
	s_waitcnt vmcnt(22)
	v_permlane16_swap_b32_e32 v218, v219
	s_nop 1
	v_permlane32_swap_b32_e32 v218, v219
	v_cvt_f32_ubyte1_e32 v155, v218
	v_cvt_f32_ubyte0_e32 v154, v218
	v_cvt_f32_ubyte3_e32 v157, v218
	v_cvt_f32_ubyte2_e32 v156, v218
	v_pk_mul_f32 v[154:155], v[154:155], s[14:15] op_sel_hi:[1,0]
	v_pk_mul_f32 v[156:157], v[156:157], s[14:15] op_sel_hi:[1,0]
	v_pk_mul_f32 v[74:75], v[74:75], v[154:155]
	v_pk_mul_f32 v[76:77], v[76:77], v[156:157]
	v_cvt_pk_bf16_f32 v74, v74, v75
	v_cvt_pk_bf16_f32 v75, v76, v77
	global_store_dwordx2 v18, v[74:75], s[62:63] offset:256
	v_cvt_f32_ubyte1_e32 v155, v219
	v_cvt_f32_ubyte0_e32 v154, v219
	v_cvt_f32_ubyte3_e32 v157, v219
	v_cvt_f32_ubyte2_e32 v156, v219
	v_pk_mul_f32 v[154:155], v[154:155], s[14:15] op_sel_hi:[1,0]
	v_pk_mul_f32 v[156:157], v[156:157], s[14:15] op_sel_hi:[1,0]
	v_pk_mul_f32 v[70:71], v[70:71], v[154:155]
	v_pk_mul_f32 v[72:73], v[72:73], v[156:157]
	v_cvt_pk_bf16_f32 v70, v70, v71
	v_cvt_pk_bf16_f32 v71, v72, v73
	global_store_dwordx2 v18, v[70:71], s[62:63] offset:288
	s_add_u32 s60, s12, 0x40000
	s_addc_u32 s61, s13, 0
	s_waitcnt vmcnt(23)
	v_permlane16_swap_b32_e32 v220, v221
	s_nop 1
	v_permlane32_swap_b32_e32 v220, v221
	v_cvt_f32_ubyte1_e32 v155, v220
	v_cvt_f32_ubyte0_e32 v154, v220
	v_cvt_f32_ubyte3_e32 v157, v220
	v_cvt_f32_ubyte2_e32 v156, v220
	v_pk_mul_f32 v[154:155], v[154:155], s[14:15] op_sel_hi:[1,0]
	v_pk_mul_f32 v[156:157], v[156:157], s[14:15] op_sel_hi:[1,0]
	v_pk_mul_f32 v[66:67], v[66:67], v[154:155]
	v_pk_mul_f32 v[68:69], v[68:69], v[156:157]
	v_cvt_pk_bf16_f32 v66, v66, v67
	v_cvt_pk_bf16_f32 v67, v68, v69
	global_store_dwordx2 v18, v[66:67], s[60:61]
	v_cvt_f32_ubyte1_e32 v155, v221
	v_cvt_f32_ubyte0_e32 v154, v221
	v_cvt_f32_ubyte3_e32 v157, v221
	v_cvt_f32_ubyte2_e32 v156, v221
	v_pk_mul_f32 v[154:155], v[154:155], s[14:15] op_sel_hi:[1,0]
	v_pk_mul_f32 v[156:157], v[156:157], s[14:15] op_sel_hi:[1,0]
	v_pk_mul_f32 v[62:63], v[62:63], v[154:155]
	v_pk_mul_f32 v[64:65], v[64:65], v[156:157]
	v_cvt_pk_bf16_f32 v62, v62, v63
	v_cvt_pk_bf16_f32 v63, v64, v65
	global_store_dwordx2 v18, v[62:63], s[60:61] offset:32
	s_waitcnt vmcnt(24)
; DI bf16x4 pack4(float a, float b, float c, float d) { u32x2v u; u.x = pk2(a, b); u.y = pk2(c, d); return __builtin_bit_cast(bf16x4, u); }
;   DI void operator()(const f32x4 (&acc)[2][2][4][2], const pg8::Unit& u, int wr, int wc, int fr, int fq) const {
;     bf16_t* MERGED = (reinterpret_cast<bf16_t*>(p.ws + OFF_GA));
; #pragma unroll
;     for (int ai = 0; ai < 2; ++ai)
; #pragma unroll
;       for (int m = 0; m < 4; ++m) {
;         const int row = u.pm * 256 + 128 * ai + 64 * wr + 16 * m + fr;
; #pragma unroll
;         for (int bj = 0; bj < 2; ++bj)
; #pragma unroll
;           for (int n = 0; n < 2; ++n) {
;             const size_t idx = (size_t)row * 1024 + u.pn * 256 + 128 * bj + 32 * wc + 16 * n + 4 * fq;
;             const f32x4 a = acc[ai][bj][m][n];
;             if (MODE == 0) {
;               const unsigned g = *reinterpret_cast<const unsigned*>(reinterpret_cast<const unsigned char*>(p.ws + OFF_RB) + idx);
;               const float k = 1.f / 255.f;
;               st4(MERGED + idx, pack4((float)(g & 255u) * k * a[0], (float)((g >> 8) & 255u) * k * a[1], (float)((g >> 16) & 255u) * k * a[2], (float)(g >> 24) * k * a[3]));
	v_permlane16_swap_b32_e32 v222, v223
	s_nop 1
	v_permlane32_swap_b32_e32 v222, v223
	v_cvt_f32_ubyte1_e32 v155, v222
	v_cvt_f32_ubyte0_e32 v154, v222
	v_cvt_f32_ubyte3_e32 v157, v222
	v_cvt_f32_ubyte2_e32 v156, v222
	v_pk_mul_f32 v[154:155], v[154:155], s[14:15] op_sel_hi:[1,0]
	v_pk_mul_f32 v[156:157], v[156:157], s[14:15] op_sel_hi:[1,0]
	v_pk_mul_f32 v[58:59], v[58:59], v[154:155]
	v_pk_mul_f32 v[60:61], v[60:61], v[156:157]
	v_cvt_pk_bf16_f32 v58, v58, v59
	v_cvt_pk_bf16_f32 v59, v60, v61
	global_store_dwordx2 v18, v[58:59], s[60:61] offset:256
	v_cvt_f32_ubyte1_e32 v155, v223
	v_cvt_f32_ubyte0_e32 v154, v223
	v_cvt_f32_ubyte3_e32 v157, v223
	v_cvt_f32_ubyte2_e32 v156, v223
	v_pk_mul_f32 v[154:155], v[154:155], s[14:15] op_sel_hi:[1,0]
	v_pk_mul_f32 v[156:157], v[156:157], s[14:15] op_sel_hi:[1,0]
	v_pk_mul_f32 v[54:55], v[54:55], v[154:155]
	v_pk_mul_f32 v[56:57], v[56:57], v[156:157]
	v_cvt_pk_bf16_f32 v54, v54, v55
	v_cvt_pk_bf16_f32 v55, v56, v57
	global_store_dwordx2 v18, v[54:55], s[60:61] offset:288
	s_add_u32 s62, s12, 0x48000
	s_addc_u32 s63, s13, 0
	s_waitcnt vmcnt(25)
	v_permlane16_swap_b32_e32 v224, v225
	s_nop 1
	v_permlane32_swap_b32_e32 v224, v225
	v_cvt_f32_ubyte1_e32 v155, v224
	v_cvt_f32_ubyte0_e32 v154, v224
	v_cvt_f32_ubyte3_e32 v157, v224
	v_cvt_f32_ubyte2_e32 v156, v224
	v_pk_mul_f32 v[154:155], v[154:155], s[14:15] op_sel_hi:[1,0]
	v_pk_mul_f32 v[156:157], v[156:157], s[14:15] op_sel_hi:[1,0]
	v_pk_mul_f32 v[50:51], v[50:51], v[154:155]
	v_pk_mul_f32 v[52:53], v[52:53], v[156:157]
	v_cvt_pk_bf16_f32 v50, v50, v51
	v_cvt_pk_bf16_f32 v51, v52, v53
	global_store_dwordx2 v18, v[50:51], s[62:63]
	v_cvt_f32_ubyte1_e32 v155, v225
	v_cvt_f32_ubyte0_e32 v154, v225
	v_cvt_f32_ubyte3_e32 v157, v225
	v_cvt_f32_ubyte2_e32 v156, v225
	v_pk_mul_f32 v[154:155], v[154:155], s[14:15] op_sel_hi:[1,0]
	v_pk_mul_f32 v[156:157], v[156:157], s[14:15] op_sel_hi:[1,0]
	v_pk_mul_f32 v[46:47], v[46:47], v[154:155]
	v_pk_mul_f32 v[48:49], v[48:49], v[156:157]
	v_cvt_pk_bf16_f32 v46, v46, v47
	v_cvt_pk_bf16_f32 v47, v48, v49
	global_store_dwordx2 v18, v[46:47], s[62:63] offset:32
	s_waitcnt vmcnt(26)
	v_permlane16_swap_b32_e32 v226, v227
	s_nop 1
	v_permlane32_swap_b32_e32 v226, v227
	v_cvt_f32_ubyte1_e32 v155, v226
	v_cvt_f32_ubyte0_e32 v154, v226
	v_cvt_f32_ubyte3_e32 v157, v226
	v_cvt_f32_ubyte2_e32 v156, v226
	v_pk_mul_f32 v[154:155], v[154:155], s[14:15] op_sel_hi:[1,0]
	v_pk_mul_f32 v[156:157], v[156:157], s[14:15] op_sel_hi:[1,0]
	v_pk_mul_f32 v[42:43], v[42:43], v[154:155]
	v_pk_mul_f32 v[44:45], v[44:45], v[156:157]
	v_cvt_pk_bf16_f32 v42, v42, v43
	v_cvt_pk_bf16_f32 v43, v44, v45
	global_store_dwordx2 v18, v[42:43], s[62:63] offset:256
	v_cvt_f32_ubyte1_e32 v155, v227
	v_cvt_f32_ubyte0_e32 v154, v227
	v_cvt_f32_ubyte3_e32 v157, v227
	v_cvt_f32_ubyte2_e32 v156, v227
	v_pk_mul_f32 v[154:155], v[154:155], s[14:15] op_sel_hi:[1,0]
	v_pk_mul_f32 v[156:157], v[156:157], s[14:15] op_sel_hi:[1,0]
	v_pk_mul_f32 v[38:39], v[38:39], v[154:155]
	v_pk_mul_f32 v[40:41], v[40:41], v[156:157]
	v_cvt_pk_bf16_f32 v38, v38, v39
	v_cvt_pk_bf16_f32 v39, v40, v41
	global_store_dwordx2 v18, v[38:39], s[62:63] offset:288
	s_add_u32 s60, s12, 0x50000
	s_addc_u32 s61, s13, 0
	s_waitcnt vmcnt(27)
	v_permlane16_swap_b32_e32 v228, v229
	s_nop 1
	v_permlane32_swap_b32_e32 v228, v229
	v_cvt_f32_ubyte1_e32 v155, v228
	v_cvt_f32_ubyte0_e32 v154, v228
	v_cvt_f32_ubyte3_e32 v157, v228
	v_cvt_f32_ubyte2_e32 v156, v228
	v_pk_mul_f32 v[154:155], v[154:155], s[14:15] op_sel_hi:[1,0]
	v_pk_mul_f32 v[156:157], v[156:157], s[14:15] op_sel_hi:[1,0]
	v_pk_mul_f32 v[34:35], v[34:35], v[154:155]
	v_pk_mul_f32 v[36:37], v[36:37], v[156:157]
	v_cvt_pk_bf16_f32 v34, v34, v35
	v_cvt_pk_bf16_f32 v35, v36, v37
	global_store_dwordx2 v18, v[34:35], s[60:61]
	v_cvt_f32_ubyte1_e32 v155, v229
	v_cvt_f32_ubyte0_e32 v154, v229
	v_cvt_f32_ubyte3_e32 v157, v229
	v_cvt_f32_ubyte2_e32 v156, v229
	v_pk_mul_f32 v[154:155], v[154:155], s[14:15] op_sel_hi:[1,0]
	v_pk_mul_f32 v[156:157], v[156:157], s[14:15] op_sel_hi:[1,0]
	v_pk_mul_f32 v[30:31], v[30:31], v[154:155]
	v_pk_mul_f32 v[32:33], v[32:33], v[156:157]
	v_cvt_pk_bf16_f32 v30, v30, v31
	v_cvt_pk_bf16_f32 v31, v32, v33
	global_store_dwordx2 v18, v[30:31], s[60:61] offset:32
	s_waitcnt vmcnt(28)
; DI bf16x4 pack4(float a, float b, float c, float d) { u32x2v u; u.x = pk2(a, b); u.y = pk2(c, d); return __builtin_bit_cast(bf16x4, u); }
;   DI void operator()(const f32x4 (&acc)[2][2][4][2], const pg8::Unit& u, int wr, int wc, int fr, int fq) const {
;     bf16_t* MERGED = (reinterpret_cast<bf16_t*>(p.ws + OFF_GA));
; #pragma unroll
;     for (int ai = 0; ai < 2; ++ai)
; #pragma unroll
;       for (int m = 0; m < 4; ++m) {
;         const int row = u.pm * 256 + 128 * ai + 64 * wr + 16 * m + fr;
; #pragma unroll
;         for (int bj = 0; bj < 2; ++bj)
; #pragma unroll
;           for (int n = 0; n < 2; ++n) {
;             const size_t idx = (size_t)row * 1024 + u.pn * 256 + 128 * bj + 32 * wc + 16 * n + 4 * fq;
;             const f32x4 a = acc[ai][bj][m][n];
;             if (MODE == 0) {
;               const unsigned g = *reinterpret_cast<const unsigned*>(reinterpret_cast<const unsigned char*>(p.ws + OFF_RB) + idx);
;               const float k = 1.f / 255.f;
;               st4(MERGED + idx, pack4((float)(g & 255u) * k * a[0], (float)((g >> 8) & 255u) * k * a[1], (float)((g >> 16) & 255u) * k * a[2], (float)(g >> 24) * k * a[3]));
	v_permlane16_swap_b32_e32 v230, v231
	s_nop 1
	v_permlane32_swap_b32_e32 v230, v231
	v_cvt_f32_ubyte1_e32 v155, v230
	v_cvt_f32_ubyte0_e32 v154, v230
	v_cvt_f32_ubyte3_e32 v157, v230
	v_cvt_f32_ubyte2_e32 v156, v230
	v_pk_mul_f32 v[154:155], v[154:155], s[14:15] op_sel_hi:[1,0]
	v_pk_mul_f32 v[156:157], v[156:157], s[14:15] op_sel_hi:[1,0]
	v_pk_mul_f32 v[26:27], v[26:27], v[154:155]
	v_pk_mul_f32 v[28:29], v[28:29], v[156:157]
	v_cvt_pk_bf16_f32 v26, v26, v27
	v_cvt_pk_bf16_f32 v27, v28, v29
	global_store_dwordx2 v18, v[26:27], s[60:61] offset:256
	v_cvt_f32_ubyte1_e32 v155, v231
	v_cvt_f32_ubyte0_e32 v154, v231
	v_cvt_f32_ubyte3_e32 v157, v231
	v_cvt_f32_ubyte2_e32 v156, v231
	v_pk_mul_f32 v[154:155], v[154:155], s[14:15] op_sel_hi:[1,0]
	v_pk_mul_f32 v[156:157], v[156:157], s[14:15] op_sel_hi:[1,0]
	v_pk_mul_f32 v[22:23], v[22:23], v[154:155]
	v_pk_mul_f32 v[24:25], v[24:25], v[156:157]
	v_cvt_pk_bf16_f32 v22, v22, v23
	v_cvt_pk_bf16_f32 v23, v24, v25
	global_store_dwordx2 v18, v[22:23], s[60:61] offset:288
	s_add_u32 s62, s12, 0x58000
	s_addc_u32 s63, s13, 0
	s_waitcnt vmcnt(29)
	v_permlane16_swap_b32_e32 v232, v233
	s_nop 1
	v_permlane32_swap_b32_e32 v232, v233
	v_cvt_f32_ubyte1_e32 v155, v232
	v_cvt_f32_ubyte0_e32 v154, v232
	v_cvt_f32_ubyte3_e32 v157, v232
	v_cvt_f32_ubyte2_e32 v156, v232
	v_pk_mul_f32 v[154:155], v[154:155], s[14:15] op_sel_hi:[1,0]
	v_pk_mul_f32 v[156:157], v[156:157], s[14:15] op_sel_hi:[1,0]
	v_pk_mul_f32 v[12:13], v[12:13], v[154:155]
	v_pk_mul_f32 v[14:15], v[14:15], v[156:157]
	v_cvt_pk_bf16_f32 v12, v12, v13
	v_cvt_pk_bf16_f32 v13, v14, v15
	global_store_dwordx2 v18, v[12:13], s[62:63]
	v_cvt_f32_ubyte1_e32 v155, v233
	v_cvt_f32_ubyte0_e32 v154, v233
	v_cvt_f32_ubyte3_e32 v157, v233
	v_cvt_f32_ubyte2_e32 v156, v233
	v_pk_mul_f32 v[154:155], v[154:155], s[14:15] op_sel_hi:[1,0]
	v_pk_mul_f32 v[156:157], v[156:157], s[14:15] op_sel_hi:[1,0]
	v_pk_mul_f32 v[8:9], v[8:9], v[154:155]
	v_pk_mul_f32 v[10:11], v[10:11], v[156:157]
	v_cvt_pk_bf16_f32 v8, v8, v9
	v_cvt_pk_bf16_f32 v9, v10, v11
	global_store_dwordx2 v18, v[8:9], s[62:63] offset:32
	s_waitcnt vmcnt(30)
	v_permlane16_swap_b32_e32 v234, v235
	s_nop 1
	v_permlane32_swap_b32_e32 v234, v235
	v_cvt_f32_ubyte1_e32 v155, v234
	v_cvt_f32_ubyte0_e32 v154, v234
	v_cvt_f32_ubyte3_e32 v157, v234
	v_cvt_f32_ubyte2_e32 v156, v234
	v_pk_mul_f32 v[154:155], v[154:155], s[14:15] op_sel_hi:[1,0]
	v_pk_mul_f32 v[156:157], v[156:157], s[14:15] op_sel_hi:[1,0]
	v_pk_mul_f32 v[4:5], v[4:5], v[154:155]
	v_pk_mul_f32 v[6:7], v[6:7], v[156:157]
	v_cvt_pk_bf16_f32 v4, v4, v5
	v_cvt_pk_bf16_f32 v5, v6, v7
	global_store_dwordx2 v18, v[4:5], s[62:63] offset:256
	v_cvt_f32_ubyte1_e32 v155, v235
	v_cvt_f32_ubyte0_e32 v154, v235
	v_cvt_f32_ubyte3_e32 v157, v235
	v_cvt_f32_ubyte2_e32 v156, v235
	v_pk_mul_f32 v[154:155], v[154:155], s[14:15] op_sel_hi:[1,0]
	v_pk_mul_f32 v[156:157], v[156:157], s[14:15] op_sel_hi:[1,0]
	v_pk_mul_f32 v[0:1], v[0:1], v[154:155]
	v_pk_mul_f32 v[2:3], v[2:3], v[156:157]
	v_cvt_pk_bf16_f32 v0, v0, v1
	v_cvt_pk_bf16_f32 v1, v2, v3
	global_store_dwordx2 v18, v[0:1], s[62:63] offset:288
	s_mov_b32 s11, s2
	s_mov_b32 s10, s4
	s_mov_b64 s[12:13], s[6:7]
	s_mov_b64 s[14:15], s[8:9]
	s_and_b64 vcc, exec, s[0:1]
	s_cbranch_vccnz .LBB0_2738

;   DI void mid(f32x4 (&acc)[2][2][4][2], const pg8::Unit& u, int wr, int wc, int fr, int fq) const {
; #pragma unroll
;     for (int ai = 0; ai < 2; ++ai)
; #pragma unroll
;       for (int m = 0; m < 4; ++m) {
;         int row = u.pm * 256 + 128 * ai + 64 * wr + 16 * m + fr;
;         asm volatile("" : "+v"(row));
; #pragma unroll
;         for (int bj = 0; bj < 2; ++bj)
; #pragma unroll
;           for (int n = 0; n < 2; ++n) {
;             const size_t idx = (size_t)row * 1024 + u.pn * 256 + 128 * bj + 32 * wc + 16 * n + 4 * fq;
;             const unsigned ga = *reinterpret_cast<const unsigned*>(reinterpret_cast<const unsigned char*>(p.ws + OFF_RA) + idx);
;             const unsigned gb = *reinterpret_cast<const unsigned*>(reinterpret_cast<const unsigned char*>(p.ws + OFF_RB) + idx);
; #pragma unroll
;             for (int j = 0; j < 4; ++j) {
;               const unsigned a8 = (ga >> (8 * j)) & 255u, b8 = (gb >> (8 * j)) & 255u;
;               acc[ai][bj][m][n][j] *= (float)a8 * __builtin_amdgcn_rcpf((float)(b8 > 1u ? b8 : 1u));
;             }
;           }
.LBB0_2736:
	s_cmpk_lg_i32 s14, 0x400
	s_cbranch_scc1 .LBB0_2735
	v_lshlrev_b32_e32 v16, 1, v138
	v_lshl_add_u32 v16, v148, 5, v16
	s_or_b32 s56, s29, s10
	s_lshr_b32 s56, s56, 5
	s_mul_i32 s56, s56, 0x204000
	s_add_u32 s64, s46, s56
	s_addc_u32 s65, s47, 0
	s_add_u32 s74, s48, s56
	s_addc_u32 s75, s49, 0
	s_add_u32 s66, s64, 0
	s_addc_u32 s67, s65, 0
	s_add_u32 s68, s64, 0x1000
	s_addc_u32 s69, s65, 0
	s_add_u32 s70, s64, 0x810000
	s_addc_u32 s71, s65, 0
	s_add_u32 s72, s64, 0x811000
	s_addc_u32 s73, s65, 0
	s_add_u32 s76, s74, 0
	s_addc_u32 s77, s75, 0
	s_add_u32 s78, s74, 0x1000
	s_addc_u32 s79, s75, 0
	s_add_u32 s80, s74, 0x810000
	s_addc_u32 s81, s75, 0
	s_add_u32 s82, s74, 0x811000
	s_addc_u32 s83, s75, 0
	global_load_dwordx2 v[186:187], v16, s[66:67]
	global_load_dwordx2 v[188:189], v16, s[76:77]
	global_load_dwordx2 v[190:191], v16, s[70:71]
	global_load_dwordx2 v[192:193], v16, s[80:81]
	global_load_dwordx2 v[194:195], v16, s[66:67] offset:512
	global_load_dwordx2 v[196:197], v16, s[76:77] offset:512
	global_load_dwordx2 v[198:199], v16, s[70:71] offset:512
	global_load_dwordx2 v[200:201], v16, s[80:81] offset:512
	global_load_dwordx2 v[202:203], v16, s[66:67] offset:1024
	global_load_dwordx2 v[204:205], v16, s[76:77] offset:1024
	global_load_dwordx2 v[206:207], v16, s[70:71] offset:1024
	global_load_dwordx2 v[208:209], v16, s[80:81] offset:1024
	global_load_dwordx2 v[210:211], v16, s[66:67] offset:1536
	global_load_dwordx2 v[212:213], v16, s[76:77] offset:1536
	global_load_dwordx2 v[214:215], v16, s[70:71] offset:1536
	global_load_dwordx2 v[216:217], v16, s[80:81] offset:1536
	global_load_dwordx2 v[218:219], v16, s[68:69]
	global_load_dwordx2 v[220:221], v16, s[78:79]
	global_load_dwordx2 v[222:223], v16, s[72:73]
	global_load_dwordx2 v[224:225], v16, s[82:83]
	global_load_dwordx2 v[226:227], v16, s[68:69] offset:512
	global_load_dwordx2 v[228:229], v16, s[78:79] offset:512
	global_load_dwordx2 v[230:231], v16, s[72:73] offset:512
	global_load_dwordx2 v[232:233], v16, s[82:83] offset:512
	s_waitcnt vmcnt(22)
	v_permlane16_swap_b32_e32 v186, v187
	v_permlane16_swap_b32_e32 v188, v189
	s_nop 0
	v_permlane32_swap_b32_e32 v186, v187
	v_permlane32_swap_b32_e32 v188, v189
	v_max_u32_sdwa v154, v188, v182 dst_sel:DWORD dst_unused:UNUSED_PAD src0_sel:BYTE_0 src1_sel:DWORD
	v_max_u32_sdwa v155, v188, v182 dst_sel:DWORD dst_unused:UNUSED_PAD src0_sel:BYTE_1 src1_sel:DWORD
	v_max_u32_sdwa v156, v188, v182 dst_sel:DWORD dst_unused:UNUSED_PAD src0_sel:BYTE_2 src1_sel:DWORD
	v_max_u32_sdwa v157, v188, v182 dst_sel:DWORD dst_unused:UNUSED_PAD src0_sel:BYTE_3 src1_sel:DWORD
	v_cvt_f32_ubyte0_e32 v154, v154
	v_cvt_f32_ubyte0_e32 v155, v155
	v_cvt_f32_ubyte0_e32 v156, v156
	v_cvt_f32_ubyte0_e32 v157, v157
	v_rcp_iflag_f32_e32 v154, v154
	v_rcp_iflag_f32_e32 v155, v155
	v_rcp_iflag_f32_e32 v156, v156
	v_rcp_iflag_f32_e32 v157, v157
	v_cvt_f32_ubyte0_e32 v178, v186
	v_cvt_f32_ubyte1_e32 v179, v186
	v_cvt_f32_ubyte2_e32 v180, v186
	v_cvt_f32_ubyte3_e32 v181, v186
	v_pk_mul_f32 v[154:155], v[154:155], v[178:179]
	v_pk_mul_f32 v[156:157], v[156:157], v[180:181]
	v_pk_mul_f32 v[130:131], v[130:131], v[154:155]
	v_pk_mul_f32 v[132:133], v[132:133], v[156:157]
	v_max_u32_sdwa v154, v189, v182 dst_sel:DWORD dst_unused:UNUSED_PAD src0_sel:BYTE_0 src1_sel:DWORD
	v_max_u32_sdwa v155, v189, v182 dst_sel:DWORD dst_unused:UNUSED_PAD src0_sel:BYTE_1 src1_sel:DWORD
	v_max_u32_sdwa v156, v189, v182 dst_sel:DWORD dst_unused:UNUSED_PAD src0_sel:BYTE_2 src1_sel:DWORD
	v_max_u32_sdwa v157, v189, v182 dst_sel:DWORD dst_unused:UNUSED_PAD src0_sel:BYTE_3 src1_sel:DWORD
	v_cvt_f32_ubyte0_e32 v154, v154
	v_cvt_f32_ubyte0_e32 v155, v155
	v_cvt_f32_ubyte0_e32 v156, v156
	v_cvt_f32_ubyte0_e32 v157, v157
	v_rcp_iflag_f32_e32 v154, v154
	v_rcp_iflag_f32_e32 v155, v155
	v_rcp_iflag_f32_e32 v156, v156
	v_rcp_iflag_f32_e32 v157, v157
	v_cvt_f32_ubyte0_e32 v178, v187
	v_cvt_f32_ubyte1_e32 v179, v187
	v_cvt_f32_ubyte2_e32 v180, v187
	v_cvt_f32_ubyte3_e32 v181, v187
	global_load_dwordx2 v[186:187], v16, s[68:69] offset:1024
	global_load_dwordx2 v[188:189], v16, s[78:79] offset:1024
	v_pk_mul_f32 v[154:155], v[154:155], v[178:179]
	v_pk_mul_f32 v[156:157], v[156:157], v[180:181]
	v_pk_mul_f32 v[126:127], v[126:127], v[154:155]
	v_pk_mul_f32 v[128:129], v[128:129], v[156:157]
	s_waitcnt vmcnt(22)
	v_permlane16_swap_b32_e32 v190, v191
	v_permlane16_swap_b32_e32 v192, v193
	s_nop 0
	v_permlane32_swap_b32_e32 v190, v191
	v_permlane32_swap_b32_e32 v192, v193
	v_max_u32_sdwa v154, v192, v182 dst_sel:DWORD dst_unused:UNUSED_PAD src0_sel:BYTE_0 src1_sel:DWORD
	v_max_u32_sdwa v155, v192, v182 dst_sel:DWORD dst_unused:UNUSED_PAD src0_sel:BYTE_1 src1_sel:DWORD
	v_max_u32_sdwa v156, v192, v182 dst_sel:DWORD dst_unused:UNUSED_PAD src0_sel:BYTE_2 src1_sel:DWORD
	v_max_u32_sdwa v157, v192, v182 dst_sel:DWORD dst_unused:UNUSED_PAD src0_sel:BYTE_3 src1_sel:DWORD
	v_cvt_f32_ubyte0_e32 v154, v154
	v_cvt_f32_ubyte0_e32 v155, v155
	v_cvt_f32_ubyte0_e32 v156, v156
	v_cvt_f32_ubyte0_e32 v157, v157
	v_rcp_iflag_f32_e32 v154, v154
	v_rcp_iflag_f32_e32 v155, v155
	v_rcp_iflag_f32_e32 v156, v156
	v_rcp_iflag_f32_e32 v157, v157
	v_cvt_f32_ubyte0_e32 v178, v190
	v_cvt_f32_ubyte1_e32 v179, v190
	v_cvt_f32_ubyte2_e32 v180, v190
	v_cvt_f32_ubyte3_e32 v181, v190
	v_pk_mul_f32 v[154:155], v[154:155], v[178:179]
	v_pk_mul_f32 v[156:157], v[156:157], v[180:181]
	v_pk_mul_f32 v[122:123], v[122:123], v[154:155]
	v_pk_mul_f32 v[124:125], v[124:125], v[156:157]
	v_max_u32_sdwa v154, v193, v182 dst_sel:DWORD dst_unused:UNUSED_PAD src0_sel:BYTE_0 src1_sel:DWORD
	v_max_u32_sdwa v155, v193, v182 dst_sel:DWORD dst_unused:UNUSED_PAD src0_sel:BYTE_1 src1_sel:DWORD
	v_max_u32_sdwa v156, v193, v182 dst_sel:DWORD dst_unused:UNUSED_PAD src0_sel:BYTE_2 src1_sel:DWORD
	v_max_u32_sdwa v157, v193, v182 dst_sel:DWORD dst_unused:UNUSED_PAD src0_sel:BYTE_3 src1_sel:DWORD
	v_cvt_f32_ubyte0_e32 v154, v154
	v_cvt_f32_ubyte0_e32 v155, v155
	v_cvt_f32_ubyte0_e32 v156, v156
	v_cvt_f32_ubyte0_e32 v157, v157
	v_rcp_iflag_f32_e32 v154, v154
	v_rcp_iflag_f32_e32 v155, v155
	v_rcp_iflag_f32_e32 v156, v156
	v_rcp_iflag_f32_e32 v157, v157
	v_cvt_f32_ubyte0_e32 v178, v191
	v_cvt_f32_ubyte1_e32 v179, v191
	v_cvt_f32_ubyte2_e32 v180, v191
	v_cvt_f32_ubyte3_e32 v181, v191
	global_load_dwordx2 v[190:191], v16, s[72:73] offset:1024
	global_load_dwordx2 v[192:193], v16, s[82:83] offset:1024
	v_pk_mul_f32 v[154:155], v[154:155], v[178:179]
	v_pk_mul_f32 v[156:157], v[156:157], v[180:181]
	v_pk_mul_f32 v[118:119], v[118:119], v[154:155]
	v_pk_mul_f32 v[120:121], v[120:121], v[156:157]
	s_waitcnt vmcnt(22)
;   DI void mid(f32x4 (&acc)[2][2][4][2], const pg8::Unit& u, int wr, int wc, int fr, int fq) const {
; #pragma unroll
;     for (int ai = 0; ai < 2; ++ai)
; #pragma unroll
;       for (int m = 0; m < 4; ++m) {
;         int row = u.pm * 256 + 128 * ai + 64 * wr + 16 * m + fr;
;         asm volatile("" : "+v"(row));
; #pragma unroll
;         for (int bj = 0; bj < 2; ++bj)
; #pragma unroll
;           for (int n = 0; n < 2; ++n) {
;             const size_t idx = (size_t)row * 1024 + u.pn * 256 + 128 * bj + 32 * wc + 16 * n + 4 * fq;
;             const unsigned ga = *reinterpret_cast<const unsigned*>(reinterpret_cast<const unsigned char*>(p.ws + OFF_RA) + idx);
;             const unsigned gb = *reinterpret_cast<const unsigned*>(reinterpret_cast<const unsigned char*>(p.ws + OFF_RB) + idx);
; #pragma unroll
;             for (int j = 0; j < 4; ++j) {
;               const unsigned a8 = (ga >> (8 * j)) & 255u, b8 = (gb >> (8 * j)) & 255u;
;               acc[ai][bj][m][n][j] *= (float)a8 * __builtin_amdgcn_rcpf((float)(b8 > 1u ? b8 : 1u));
;             }
;           }
	v_permlane16_swap_b32_e32 v194, v195
	v_permlane16_swap_b32_e32 v196, v197
	s_nop 0
	v_permlane32_swap_b32_e32 v194, v195
	v_permlane32_swap_b32_e32 v196, v197
	v_max_u32_sdwa v154, v196, v182 dst_sel:DWORD dst_unused:UNUSED_PAD src0_sel:BYTE_0 src1_sel:DWORD
	v_max_u32_sdwa v155, v196, v182 dst_sel:DWORD dst_unused:UNUSED_PAD src0_sel:BYTE_1 src1_sel:DWORD
	v_max_u32_sdwa v156, v196, v182 dst_sel:DWORD dst_unused:UNUSED_PAD src0_sel:BYTE_2 src1_sel:DWORD
	v_max_u32_sdwa v157, v196, v182 dst_sel:DWORD dst_unused:UNUSED_PAD src0_sel:BYTE_3 src1_sel:DWORD
	v_cvt_f32_ubyte0_e32 v154, v154
	v_cvt_f32_ubyte0_e32 v155, v155
	v_cvt_f32_ubyte0_e32 v156, v156
	v_cvt_f32_ubyte0_e32 v157, v157
	v_rcp_iflag_f32_e32 v154, v154
	v_rcp_iflag_f32_e32 v155, v155
	v_rcp_iflag_f32_e32 v156, v156
	v_rcp_iflag_f32_e32 v157, v157
	v_cvt_f32_ubyte0_e32 v178, v194
	v_cvt_f32_ubyte1_e32 v179, v194
	v_cvt_f32_ubyte2_e32 v180, v194
	v_cvt_f32_ubyte3_e32 v181, v194
	v_pk_mul_f32 v[154:155], v[154:155], v[178:179]
	v_pk_mul_f32 v[156:157], v[156:157], v[180:181]
	v_pk_mul_f32 v[114:115], v[114:115], v[154:155]
	v_pk_mul_f32 v[116:117], v[116:117], v[156:157]
	v_max_u32_sdwa v154, v197, v182 dst_sel:DWORD dst_unused:UNUSED_PAD src0_sel:BYTE_0 src1_sel:DWORD
	v_max_u32_sdwa v155, v197, v182 dst_sel:DWORD dst_unused:UNUSED_PAD src0_sel:BYTE_1 src1_sel:DWORD
	v_max_u32_sdwa v156, v197, v182 dst_sel:DWORD dst_unused:UNUSED_PAD src0_sel:BYTE_2 src1_sel:DWORD
	v_max_u32_sdwa v157, v197, v182 dst_sel:DWORD dst_unused:UNUSED_PAD src0_sel:BYTE_3 src1_sel:DWORD
	v_cvt_f32_ubyte0_e32 v154, v154
	v_cvt_f32_ubyte0_e32 v155, v155
	v_cvt_f32_ubyte0_e32 v156, v156
	v_cvt_f32_ubyte0_e32 v157, v157
	v_rcp_iflag_f32_e32 v154, v154
	v_rcp_iflag_f32_e32 v155, v155
	v_rcp_iflag_f32_e32 v156, v156
	v_rcp_iflag_f32_e32 v157, v157
	v_cvt_f32_ubyte0_e32 v178, v195
	v_cvt_f32_ubyte1_e32 v179, v195
	v_cvt_f32_ubyte2_e32 v180, v195
	v_cvt_f32_ubyte3_e32 v181, v195
	global_load_dwordx2 v[194:195], v16, s[68:69] offset:1536
	global_load_dwordx2 v[196:197], v16, s[78:79] offset:1536
	v_pk_mul_f32 v[154:155], v[154:155], v[178:179]
	v_pk_mul_f32 v[156:157], v[156:157], v[180:181]
	v_pk_mul_f32 v[110:111], v[110:111], v[154:155]
	v_pk_mul_f32 v[112:113], v[112:113], v[156:157]
	s_waitcnt vmcnt(22)
	v_permlane16_swap_b32_e32 v198, v199
	v_permlane16_swap_b32_e32 v200, v201
	s_nop 0
	v_permlane32_swap_b32_e32 v198, v199
	v_permlane32_swap_b32_e32 v200, v201
	v_max_u32_sdwa v154, v200, v182 dst_sel:DWORD dst_unused:UNUSED_PAD src0_sel:BYTE_0 src1_sel:DWORD
	v_max_u32_sdwa v155, v200, v182 dst_sel:DWORD dst_unused:UNUSED_PAD src0_sel:BYTE_1 src1_sel:DWORD
	v_max_u32_sdwa v156, v200, v182 dst_sel:DWORD dst_unused:UNUSED_PAD src0_sel:BYTE_2 src1_sel:DWORD
	v_max_u32_sdwa v157, v200, v182 dst_sel:DWORD dst_unused:UNUSED_PAD src0_sel:BYTE_3 src1_sel:DWORD
	v_cvt_f32_ubyte0_e32 v154, v154
	v_cvt_f32_ubyte0_e32 v155, v155
	v_cvt_f32_ubyte0_e32 v156, v156
	v_cvt_f32_ubyte0_e32 v157, v157
	v_rcp_iflag_f32_e32 v154, v154
	v_rcp_iflag_f32_e32 v155, v155
	v_rcp_iflag_f32_e32 v156, v156
	v_rcp_iflag_f32_e32 v157, v157
	v_cvt_f32_ubyte0_e32 v178, v198
	v_cvt_f32_ubyte1_e32 v179, v198
	v_cvt_f32_ubyte2_e32 v180, v198
	v_cvt_f32_ubyte3_e32 v181, v198
	v_pk_mul_f32 v[154:155], v[154:155], v[178:179]
	v_pk_mul_f32 v[156:157], v[156:157], v[180:181]
	v_pk_mul_f32 v[106:107], v[106:107], v[154:155]
	v_pk_mul_f32 v[108:109], v[108:109], v[156:157]
	v_max_u32_sdwa v154, v201, v182 dst_sel:DWORD dst_unused:UNUSED_PAD src0_sel:BYTE_0 src1_sel:DWORD
	v_max_u32_sdwa v155, v201, v182 dst_sel:DWORD dst_unused:UNUSED_PAD src0_sel:BYTE_1 src1_sel:DWORD
	v_max_u32_sdwa v156, v201, v182 dst_sel:DWORD dst_unused:UNUSED_PAD src0_sel:BYTE_2 src1_sel:DWORD
	v_max_u32_sdwa v157, v201, v182 dst_sel:DWORD dst_unused:UNUSED_PAD src0_sel:BYTE_3 src1_sel:DWORD
	v_cvt_f32_ubyte0_e32 v154, v154
	v_cvt_f32_ubyte0_e32 v155, v155
	v_cvt_f32_ubyte0_e32 v156, v156
	v_cvt_f32_ubyte0_e32 v157, v157
	v_rcp_iflag_f32_e32 v154, v154
	v_rcp_iflag_f32_e32 v155, v155
	v_rcp_iflag_f32_e32 v156, v156
	v_rcp_iflag_f32_e32 v157, v157
	v_cvt_f32_ubyte0_e32 v178, v199
	v_cvt_f32_ubyte1_e32 v179, v199
	v_cvt_f32_ubyte2_e32 v180, v199
	v_cvt_f32_ubyte3_e32 v181, v199
	global_load_dwordx2 v[198:199], v16, s[72:73] offset:1536
	global_load_dwordx2 v[200:201], v16, s[82:83] offset:1536
	v_pk_mul_f32 v[154:155], v[154:155], v[178:179]
	v_pk_mul_f32 v[156:157], v[156:157], v[180:181]
	v_pk_mul_f32 v[102:103], v[102:103], v[154:155]
	v_pk_mul_f32 v[104:105], v[104:105], v[156:157]
	s_waitcnt vmcnt(22)
	v_permlane16_swap_b32_e32 v202, v203
	v_permlane16_swap_b32_e32 v204, v205
	s_nop 0
	v_permlane32_swap_b32_e32 v202, v203
	v_permlane32_swap_b32_e32 v204, v205
	v_max_u32_sdwa v154, v204, v182 dst_sel:DWORD dst_unused:UNUSED_PAD src0_sel:BYTE_0 src1_sel:DWORD
	v_max_u32_sdwa v155, v204, v182 dst_sel:DWORD dst_unused:UNUSED_PAD src0_sel:BYTE_1 src1_sel:DWORD
	v_max_u32_sdwa v156, v204, v182 dst_sel:DWORD dst_unused:UNUSED_PAD src0_sel:BYTE_2 src1_sel:DWORD
	v_max_u32_sdwa v157, v204, v182 dst_sel:DWORD dst_unused:UNUSED_PAD src0_sel:BYTE_3 src1_sel:DWORD
	v_cvt_f32_ubyte0_e32 v154, v154
	v_cvt_f32_ubyte0_e32 v155, v155
	v_cvt_f32_ubyte0_e32 v156, v156
	v_cvt_f32_ubyte0_e32 v157, v157
	v_rcp_iflag_f32_e32 v154, v154
	v_rcp_iflag_f32_e32 v155, v155
	v_rcp_iflag_f32_e32 v156, v156
	v_rcp_iflag_f32_e32 v157, v157
	v_cvt_f32_ubyte0_e32 v178, v202
	v_cvt_f32_ubyte1_e32 v179, v202
	v_cvt_f32_ubyte2_e32 v180, v202
	v_cvt_f32_ubyte3_e32 v181, v202
	v_pk_mul_f32 v[154:155], v[154:155], v[178:179]
	v_pk_mul_f32 v[156:157], v[156:157], v[180:181]
	v_pk_mul_f32 v[98:99], v[98:99], v[154:155]
	v_pk_mul_f32 v[100:101], v[100:101], v[156:157]
	v_max_u32_sdwa v154, v205, v182 dst_sel:DWORD dst_unused:UNUSED_PAD src0_sel:BYTE_0 src1_sel:DWORD
	v_max_u32_sdwa v155, v205, v182 dst_sel:DWORD dst_unused:UNUSED_PAD src0_sel:BYTE_1 src1_sel:DWORD
	v_max_u32_sdwa v156, v205, v182 dst_sel:DWORD dst_unused:UNUSED_PAD src0_sel:BYTE_2 src1_sel:DWORD
	v_max_u32_sdwa v157, v205, v182 dst_sel:DWORD dst_unused:UNUSED_PAD src0_sel:BYTE_3 src1_sel:DWORD
	v_cvt_f32_ubyte0_e32 v154, v154
	v_cvt_f32_ubyte0_e32 v155, v155
	v_cvt_f32_ubyte0_e32 v156, v156
	v_cvt_f32_ubyte0_e32 v157, v157
	v_rcp_iflag_f32_e32 v154, v154
	v_rcp_iflag_f32_e32 v155, v155
	v_rcp_iflag_f32_e32 v156, v156
	v_rcp_iflag_f32_e32 v157, v157
	v_cvt_f32_ubyte0_e32 v178, v203
	v_cvt_f32_ubyte1_e32 v179, v203
	v_cvt_f32_ubyte2_e32 v180, v203
	v_cvt_f32_ubyte3_e32 v181, v203
	v_pk_mul_f32 v[154:155], v[154:155], v[178:179]
	v_pk_mul_f32 v[156:157], v[156:157], v[180:181]
	v_pk_mul_f32 v[94:95], v[94:95], v[154:155]
	v_pk_mul_f32 v[96:97], v[96:97], v[156:157]
	s_waitcnt vmcnt(20)
;   DI void mid(f32x4 (&acc)[2][2][4][2], const pg8::Unit& u, int wr, int wc, int fr, int fq) const {
; #pragma unroll
;     for (int ai = 0; ai < 2; ++ai)
; #pragma unroll
;       for (int m = 0; m < 4; ++m) {
;         int row = u.pm * 256 + 128 * ai + 64 * wr + 16 * m + fr;
;         asm volatile("" : "+v"(row));
; #pragma unroll
;         for (int bj = 0; bj < 2; ++bj)
; #pragma unroll
;           for (int n = 0; n < 2; ++n) {
;             const size_t idx = (size_t)row * 1024 + u.pn * 256 + 128 * bj + 32 * wc + 16 * n + 4 * fq;
;             const unsigned ga = *reinterpret_cast<const unsigned*>(reinterpret_cast<const unsigned char*>(p.ws + OFF_RA) + idx);
;             const unsigned gb = *reinterpret_cast<const unsigned*>(reinterpret_cast<const unsigned char*>(p.ws + OFF_RB) + idx);
; #pragma unroll
;             for (int j = 0; j < 4; ++j) {
;               const unsigned a8 = (ga >> (8 * j)) & 255u, b8 = (gb >> (8 * j)) & 255u;
;               acc[ai][bj][m][n][j] *= (float)a8 * __builtin_amdgcn_rcpf((float)(b8 > 1u ? b8 : 1u));
;             }
;           }
;         asm volatile("" ::: "memory");
;       }
;   }
	v_permlane16_swap_b32_e32 v206, v207
	v_permlane16_swap_b32_e32 v208, v209
	s_nop 0
	v_permlane32_swap_b32_e32 v206, v207
	v_permlane32_swap_b32_e32 v208, v209
	v_max_u32_sdwa v154, v208, v182 dst_sel:DWORD dst_unused:UNUSED_PAD src0_sel:BYTE_0 src1_sel:DWORD
	v_max_u32_sdwa v155, v208, v182 dst_sel:DWORD dst_unused:UNUSED_PAD src0_sel:BYTE_1 src1_sel:DWORD
	v_max_u32_sdwa v156, v208, v182 dst_sel:DWORD dst_unused:UNUSED_PAD src0_sel:BYTE_2 src1_sel:DWORD
	v_max_u32_sdwa v157, v208, v182 dst_sel:DWORD dst_unused:UNUSED_PAD src0_sel:BYTE_3 src1_sel:DWORD
	v_cvt_f32_ubyte0_e32 v154, v154
	v_cvt_f32_ubyte0_e32 v155, v155
	v_cvt_f32_ubyte0_e32 v156, v156
	v_cvt_f32_ubyte0_e32 v157, v157
	v_rcp_iflag_f32_e32 v154, v154
	v_rcp_iflag_f32_e32 v155, v155
	v_rcp_iflag_f32_e32 v156, v156
	v_rcp_iflag_f32_e32 v157, v157
	v_cvt_f32_ubyte0_e32 v178, v206
	v_cvt_f32_ubyte1_e32 v179, v206
	v_cvt_f32_ubyte2_e32 v180, v206
	v_cvt_f32_ubyte3_e32 v181, v206
	v_pk_mul_f32 v[154:155], v[154:155], v[178:179]
	v_pk_mul_f32 v[156:157], v[156:157], v[180:181]
	v_pk_mul_f32 v[90:91], v[90:91], v[154:155]
	v_pk_mul_f32 v[92:93], v[92:93], v[156:157]
	v_max_u32_sdwa v154, v209, v182 dst_sel:DWORD dst_unused:UNUSED_PAD src0_sel:BYTE_0 src1_sel:DWORD
	v_max_u32_sdwa v155, v209, v182 dst_sel:DWORD dst_unused:UNUSED_PAD src0_sel:BYTE_1 src1_sel:DWORD
	v_max_u32_sdwa v156, v209, v182 dst_sel:DWORD dst_unused:UNUSED_PAD src0_sel:BYTE_2 src1_sel:DWORD
	v_max_u32_sdwa v157, v209, v182 dst_sel:DWORD dst_unused:UNUSED_PAD src0_sel:BYTE_3 src1_sel:DWORD
	v_cvt_f32_ubyte0_e32 v154, v154
	v_cvt_f32_ubyte0_e32 v155, v155
	v_cvt_f32_ubyte0_e32 v156, v156
	v_cvt_f32_ubyte0_e32 v157, v157
	v_rcp_iflag_f32_e32 v154, v154
	v_rcp_iflag_f32_e32 v155, v155
	v_rcp_iflag_f32_e32 v156, v156
	v_rcp_iflag_f32_e32 v157, v157
	v_cvt_f32_ubyte0_e32 v178, v207
	v_cvt_f32_ubyte1_e32 v179, v207
	v_cvt_f32_ubyte2_e32 v180, v207
	v_cvt_f32_ubyte3_e32 v181, v207
	v_pk_mul_f32 v[154:155], v[154:155], v[178:179]
	v_pk_mul_f32 v[156:157], v[156:157], v[180:181]
	v_pk_mul_f32 v[86:87], v[86:87], v[154:155]
	v_pk_mul_f32 v[88:89], v[88:89], v[156:157]
	s_waitcnt vmcnt(18)
	v_permlane16_swap_b32_e32 v210, v211
	v_permlane16_swap_b32_e32 v212, v213
	s_nop 0
	v_permlane32_swap_b32_e32 v210, v211
	v_permlane32_swap_b32_e32 v212, v213
	v_max_u32_sdwa v154, v212, v182 dst_sel:DWORD dst_unused:UNUSED_PAD src0_sel:BYTE_0 src1_sel:DWORD
	v_max_u32_sdwa v155, v212, v182 dst_sel:DWORD dst_unused:UNUSED_PAD src0_sel:BYTE_1 src1_sel:DWORD
	v_max_u32_sdwa v156, v212, v182 dst_sel:DWORD dst_unused:UNUSED_PAD src0_sel:BYTE_2 src1_sel:DWORD
	v_max_u32_sdwa v157, v212, v182 dst_sel:DWORD dst_unused:UNUSED_PAD src0_sel:BYTE_3 src1_sel:DWORD
	v_cvt_f32_ubyte0_e32 v154, v154
	v_cvt_f32_ubyte0_e32 v155, v155
	v_cvt_f32_ubyte0_e32 v156, v156
	v_cvt_f32_ubyte0_e32 v157, v157
	v_rcp_iflag_f32_e32 v154, v154
	v_rcp_iflag_f32_e32 v155, v155
	v_rcp_iflag_f32_e32 v156, v156
	v_rcp_iflag_f32_e32 v157, v157
	v_cvt_f32_ubyte0_e32 v178, v210
	v_cvt_f32_ubyte1_e32 v179, v210
	v_cvt_f32_ubyte2_e32 v180, v210
	v_cvt_f32_ubyte3_e32 v181, v210
	v_pk_mul_f32 v[154:155], v[154:155], v[178:179]
	v_pk_mul_f32 v[156:157], v[156:157], v[180:181]
	v_pk_mul_f32 v[82:83], v[82:83], v[154:155]
	v_pk_mul_f32 v[84:85], v[84:85], v[156:157]
	v_max_u32_sdwa v154, v213, v182 dst_sel:DWORD dst_unused:UNUSED_PAD src0_sel:BYTE_0 src1_sel:DWORD
	v_max_u32_sdwa v155, v213, v182 dst_sel:DWORD dst_unused:UNUSED_PAD src0_sel:BYTE_1 src1_sel:DWORD
	v_max_u32_sdwa v156, v213, v182 dst_sel:DWORD dst_unused:UNUSED_PAD src0_sel:BYTE_2 src1_sel:DWORD
	v_max_u32_sdwa v157, v213, v182 dst_sel:DWORD dst_unused:UNUSED_PAD src0_sel:BYTE_3 src1_sel:DWORD
	v_cvt_f32_ubyte0_e32 v154, v154
	v_cvt_f32_ubyte0_e32 v155, v155
	v_cvt_f32_ubyte0_e32 v156, v156
	v_cvt_f32_ubyte0_e32 v157, v157
	v_rcp_iflag_f32_e32 v154, v154
	v_rcp_iflag_f32_e32 v155, v155
	v_rcp_iflag_f32_e32 v156, v156
	v_rcp_iflag_f32_e32 v157, v157
	v_cvt_f32_ubyte0_e32 v178, v211
	v_cvt_f32_ubyte1_e32 v179, v211
	v_cvt_f32_ubyte2_e32 v180, v211
	v_cvt_f32_ubyte3_e32 v181, v211
	v_pk_mul_f32 v[154:155], v[154:155], v[178:179]
	v_pk_mul_f32 v[156:157], v[156:157], v[180:181]
	v_pk_mul_f32 v[78:79], v[78:79], v[154:155]
	v_pk_mul_f32 v[80:81], v[80:81], v[156:157]
	s_waitcnt vmcnt(16)
	v_permlane16_swap_b32_e32 v214, v215
	v_permlane16_swap_b32_e32 v216, v217
	s_nop 0
	v_permlane32_swap_b32_e32 v214, v215
	v_permlane32_swap_b32_e32 v216, v217
	v_max_u32_sdwa v154, v216, v182 dst_sel:DWORD dst_unused:UNUSED_PAD src0_sel:BYTE_0 src1_sel:DWORD
	v_max_u32_sdwa v155, v216, v182 dst_sel:DWORD dst_unused:UNUSED_PAD src0_sel:BYTE_1 src1_sel:DWORD
	v_max_u32_sdwa v156, v216, v182 dst_sel:DWORD dst_unused:UNUSED_PAD src0_sel:BYTE_2 src1_sel:DWORD
	v_max_u32_sdwa v157, v216, v182 dst_sel:DWORD dst_unused:UNUSED_PAD src0_sel:BYTE_3 src1_sel:DWORD
	v_cvt_f32_ubyte0_e32 v154, v154
	v_cvt_f32_ubyte0_e32 v155, v155
	v_cvt_f32_ubyte0_e32 v156, v156
	v_cvt_f32_ubyte0_e32 v157, v157
	v_rcp_iflag_f32_e32 v154, v154
	v_rcp_iflag_f32_e32 v155, v155
	v_rcp_iflag_f32_e32 v156, v156
	v_rcp_iflag_f32_e32 v157, v157
	v_cvt_f32_ubyte0_e32 v178, v214
	v_cvt_f32_ubyte1_e32 v179, v214
	v_cvt_f32_ubyte2_e32 v180, v214
	v_cvt_f32_ubyte3_e32 v181, v214
	v_pk_mul_f32 v[154:155], v[154:155], v[178:179]
	v_pk_mul_f32 v[156:157], v[156:157], v[180:181]
	v_pk_mul_f32 v[74:75], v[74:75], v[154:155]
	v_pk_mul_f32 v[76:77], v[76:77], v[156:157]
	v_max_u32_sdwa v154, v217, v182 dst_sel:DWORD dst_unused:UNUSED_PAD src0_sel:BYTE_0 src1_sel:DWORD
	v_max_u32_sdwa v155, v217, v182 dst_sel:DWORD dst_unused:UNUSED_PAD src0_sel:BYTE_1 src1_sel:DWORD
	v_max_u32_sdwa v156, v217, v182 dst_sel:DWORD dst_unused:UNUSED_PAD src0_sel:BYTE_2 src1_sel:DWORD
	v_max_u32_sdwa v157, v217, v182 dst_sel:DWORD dst_unused:UNUSED_PAD src0_sel:BYTE_3 src1_sel:DWORD
	v_cvt_f32_ubyte0_e32 v154, v154
	v_cvt_f32_ubyte0_e32 v155, v155
	v_cvt_f32_ubyte0_e32 v156, v156
	v_cvt_f32_ubyte0_e32 v157, v157
	v_rcp_iflag_f32_e32 v154, v154
	v_rcp_iflag_f32_e32 v155, v155
	v_rcp_iflag_f32_e32 v156, v156
	v_rcp_iflag_f32_e32 v157, v157
	v_cvt_f32_ubyte0_e32 v178, v215
	v_cvt_f32_ubyte1_e32 v179, v215
	v_cvt_f32_ubyte2_e32 v180, v215
	v_cvt_f32_ubyte3_e32 v181, v215
	v_pk_mul_f32 v[154:155], v[154:155], v[178:179]
	v_pk_mul_f32 v[156:157], v[156:157], v[180:181]
	v_pk_mul_f32 v[70:71], v[70:71], v[154:155]
	v_pk_mul_f32 v[72:73], v[72:73], v[156:157]
	s_waitcnt vmcnt(14)
;   DI void mid(f32x4 (&acc)[2][2][4][2], const pg8::Unit& u, int wr, int wc, int fr, int fq) const {
; #pragma unroll
;     for (int ai = 0; ai < 2; ++ai)
; #pragma unroll
;       for (int m = 0; m < 4; ++m) {
;         int row = u.pm * 256 + 128 * ai + 64 * wr + 16 * m + fr;
;         asm volatile("" : "+v"(row));
; #pragma unroll
;         for (int bj = 0; bj < 2; ++bj)
; #pragma unroll
;           for (int n = 0; n < 2; ++n) {
;             const size_t idx = (size_t)row * 1024 + u.pn * 256 + 128 * bj + 32 * wc + 16 * n + 4 * fq;
;             const unsigned ga = *reinterpret_cast<const unsigned*>(reinterpret_cast<const unsigned char*>(p.ws + OFF_RA) + idx);
;             const unsigned gb = *reinterpret_cast<const unsigned*>(reinterpret_cast<const unsigned char*>(p.ws + OFF_RB) + idx);
; #pragma unroll
;             for (int j = 0; j < 4; ++j) {
;               const unsigned a8 = (ga >> (8 * j)) & 255u, b8 = (gb >> (8 * j)) & 255u;
;               acc[ai][bj][m][n][j] *= (float)a8 * __builtin_amdgcn_rcpf((float)(b8 > 1u ? b8 : 1u));
;             }
;           }
;         asm volatile("" ::: "memory");
;       }
;   }
	v_permlane16_swap_b32_e32 v218, v219
	v_permlane16_swap_b32_e32 v220, v221
	s_nop 0
	v_permlane32_swap_b32_e32 v218, v219
	v_permlane32_swap_b32_e32 v220, v221
	v_max_u32_sdwa v154, v220, v182 dst_sel:DWORD dst_unused:UNUSED_PAD src0_sel:BYTE_0 src1_sel:DWORD
	v_max_u32_sdwa v155, v220, v182 dst_sel:DWORD dst_unused:UNUSED_PAD src0_sel:BYTE_1 src1_sel:DWORD
	v_max_u32_sdwa v156, v220, v182 dst_sel:DWORD dst_unused:UNUSED_PAD src0_sel:BYTE_2 src1_sel:DWORD
	v_max_u32_sdwa v157, v220, v182 dst_sel:DWORD dst_unused:UNUSED_PAD src0_sel:BYTE_3 src1_sel:DWORD
	v_cvt_f32_ubyte0_e32 v154, v154
	v_cvt_f32_ubyte0_e32 v155, v155
	v_cvt_f32_ubyte0_e32 v156, v156
	v_cvt_f32_ubyte0_e32 v157, v157
	v_rcp_iflag_f32_e32 v154, v154
	v_rcp_iflag_f32_e32 v155, v155
	v_rcp_iflag_f32_e32 v156, v156
	v_rcp_iflag_f32_e32 v157, v157
	v_cvt_f32_ubyte0_e32 v178, v218
	v_cvt_f32_ubyte1_e32 v179, v218
	v_cvt_f32_ubyte2_e32 v180, v218
	v_cvt_f32_ubyte3_e32 v181, v218
	v_pk_mul_f32 v[154:155], v[154:155], v[178:179]
	v_pk_mul_f32 v[156:157], v[156:157], v[180:181]
	v_pk_mul_f32 v[66:67], v[66:67], v[154:155]
	v_pk_mul_f32 v[68:69], v[68:69], v[156:157]
	v_max_u32_sdwa v154, v221, v182 dst_sel:DWORD dst_unused:UNUSED_PAD src0_sel:BYTE_0 src1_sel:DWORD
	v_max_u32_sdwa v155, v221, v182 dst_sel:DWORD dst_unused:UNUSED_PAD src0_sel:BYTE_1 src1_sel:DWORD
	v_max_u32_sdwa v156, v221, v182 dst_sel:DWORD dst_unused:UNUSED_PAD src0_sel:BYTE_2 src1_sel:DWORD
	v_max_u32_sdwa v157, v221, v182 dst_sel:DWORD dst_unused:UNUSED_PAD src0_sel:BYTE_3 src1_sel:DWORD
	v_cvt_f32_ubyte0_e32 v154, v154
	v_cvt_f32_ubyte0_e32 v155, v155
	v_cvt_f32_ubyte0_e32 v156, v156
	v_cvt_f32_ubyte0_e32 v157, v157
	v_rcp_iflag_f32_e32 v154, v154
	v_rcp_iflag_f32_e32 v155, v155
	v_rcp_iflag_f32_e32 v156, v156
	v_rcp_iflag_f32_e32 v157, v157
	v_cvt_f32_ubyte0_e32 v178, v219
	v_cvt_f32_ubyte1_e32 v179, v219
	v_cvt_f32_ubyte2_e32 v180, v219
	v_cvt_f32_ubyte3_e32 v181, v219
	v_pk_mul_f32 v[154:155], v[154:155], v[178:179]
	v_pk_mul_f32 v[156:157], v[156:157], v[180:181]
	v_pk_mul_f32 v[62:63], v[62:63], v[154:155]
	v_pk_mul_f32 v[64:65], v[64:65], v[156:157]
	s_waitcnt vmcnt(12)
	v_permlane16_swap_b32_e32 v222, v223
	v_permlane16_swap_b32_e32 v224, v225
	s_nop 0
	v_permlane32_swap_b32_e32 v222, v223
	v_permlane32_swap_b32_e32 v224, v225
	v_max_u32_sdwa v154, v224, v182 dst_sel:DWORD dst_unused:UNUSED_PAD src0_sel:BYTE_0 src1_sel:DWORD
	v_max_u32_sdwa v155, v224, v182 dst_sel:DWORD dst_unused:UNUSED_PAD src0_sel:BYTE_1 src1_sel:DWORD
	v_max_u32_sdwa v156, v224, v182 dst_sel:DWORD dst_unused:UNUSED_PAD src0_sel:BYTE_2 src1_sel:DWORD
	v_max_u32_sdwa v157, v224, v182 dst_sel:DWORD dst_unused:UNUSED_PAD src0_sel:BYTE_3 src1_sel:DWORD
	v_cvt_f32_ubyte0_e32 v154, v154
	v_cvt_f32_ubyte0_e32 v155, v155
	v_cvt_f32_ubyte0_e32 v156, v156
	v_cvt_f32_ubyte0_e32 v157, v157
	v_rcp_iflag_f32_e32 v154, v154
	v_rcp_iflag_f32_e32 v155, v155
	v_rcp_iflag_f32_e32 v156, v156
	v_rcp_iflag_f32_e32 v157, v157
	v_cvt_f32_ubyte0_e32 v178, v222
	v_cvt_f32_ubyte1_e32 v179, v222
	v_cvt_f32_ubyte2_e32 v180, v222
	v_cvt_f32_ubyte3_e32 v181, v222
	v_pk_mul_f32 v[154:155], v[154:155], v[178:179]
	v_pk_mul_f32 v[156:157], v[156:157], v[180:181]
	v_pk_mul_f32 v[58:59], v[58:59], v[154:155]
	v_pk_mul_f32 v[60:61], v[60:61], v[156:157]
	v_max_u32_sdwa v154, v225, v182 dst_sel:DWORD dst_unused:UNUSED_PAD src0_sel:BYTE_0 src1_sel:DWORD
	v_max_u32_sdwa v155, v225, v182 dst_sel:DWORD dst_unused:UNUSED_PAD src0_sel:BYTE_1 src1_sel:DWORD
	v_max_u32_sdwa v156, v225, v182 dst_sel:DWORD dst_unused:UNUSED_PAD src0_sel:BYTE_2 src1_sel:DWORD
	v_max_u32_sdwa v157, v225, v182 dst_sel:DWORD dst_unused:UNUSED_PAD src0_sel:BYTE_3 src1_sel:DWORD
	v_cvt_f32_ubyte0_e32 v154, v154
	v_cvt_f32_ubyte0_e32 v155, v155
	v_cvt_f32_ubyte0_e32 v156, v156
	v_cvt_f32_ubyte0_e32 v157, v157
	v_rcp_iflag_f32_e32 v154, v154
	v_rcp_iflag_f32_e32 v155, v155
	v_rcp_iflag_f32_e32 v156, v156
	v_rcp_iflag_f32_e32 v157, v157
	v_cvt_f32_ubyte0_e32 v178, v223
	v_cvt_f32_ubyte1_e32 v179, v223
	v_cvt_f32_ubyte2_e32 v180, v223
	v_cvt_f32_ubyte3_e32 v181, v223
	v_pk_mul_f32 v[154:155], v[154:155], v[178:179]
	v_pk_mul_f32 v[156:157], v[156:157], v[180:181]
	v_pk_mul_f32 v[54:55], v[54:55], v[154:155]
	v_pk_mul_f32 v[56:57], v[56:57], v[156:157]
	s_waitcnt vmcnt(10)
	v_permlane16_swap_b32_e32 v226, v227
	v_permlane16_swap_b32_e32 v228, v229
	s_nop 0
	v_permlane32_swap_b32_e32 v226, v227
	v_permlane32_swap_b32_e32 v228, v229
	v_max_u32_sdwa v154, v228, v182 dst_sel:DWORD dst_unused:UNUSED_PAD src0_sel:BYTE_0 src1_sel:DWORD
	v_max_u32_sdwa v155, v228, v182 dst_sel:DWORD dst_unused:UNUSED_PAD src0_sel:BYTE_1 src1_sel:DWORD
	v_max_u32_sdwa v156, v228, v182 dst_sel:DWORD dst_unused:UNUSED_PAD src0_sel:BYTE_2 src1_sel:DWORD
	v_max_u32_sdwa v157, v228, v182 dst_sel:DWORD dst_unused:UNUSED_PAD src0_sel:BYTE_3 src1_sel:DWORD
	v_cvt_f32_ubyte0_e32 v154, v154
	v_cvt_f32_ubyte0_e32 v155, v155
	v_cvt_f32_ubyte0_e32 v156, v156
	v_cvt_f32_ubyte0_e32 v157, v157
	v_rcp_iflag_f32_e32 v154, v154
	v_rcp_iflag_f32_e32 v155, v155
	v_rcp_iflag_f32_e32 v156, v156
	v_rcp_iflag_f32_e32 v157, v157
	v_cvt_f32_ubyte0_e32 v178, v226
	v_cvt_f32_ubyte1_e32 v179, v226
	v_cvt_f32_ubyte2_e32 v180, v226
	v_cvt_f32_ubyte3_e32 v181, v226
	v_pk_mul_f32 v[154:155], v[154:155], v[178:179]
	v_pk_mul_f32 v[156:157], v[156:157], v[180:181]
	v_pk_mul_f32 v[50:51], v[50:51], v[154:155]
	v_pk_mul_f32 v[52:53], v[52:53], v[156:157]
	v_max_u32_sdwa v154, v229, v182 dst_sel:DWORD dst_unused:UNUSED_PAD src0_sel:BYTE_0 src1_sel:DWORD
	v_max_u32_sdwa v155, v229, v182 dst_sel:DWORD dst_unused:UNUSED_PAD src0_sel:BYTE_1 src1_sel:DWORD
	v_max_u32_sdwa v156, v229, v182 dst_sel:DWORD dst_unused:UNUSED_PAD src0_sel:BYTE_2 src1_sel:DWORD
	v_max_u32_sdwa v157, v229, v182 dst_sel:DWORD dst_unused:UNUSED_PAD src0_sel:BYTE_3 src1_sel:DWORD
	v_cvt_f32_ubyte0_e32 v154, v154
	v_cvt_f32_ubyte0_e32 v155, v155
	v_cvt_f32_ubyte0_e32 v156, v156
	v_cvt_f32_ubyte0_e32 v157, v157
	v_rcp_iflag_f32_e32 v154, v154
	v_rcp_iflag_f32_e32 v155, v155
	v_rcp_iflag_f32_e32 v156, v156
	v_rcp_iflag_f32_e32 v157, v157
	v_cvt_f32_ubyte0_e32 v178, v227
	v_cvt_f32_ubyte1_e32 v179, v227
	v_cvt_f32_ubyte2_e32 v180, v227
	v_cvt_f32_ubyte3_e32 v181, v227
	v_pk_mul_f32 v[154:155], v[154:155], v[178:179]
	v_pk_mul_f32 v[156:157], v[156:157], v[180:181]
	v_pk_mul_f32 v[46:47], v[46:47], v[154:155]
	v_pk_mul_f32 v[48:49], v[48:49], v[156:157]
	s_waitcnt vmcnt(8)
;   DI void mid(f32x4 (&acc)[2][2][4][2], const pg8::Unit& u, int wr, int wc, int fr, int fq) const {
; #pragma unroll
;     for (int ai = 0; ai < 2; ++ai)
; #pragma unroll
;       for (int m = 0; m < 4; ++m) {
;         int row = u.pm * 256 + 128 * ai + 64 * wr + 16 * m + fr;
;         asm volatile("" : "+v"(row));
; #pragma unroll
;         for (int bj = 0; bj < 2; ++bj)
; #pragma unroll
;           for (int n = 0; n < 2; ++n) {
;             const size_t idx = (size_t)row * 1024 + u.pn * 256 + 128 * bj + 32 * wc + 16 * n + 4 * fq;
;             const unsigned ga = *reinterpret_cast<const unsigned*>(reinterpret_cast<const unsigned char*>(p.ws + OFF_RA) + idx);
;             const unsigned gb = *reinterpret_cast<const unsigned*>(reinterpret_cast<const unsigned char*>(p.ws + OFF_RB) + idx);
; #pragma unroll
;             for (int j = 0; j < 4; ++j) {
;               const unsigned a8 = (ga >> (8 * j)) & 255u, b8 = (gb >> (8 * j)) & 255u;
;               acc[ai][bj][m][n][j] *= (float)a8 * __builtin_amdgcn_rcpf((float)(b8 > 1u ? b8 : 1u));
;             }
;           }
;         asm volatile("" ::: "memory");
;       }
;   }
	v_permlane16_swap_b32_e32 v230, v231
	v_permlane16_swap_b32_e32 v232, v233
	s_nop 0
	v_permlane32_swap_b32_e32 v230, v231
	v_permlane32_swap_b32_e32 v232, v233
	v_max_u32_sdwa v154, v232, v182 dst_sel:DWORD dst_unused:UNUSED_PAD src0_sel:BYTE_0 src1_sel:DWORD
	v_max_u32_sdwa v155, v232, v182 dst_sel:DWORD dst_unused:UNUSED_PAD src0_sel:BYTE_1 src1_sel:DWORD
	v_max_u32_sdwa v156, v232, v182 dst_sel:DWORD dst_unused:UNUSED_PAD src0_sel:BYTE_2 src1_sel:DWORD
	v_max_u32_sdwa v157, v232, v182 dst_sel:DWORD dst_unused:UNUSED_PAD src0_sel:BYTE_3 src1_sel:DWORD
	v_cvt_f32_ubyte0_e32 v154, v154
	v_cvt_f32_ubyte0_e32 v155, v155
	v_cvt_f32_ubyte0_e32 v156, v156
	v_cvt_f32_ubyte0_e32 v157, v157
	v_rcp_iflag_f32_e32 v154, v154
	v_rcp_iflag_f32_e32 v155, v155
	v_rcp_iflag_f32_e32 v156, v156
	v_rcp_iflag_f32_e32 v157, v157
	v_cvt_f32_ubyte0_e32 v178, v230
	v_cvt_f32_ubyte1_e32 v179, v230
	v_cvt_f32_ubyte2_e32 v180, v230
	v_cvt_f32_ubyte3_e32 v181, v230
	v_pk_mul_f32 v[154:155], v[154:155], v[178:179]
	v_pk_mul_f32 v[156:157], v[156:157], v[180:181]
	v_pk_mul_f32 v[42:43], v[42:43], v[154:155]
	v_pk_mul_f32 v[44:45], v[44:45], v[156:157]
	v_max_u32_sdwa v154, v233, v182 dst_sel:DWORD dst_unused:UNUSED_PAD src0_sel:BYTE_0 src1_sel:DWORD
	v_max_u32_sdwa v155, v233, v182 dst_sel:DWORD dst_unused:UNUSED_PAD src0_sel:BYTE_1 src1_sel:DWORD
	v_max_u32_sdwa v156, v233, v182 dst_sel:DWORD dst_unused:UNUSED_PAD src0_sel:BYTE_2 src1_sel:DWORD
	v_max_u32_sdwa v157, v233, v182 dst_sel:DWORD dst_unused:UNUSED_PAD src0_sel:BYTE_3 src1_sel:DWORD
	v_cvt_f32_ubyte0_e32 v154, v154
	v_cvt_f32_ubyte0_e32 v155, v155
	v_cvt_f32_ubyte0_e32 v156, v156
	v_cvt_f32_ubyte0_e32 v157, v157
	v_rcp_iflag_f32_e32 v154, v154
	v_rcp_iflag_f32_e32 v155, v155
	v_rcp_iflag_f32_e32 v156, v156
	v_rcp_iflag_f32_e32 v157, v157
	v_cvt_f32_ubyte0_e32 v178, v231
	v_cvt_f32_ubyte1_e32 v179, v231
	v_cvt_f32_ubyte2_e32 v180, v231
	v_cvt_f32_ubyte3_e32 v181, v231
	v_pk_mul_f32 v[154:155], v[154:155], v[178:179]
	v_pk_mul_f32 v[156:157], v[156:157], v[180:181]
	v_pk_mul_f32 v[38:39], v[38:39], v[154:155]
	v_pk_mul_f32 v[40:41], v[40:41], v[156:157]
	s_waitcnt vmcnt(6)
	v_permlane16_swap_b32_e32 v186, v187
	v_permlane16_swap_b32_e32 v188, v189
	s_nop 0
	v_permlane32_swap_b32_e32 v186, v187
	v_permlane32_swap_b32_e32 v188, v189
	v_max_u32_sdwa v154, v188, v182 dst_sel:DWORD dst_unused:UNUSED_PAD src0_sel:BYTE_0 src1_sel:DWORD
	v_max_u32_sdwa v155, v188, v182 dst_sel:DWORD dst_unused:UNUSED_PAD src0_sel:BYTE_1 src1_sel:DWORD
	v_max_u32_sdwa v156, v188, v182 dst_sel:DWORD dst_unused:UNUSED_PAD src0_sel:BYTE_2 src1_sel:DWORD
	v_max_u32_sdwa v157, v188, v182 dst_sel:DWORD dst_unused:UNUSED_PAD src0_sel:BYTE_3 src1_sel:DWORD
	v_cvt_f32_ubyte0_e32 v154, v154
	v_cvt_f32_ubyte0_e32 v155, v155
	v_cvt_f32_ubyte0_e32 v156, v156
	v_cvt_f32_ubyte0_e32 v157, v157
	v_rcp_iflag_f32_e32 v154, v154
	v_rcp_iflag_f32_e32 v155, v155
	v_rcp_iflag_f32_e32 v156, v156
	v_rcp_iflag_f32_e32 v157, v157
	v_cvt_f32_ubyte0_e32 v178, v186
	v_cvt_f32_ubyte1_e32 v179, v186
	v_cvt_f32_ubyte2_e32 v180, v186
	v_cvt_f32_ubyte3_e32 v181, v186
	v_pk_mul_f32 v[154:155], v[154:155], v[178:179]
	v_pk_mul_f32 v[156:157], v[156:157], v[180:181]
	v_pk_mul_f32 v[34:35], v[34:35], v[154:155]
	v_pk_mul_f32 v[36:37], v[36:37], v[156:157]
	v_max_u32_sdwa v154, v189, v182 dst_sel:DWORD dst_unused:UNUSED_PAD src0_sel:BYTE_0 src1_sel:DWORD
	v_max_u32_sdwa v155, v189, v182 dst_sel:DWORD dst_unused:UNUSED_PAD src0_sel:BYTE_1 src1_sel:DWORD
	v_max_u32_sdwa v156, v189, v182 dst_sel:DWORD dst_unused:UNUSED_PAD src0_sel:BYTE_2 src1_sel:DWORD
	v_max_u32_sdwa v157, v189, v182 dst_sel:DWORD dst_unused:UNUSED_PAD src0_sel:BYTE_3 src1_sel:DWORD
	v_cvt_f32_ubyte0_e32 v154, v154
	v_cvt_f32_ubyte0_e32 v155, v155
	v_cvt_f32_ubyte0_e32 v156, v156
	v_cvt_f32_ubyte0_e32 v157, v157
	v_rcp_iflag_f32_e32 v154, v154
	v_rcp_iflag_f32_e32 v155, v155
	v_rcp_iflag_f32_e32 v156, v156
	v_rcp_iflag_f32_e32 v157, v157
	v_cvt_f32_ubyte0_e32 v178, v187
	v_cvt_f32_ubyte1_e32 v179, v187
	v_cvt_f32_ubyte2_e32 v180, v187
	v_cvt_f32_ubyte3_e32 v181, v187
	v_pk_mul_f32 v[154:155], v[154:155], v[178:179]
	v_pk_mul_f32 v[156:157], v[156:157], v[180:181]
	v_pk_mul_f32 v[30:31], v[30:31], v[154:155]
	v_pk_mul_f32 v[32:33], v[32:33], v[156:157]
	s_waitcnt vmcnt(4)
;   DI void mid(f32x4 (&acc)[2][2][4][2], const pg8::Unit& u, int wr, int wc, int fr, int fq) const {
; #pragma unroll
;     for (int ai = 0; ai < 2; ++ai)
; #pragma unroll
;       for (int m = 0; m < 4; ++m) {
;         int row = u.pm * 256 + 128 * ai + 64 * wr + 16 * m + fr;
;         asm volatile("" : "+v"(row));
; #pragma unroll
;         for (int bj = 0; bj < 2; ++bj)
; #pragma unroll
;           for (int n = 0; n < 2; ++n) {
;             const size_t idx = (size_t)row * 1024 + u.pn * 256 + 128 * bj + 32 * wc + 16 * n + 4 * fq;
;             const unsigned ga = *reinterpret_cast<const unsigned*>(reinterpret_cast<const unsigned char*>(p.ws + OFF_RA) + idx);
;             const unsigned gb = *reinterpret_cast<const unsigned*>(reinterpret_cast<const unsigned char*>(p.ws + OFF_RB) + idx);
; #pragma unroll
;             for (int j = 0; j < 4; ++j) {
;               const unsigned a8 = (ga >> (8 * j)) & 255u, b8 = (gb >> (8 * j)) & 255u;
;               acc[ai][bj][m][n][j] *= (float)a8 * __builtin_amdgcn_rcpf((float)(b8 > 1u ? b8 : 1u));
;             }
;           }
;         asm volatile("" ::: "memory");
;       }
;   }
	v_permlane16_swap_b32_e32 v190, v191
	v_permlane16_swap_b32_e32 v192, v193
	s_nop 0
	v_permlane32_swap_b32_e32 v190, v191
	v_permlane32_swap_b32_e32 v192, v193
	v_max_u32_sdwa v154, v192, v182 dst_sel:DWORD dst_unused:UNUSED_PAD src0_sel:BYTE_0 src1_sel:DWORD
	v_max_u32_sdwa v155, v192, v182 dst_sel:DWORD dst_unused:UNUSED_PAD src0_sel:BYTE_1 src1_sel:DWORD
	v_max_u32_sdwa v156, v192, v182 dst_sel:DWORD dst_unused:UNUSED_PAD src0_sel:BYTE_2 src1_sel:DWORD
	v_max_u32_sdwa v157, v192, v182 dst_sel:DWORD dst_unused:UNUSED_PAD src0_sel:BYTE_3 src1_sel:DWORD
	v_cvt_f32_ubyte0_e32 v154, v154
	v_cvt_f32_ubyte0_e32 v155, v155
	v_cvt_f32_ubyte0_e32 v156, v156
	v_cvt_f32_ubyte0_e32 v157, v157
	v_rcp_iflag_f32_e32 v154, v154
	v_rcp_iflag_f32_e32 v155, v155
	v_rcp_iflag_f32_e32 v156, v156
	v_rcp_iflag_f32_e32 v157, v157
	v_cvt_f32_ubyte0_e32 v178, v190
	v_cvt_f32_ubyte1_e32 v179, v190
	v_cvt_f32_ubyte2_e32 v180, v190
	v_cvt_f32_ubyte3_e32 v181, v190
	v_pk_mul_f32 v[154:155], v[154:155], v[178:179]
	v_pk_mul_f32 v[156:157], v[156:157], v[180:181]
	v_pk_mul_f32 v[26:27], v[26:27], v[154:155]
	v_pk_mul_f32 v[28:29], v[28:29], v[156:157]
	v_max_u32_sdwa v154, v193, v182 dst_sel:DWORD dst_unused:UNUSED_PAD src0_sel:BYTE_0 src1_sel:DWORD
	v_max_u32_sdwa v155, v193, v182 dst_sel:DWORD dst_unused:UNUSED_PAD src0_sel:BYTE_1 src1_sel:DWORD
	v_max_u32_sdwa v156, v193, v182 dst_sel:DWORD dst_unused:UNUSED_PAD src0_sel:BYTE_2 src1_sel:DWORD
	v_max_u32_sdwa v157, v193, v182 dst_sel:DWORD dst_unused:UNUSED_PAD src0_sel:BYTE_3 src1_sel:DWORD
	v_cvt_f32_ubyte0_e32 v154, v154
	v_cvt_f32_ubyte0_e32 v155, v155
	v_cvt_f32_ubyte0_e32 v156, v156
	v_cvt_f32_ubyte0_e32 v157, v157
	v_rcp_iflag_f32_e32 v154, v154
	v_rcp_iflag_f32_e32 v155, v155
	v_rcp_iflag_f32_e32 v156, v156
	v_rcp_iflag_f32_e32 v157, v157
	v_cvt_f32_ubyte0_e32 v178, v191
	v_cvt_f32_ubyte1_e32 v179, v191
	v_cvt_f32_ubyte2_e32 v180, v191
	v_cvt_f32_ubyte3_e32 v181, v191
	v_pk_mul_f32 v[154:155], v[154:155], v[178:179]
	v_pk_mul_f32 v[156:157], v[156:157], v[180:181]
	v_pk_mul_f32 v[22:23], v[22:23], v[154:155]
	v_pk_mul_f32 v[24:25], v[24:25], v[156:157]
	s_waitcnt vmcnt(2)
	v_permlane16_swap_b32_e32 v194, v195
	v_permlane16_swap_b32_e32 v196, v197
	s_nop 0
	v_permlane32_swap_b32_e32 v194, v195
	v_permlane32_swap_b32_e32 v196, v197
	v_max_u32_sdwa v154, v196, v182 dst_sel:DWORD dst_unused:UNUSED_PAD src0_sel:BYTE_0 src1_sel:DWORD
	v_max_u32_sdwa v155, v196, v182 dst_sel:DWORD dst_unused:UNUSED_PAD src0_sel:BYTE_1 src1_sel:DWORD
	v_max_u32_sdwa v156, v196, v182 dst_sel:DWORD dst_unused:UNUSED_PAD src0_sel:BYTE_2 src1_sel:DWORD
	v_max_u32_sdwa v157, v196, v182 dst_sel:DWORD dst_unused:UNUSED_PAD src0_sel:BYTE_3 src1_sel:DWORD
	v_cvt_f32_ubyte0_e32 v154, v154
	v_cvt_f32_ubyte0_e32 v155, v155
	v_cvt_f32_ubyte0_e32 v156, v156
	v_cvt_f32_ubyte0_e32 v157, v157
	v_rcp_iflag_f32_e32 v154, v154
	v_rcp_iflag_f32_e32 v155, v155
	v_rcp_iflag_f32_e32 v156, v156
	v_rcp_iflag_f32_e32 v157, v157
	v_cvt_f32_ubyte0_e32 v178, v194
	v_cvt_f32_ubyte1_e32 v179, v194
	v_cvt_f32_ubyte2_e32 v180, v194
	v_cvt_f32_ubyte3_e32 v181, v194
	v_pk_mul_f32 v[154:155], v[154:155], v[178:179]
	v_pk_mul_f32 v[156:157], v[156:157], v[180:181]
	v_pk_mul_f32 v[12:13], v[12:13], v[154:155]
	v_pk_mul_f32 v[14:15], v[14:15], v[156:157]
	v_max_u32_sdwa v154, v197, v182 dst_sel:DWORD dst_unused:UNUSED_PAD src0_sel:BYTE_0 src1_sel:DWORD
	v_max_u32_sdwa v155, v197, v182 dst_sel:DWORD dst_unused:UNUSED_PAD src0_sel:BYTE_1 src1_sel:DWORD
	v_max_u32_sdwa v156, v197, v182 dst_sel:DWORD dst_unused:UNUSED_PAD src0_sel:BYTE_2 src1_sel:DWORD
	v_max_u32_sdwa v157, v197, v182 dst_sel:DWORD dst_unused:UNUSED_PAD src0_sel:BYTE_3 src1_sel:DWORD
	v_cvt_f32_ubyte0_e32 v154, v154
	v_cvt_f32_ubyte0_e32 v155, v155
	v_cvt_f32_ubyte0_e32 v156, v156
	v_cvt_f32_ubyte0_e32 v157, v157
	v_rcp_iflag_f32_e32 v154, v154
	v_rcp_iflag_f32_e32 v155, v155
	v_rcp_iflag_f32_e32 v156, v156
	v_rcp_iflag_f32_e32 v157, v157
	v_cvt_f32_ubyte0_e32 v178, v195
	v_cvt_f32_ubyte1_e32 v179, v195
	v_cvt_f32_ubyte2_e32 v180, v195
	v_cvt_f32_ubyte3_e32 v181, v195
	v_pk_mul_f32 v[154:155], v[154:155], v[178:179]
	v_pk_mul_f32 v[156:157], v[156:157], v[180:181]
	v_pk_mul_f32 v[8:9], v[8:9], v[154:155]
	v_pk_mul_f32 v[10:11], v[10:11], v[156:157]
	s_waitcnt vmcnt(0)
	v_permlane16_swap_b32_e32 v198, v199
	v_permlane16_swap_b32_e32 v200, v201
	s_nop 0
	v_permlane32_swap_b32_e32 v198, v199
	v_permlane32_swap_b32_e32 v200, v201
	v_max_u32_sdwa v154, v200, v182 dst_sel:DWORD dst_unused:UNUSED_PAD src0_sel:BYTE_0 src1_sel:DWORD
	v_max_u32_sdwa v155, v200, v182 dst_sel:DWORD dst_unused:UNUSED_PAD src0_sel:BYTE_1 src1_sel:DWORD
	v_max_u32_sdwa v156, v200, v182 dst_sel:DWORD dst_unused:UNUSED_PAD src0_sel:BYTE_2 src1_sel:DWORD
	v_max_u32_sdwa v157, v200, v182 dst_sel:DWORD dst_unused:UNUSED_PAD src0_sel:BYTE_3 src1_sel:DWORD
	v_cvt_f32_ubyte0_e32 v154, v154
	v_cvt_f32_ubyte0_e32 v155, v155
	v_cvt_f32_ubyte0_e32 v156, v156
	v_cvt_f32_ubyte0_e32 v157, v157
	v_rcp_iflag_f32_e32 v154, v154
	v_rcp_iflag_f32_e32 v155, v155
	v_rcp_iflag_f32_e32 v156, v156
	v_rcp_iflag_f32_e32 v157, v157
	v_cvt_f32_ubyte0_e32 v178, v198
	v_cvt_f32_ubyte1_e32 v179, v198
	v_cvt_f32_ubyte2_e32 v180, v198
	v_cvt_f32_ubyte3_e32 v181, v198
	v_pk_mul_f32 v[154:155], v[154:155], v[178:179]
	v_pk_mul_f32 v[156:157], v[156:157], v[180:181]
	v_pk_mul_f32 v[4:5], v[4:5], v[154:155]
	v_pk_mul_f32 v[6:7], v[6:7], v[156:157]
	v_max_u32_sdwa v154, v201, v182 dst_sel:DWORD dst_unused:UNUSED_PAD src0_sel:BYTE_0 src1_sel:DWORD
	v_max_u32_sdwa v155, v201, v182 dst_sel:DWORD dst_unused:UNUSED_PAD src0_sel:BYTE_1 src1_sel:DWORD
	v_max_u32_sdwa v156, v201, v182 dst_sel:DWORD dst_unused:UNUSED_PAD src0_sel:BYTE_2 src1_sel:DWORD
	v_max_u32_sdwa v157, v201, v182 dst_sel:DWORD dst_unused:UNUSED_PAD src0_sel:BYTE_3 src1_sel:DWORD
	v_cvt_f32_ubyte0_e32 v154, v154
	v_cvt_f32_ubyte0_e32 v155, v155
	v_cvt_f32_ubyte0_e32 v156, v156
	v_cvt_f32_ubyte0_e32 v157, v157
	v_rcp_iflag_f32_e32 v154, v154
	v_rcp_iflag_f32_e32 v155, v155
	v_rcp_iflag_f32_e32 v156, v156
	v_rcp_iflag_f32_e32 v157, v157
	v_cvt_f32_ubyte0_e32 v178, v199
	v_cvt_f32_ubyte1_e32 v179, v199
	v_cvt_f32_ubyte2_e32 v180, v199
	v_cvt_f32_ubyte3_e32 v181, v199
	v_pk_mul_f32 v[154:155], v[154:155], v[178:179]
	v_pk_mul_f32 v[156:157], v[156:157], v[180:181]
	v_pk_mul_f32 v[0:1], v[0:1], v[154:155]
	v_pk_mul_f32 v[2:3], v[2:3], v[156:157]
	s_branch .LBB0_2735
